# plus P4 epilogue: attention/LRU tile values read from LDS in two batches instead of one read per element; rcp sigmoid also in the sample-row epilogues
# baseline (speedup 1.0000x reference)
; DEV u16 f2bf(float f) { return (u16)(pk2bf(f, 0.f) & 0xffffu); }
; DEV float bf2f(u16 h) { return __uint_as_float(((unsigned)h) << 16); }
; DEV float siluf_(float x) { return x / (1.0f + __expf(-x)); }
; template <int MI>
; DEV void tile_load_t(unsigned char* smem, const u16* src, size_t lds_) {
;   u16* sC = (u16*)smem;
;   const int tid_ = TIDX();
; #pragma unroll
;   for (int i = 0; i < MI * 4; ++i) {
;     const int c = tid_ + 256 * i, row = c >> 4, cc = (c & 15) * 8;
;     *(bf16x8*)(sC + row * LDC + cc) = __builtin_nontemporal_load((const bf16x8*)(src + (size_t)row * lds_ + cc));
;   }
;   __syncthreads();
; }
; template <int MI>
; DEV void p4_tile(const Params& p, int l, int m0, int nt, unsigned char* smem) {
;     ...
;     tile_load_t<MI>(smem, Q + (size_t)m0 * 1536 + nt * 192, 1536);
;     acc_foreach_t<MI>([&](int mi, int ni, int r, int row, int col) __attribute__((always_inline)) {
;       sC[row * LDC + col] = f2bf(bf2f(sC[row * LDC + col]) * siluf_(acc[mi][ni][r]));
.LBB0_1211:
	s_mul_hi_i32 s1, s0, 0xc00
	s_mulk_i32 s0, 0xc00
	s_add_u32 s0, s19, s0
	s_addc_u32 s1, s36, s1
	s_mul_i32 s6, s37, 0x180
	s_waitcnt vmcnt(8)
	v_mov_b32_e32 v136, v232
	s_barrier
	s_add_u32 s0, s0, s6
	s_addc_u32 s1, s1, 0
	v_lshlrev_b32_e32 v128, 4, v136
	v_and_b32_e32 v224, 0xf0, v128
	v_lshl_add_u64 v[128:129], s[0:1], 0, v[224:225]
	v_ashrrev_i32_e32 v134, 4, v136
	v_mad_i64_i32 v[204:205], s[0:1], v134, s41, v[128:129]
	v_mad_u64_u32 v[206:207], s[0:1], v134, s42, v[224:225]
	s_lshl_b32 s0, s41, 4
	s_mov_b32 s1, 0
	global_load_dwordx4 v[140:143], v[204:205], off nt
	v_lshl_add_u64 v[204:205], v[204:205], 0, s[0:1]
	global_load_dwordx4 v[144:147], v[204:205], off nt
	v_lshl_add_u64 v[204:205], v[204:205], 0, s[0:1]
	global_load_dwordx4 v[148:151], v[204:205], off nt
	v_lshl_add_u64 v[204:205], v[204:205], 0, s[0:1]
	global_load_dwordx4 v[152:155], v[204:205], off nt
	v_lshl_add_u64 v[204:205], v[204:205], 0, s[0:1]
	global_load_dwordx4 v[156:159], v[204:205], off nt
	v_lshl_add_u64 v[204:205], v[204:205], 0, s[0:1]
	global_load_dwordx4 v[160:163], v[204:205], off nt
	v_lshl_add_u64 v[204:205], v[204:205], 0, s[0:1]
	global_load_dwordx4 v[164:167], v[204:205], off nt
	v_lshl_add_u64 v[204:205], v[204:205], 0, s[0:1]
	global_load_dwordx4 v[168:171], v[204:205], off nt
	v_lshl_add_u64 v[204:205], v[204:205], 0, s[0:1]
	global_load_dwordx4 v[172:175], v[204:205], off nt
	v_lshl_add_u64 v[204:205], v[204:205], 0, s[0:1]
	global_load_dwordx4 v[176:179], v[204:205], off nt
	v_lshl_add_u64 v[204:205], v[204:205], 0, s[0:1]
	global_load_dwordx4 v[180:183], v[204:205], off nt
	v_lshl_add_u64 v[204:205], v[204:205], 0, s[0:1]
	global_load_dwordx4 v[184:187], v[204:205], off nt
	v_lshl_add_u64 v[204:205], v[204:205], 0, s[0:1]
	global_load_dwordx4 v[188:191], v[204:205], off nt
	v_lshl_add_u64 v[204:205], v[204:205], 0, s[0:1]
	global_load_dwordx4 v[192:195], v[204:205], off nt
	v_lshl_add_u64 v[204:205], v[204:205], 0, s[0:1]
	global_load_dwordx4 v[196:199], v[204:205], off nt
	v_lshl_add_u64 v[204:205], v[204:205], 0, s[0:1]
	global_load_dwordx4 v[200:203], v[204:205], off nt
	s_waitcnt vmcnt(15)
	ds_write_b128 v206, v[140:143]
	s_waitcnt vmcnt(14)
	ds_write_b128 v206, v[144:147] offset:4352
	s_waitcnt vmcnt(13)
	ds_write_b128 v206, v[148:151] offset:8704
	s_waitcnt vmcnt(12)
	ds_write_b128 v206, v[152:155] offset:13056
	s_waitcnt vmcnt(11)
	ds_write_b128 v206, v[156:159] offset:17408
	s_waitcnt vmcnt(10)
	ds_write_b128 v206, v[160:163] offset:21760
	s_waitcnt vmcnt(9)
	ds_write_b128 v206, v[164:167] offset:26112
	s_waitcnt vmcnt(8)
	ds_write_b128 v206, v[168:171] offset:30464
	s_waitcnt vmcnt(7)
	ds_write_b128 v206, v[172:175] offset:34816
	s_waitcnt vmcnt(6)
	ds_write_b128 v206, v[176:179] offset:39168
	s_waitcnt vmcnt(5)
	ds_write_b128 v206, v[180:183] offset:43520
	s_waitcnt vmcnt(4)
	ds_write_b128 v206, v[184:187] offset:47872
	s_waitcnt vmcnt(3)
	ds_write_b128 v206, v[188:191] offset:52224
	s_waitcnt vmcnt(2)
	ds_write_b128 v206, v[192:195] offset:56576
	s_waitcnt vmcnt(1)
	ds_write_b128 v206, v[196:199] offset:60928
	s_waitcnt vmcnt(0)
	ds_write_b128 v206, v[200:203] offset:65280
	v_mov_b32_e32 v128, v232
	s_waitcnt lgkmcnt(0)
	s_barrier
	s_nop 0
	v_and_b32_e32 v129, 0xfffff80, v128
	v_lshrrev_b32_e32 v130, 3, v128
	v_and_or_b32 v129, v130, 4, v129
	v_mul_f32_e32 v130, 0xbfb8aa3b, v112
	v_exp_f32_e32 v130, v130
	v_and_b32_e32 v128, 0x5f, v128
	v_mul_lo_u32 v129, v129, s42
	v_lshl_add_u32 v128, v128, 1, v129
	v_add_f32_e32 v130, 1.0, v130
	ds_read_u16 v140, v128
	ds_read_u16 v141, v128 offset:272
	ds_read_u16 v142, v128 offset:544
	ds_read_u16 v143, v128 offset:816
	ds_read_u16 v144, v128 offset:2176
	ds_read_u16 v145, v128 offset:2448
	ds_read_u16 v146, v128 offset:2720
	ds_read_u16 v147, v128 offset:2992
	ds_read_u16 v148, v128 offset:4352
	ds_read_u16 v149, v128 offset:4624
	ds_read_u16 v150, v128 offset:4896
	ds_read_u16 v151, v128 offset:5168
	ds_read_u16 v152, v128 offset:6528
	ds_read_u16 v153, v128 offset:6800
	ds_read_u16 v154, v128 offset:7072
	ds_read_u16 v155, v128 offset:7344
	ds_read_u16 v156, v128 offset:64
	ds_read_u16 v157, v128 offset:336
	ds_read_u16 v158, v128 offset:608
	ds_read_u16 v159, v128 offset:880
	ds_read_u16 v160, v128 offset:2240
	ds_read_u16 v161, v128 offset:2512
	ds_read_u16 v162, v128 offset:2784
	ds_read_u16 v163, v128 offset:3056
	ds_read_u16 v164, v128 offset:4416
	ds_read_u16 v165, v128 offset:4688
	ds_read_u16 v166, v128 offset:4960
	ds_read_u16 v167, v128 offset:5232
	ds_read_u16 v168, v128 offset:6592
	ds_read_u16 v169, v128 offset:6864
	ds_read_u16 v170, v128 offset:7136
	ds_read_u16 v171, v128 offset:7408
	ds_read_u16 v172, v128 offset:8704
	ds_read_u16 v173, v128 offset:8976
	ds_read_u16 v174, v128 offset:9248
	ds_read_u16 v175, v128 offset:9520
	ds_read_u16 v176, v128 offset:10880
	ds_read_u16 v177, v128 offset:11152
	ds_read_u16 v178, v128 offset:11424
	ds_read_u16 v179, v128 offset:11696
	ds_read_u16 v180, v128 offset:13056
	ds_read_u16 v181, v128 offset:13328
	ds_read_u16 v182, v128 offset:13600
	ds_read_u16 v183, v128 offset:13872
	ds_read_u16 v184, v128 offset:15232
	ds_read_u16 v185, v128 offset:15504
	ds_read_u16 v186, v128 offset:15776
	ds_read_u16 v187, v128 offset:16048
	ds_read_u16 v188, v128 offset:8768
	ds_read_u16 v189, v128 offset:9040
	ds_read_u16 v190, v128 offset:9312
	ds_read_u16 v191, v128 offset:9584
	ds_read_u16 v192, v128 offset:10944
	ds_read_u16 v193, v128 offset:11216
	ds_read_u16 v194, v128 offset:11488
	ds_read_u16 v195, v128 offset:11760
	ds_read_u16 v196, v128 offset:13120
	ds_read_u16 v197, v128 offset:13392
	ds_read_u16 v198, v128 offset:13664
	ds_read_u16 v199, v128 offset:13936
	ds_read_u16 v200, v128 offset:15296
	ds_read_u16 v201, v128 offset:15568
	ds_read_u16 v202, v128 offset:15840
	ds_read_u16 v203, v128 offset:16112
	s_waitcnt lgkmcnt(0)
; DEV u16 f2bf(float f) { return (u16)(pk2bf(f, 0.f) & 0xffffu); }
; DEV float bf2f(u16 h) { return __uint_as_float(((unsigned)h) << 16); }
; DEV float siluf_(float x) { return x / (1.0f + __expf(-x)); }
; template <int MI>
; DEV void p4_tile(const Params& p, int l, int m0, int nt, unsigned char* smem) {
;     ...
;     acc_foreach_t<MI>([&](int mi, int ni, int r, int row, int col) __attribute__((always_inline)) {
;       sC[row * LDC + col] = f2bf(bf2f(sC[row * LDC + col]) * siluf_(acc[mi][ni][r]));
	v_lshlrev_b32_e32 v129, 16, v140
	v_rcp_f32_e32 v131, v130
	s_nop 0
	v_mul_f32_e32 v112, v112, v131
	v_mul_f32_e32 v112, v112, v129
	v_mul_f32_e32 v129, 0xbfb8aa3b, v113
	v_exp_f32_e32 v129, v129
	v_cvt_pk_bf16_f32 v112, v112, s0
	ds_write_b16 v128, v112
	v_add_f32_e32 v129, 1.0, v129
	v_lshlrev_b32_e32 v112, 16, v141
	v_rcp_f32_e32 v130, v129
	s_nop 0
	v_mul_f32_e32 v113, v113, v130
	v_mul_f32_e32 v112, v113, v112
	v_mul_f32_e32 v113, 0xbfb8aa3b, v114
	v_exp_f32_e32 v113, v113
	v_cvt_pk_bf16_f32 v112, v112, s0
	ds_write_b16 v128, v112 offset:272
	v_add_f32_e32 v113, 1.0, v113
	v_lshlrev_b32_e32 v112, 16, v142
	v_rcp_f32_e32 v129, v113
	s_nop 0
	v_mul_f32_e32 v113, v114, v129
	v_mul_f32_e32 v112, v113, v112
	v_mul_f32_e32 v113, 0xbfb8aa3b, v115
	v_exp_f32_e32 v113, v113
	v_cvt_pk_bf16_f32 v112, v112, s0
	ds_write_b16 v128, v112 offset:544
	v_add_f32_e32 v113, 1.0, v113
	v_lshlrev_b32_e32 v112, 16, v143
	v_rcp_f32_e32 v114, v113
	s_nop 0
	v_mul_f32_e32 v113, v115, v114
	v_mul_f32_e32 v112, v113, v112
	v_mul_f32_e32 v113, 0xbfb8aa3b, v116
	v_exp_f32_e32 v113, v113
	v_cvt_pk_bf16_f32 v112, v112, s0
	ds_write_b16 v128, v112 offset:816
	v_add_f32_e32 v113, 1.0, v113
	v_lshlrev_b32_e32 v112, 16, v144
	v_rcp_f32_e32 v114, v113
	s_nop 0
	v_mul_f32_e32 v113, v116, v114
	v_mul_f32_e32 v112, v113, v112
	v_mul_f32_e32 v113, 0xbfb8aa3b, v117
	v_exp_f32_e32 v113, v113
	v_cvt_pk_bf16_f32 v112, v112, s0
	ds_write_b16 v128, v112 offset:2176
	v_add_f32_e32 v113, 1.0, v113
	v_lshlrev_b32_e32 v112, 16, v145
	v_rcp_f32_e32 v114, v113
	s_nop 0
	v_mul_f32_e32 v113, v117, v114
	v_mul_f32_e32 v112, v113, v112
	v_mul_f32_e32 v113, 0xbfb8aa3b, v118
	v_exp_f32_e32 v113, v113
	v_cvt_pk_bf16_f32 v112, v112, s0
	ds_write_b16 v128, v112 offset:2448
	v_add_f32_e32 v113, 1.0, v113
	v_lshlrev_b32_e32 v112, 16, v146
	v_rcp_f32_e32 v114, v113
	s_nop 0
	v_mul_f32_e32 v113, v118, v114
	v_mul_f32_e32 v112, v113, v112
	v_mul_f32_e32 v113, 0xbfb8aa3b, v119
	v_exp_f32_e32 v113, v113
	v_cvt_pk_bf16_f32 v112, v112, s0
	ds_write_b16 v128, v112 offset:2720
	v_add_f32_e32 v113, 1.0, v113
	v_lshlrev_b32_e32 v112, 16, v147
	v_rcp_f32_e32 v114, v113
	s_nop 0
	v_mul_f32_e32 v113, v119, v114
	v_mul_f32_e32 v112, v113, v112
	v_mul_f32_e32 v113, 0xbfb8aa3b, v120
	v_exp_f32_e32 v113, v113
	v_cvt_pk_bf16_f32 v112, v112, s0
	ds_write_b16 v128, v112 offset:2992
	v_add_f32_e32 v113, 1.0, v113
	v_lshlrev_b32_e32 v112, 16, v148
	v_rcp_f32_e32 v114, v113
	s_nop 0
	v_mul_f32_e32 v113, v120, v114
	v_mul_f32_e32 v112, v113, v112
	v_mul_f32_e32 v113, 0xbfb8aa3b, v121
	v_exp_f32_e32 v113, v113
	v_cvt_pk_bf16_f32 v112, v112, s0
	ds_write_b16 v128, v112 offset:4352
	v_add_f32_e32 v113, 1.0, v113
	v_lshlrev_b32_e32 v112, 16, v149
	v_rcp_f32_e32 v114, v113
	s_nop 0
	v_mul_f32_e32 v113, v121, v114
	v_mul_f32_e32 v112, v113, v112
	v_mul_f32_e32 v113, 0xbfb8aa3b, v122
	v_exp_f32_e32 v113, v113
	v_cvt_pk_bf16_f32 v112, v112, s0
	ds_write_b16 v128, v112 offset:4624
	v_add_f32_e32 v113, 1.0, v113
	v_lshlrev_b32_e32 v112, 16, v150
	v_rcp_f32_e32 v114, v113
	s_nop 0
	v_mul_f32_e32 v113, v122, v114
	v_mul_f32_e32 v112, v113, v112
	v_mul_f32_e32 v113, 0xbfb8aa3b, v123
	v_exp_f32_e32 v113, v113
	v_cvt_pk_bf16_f32 v112, v112, s0
	ds_write_b16 v128, v112 offset:4896
	v_add_f32_e32 v113, 1.0, v113
	v_lshlrev_b32_e32 v112, 16, v151
	v_rcp_f32_e32 v114, v113
	s_nop 0
	v_mul_f32_e32 v113, v123, v114
	v_mul_f32_e32 v112, v113, v112
	v_mul_f32_e32 v113, 0xbfb8aa3b, v124
	v_exp_f32_e32 v113, v113
	v_cvt_pk_bf16_f32 v112, v112, s0
	ds_write_b16 v128, v112 offset:5168
	v_add_f32_e32 v113, 1.0, v113
	v_lshlrev_b32_e32 v112, 16, v152
	v_rcp_f32_e32 v114, v113
	s_nop 0
	v_mul_f32_e32 v113, v124, v114
	v_mul_f32_e32 v112, v113, v112
	v_mul_f32_e32 v113, 0xbfb8aa3b, v125
	v_exp_f32_e32 v113, v113
	v_cvt_pk_bf16_f32 v112, v112, s0
	ds_write_b16 v128, v112 offset:6528
	v_add_f32_e32 v113, 1.0, v113
	v_lshlrev_b32_e32 v112, 16, v153
	v_rcp_f32_e32 v114, v113
	s_nop 0
	v_mul_f32_e32 v113, v125, v114
	v_mul_f32_e32 v112, v113, v112
	v_mul_f32_e32 v113, 0xbfb8aa3b, v126
	v_exp_f32_e32 v113, v113
	v_cvt_pk_bf16_f32 v112, v112, s0
	ds_write_b16 v128, v112 offset:6800
	v_add_f32_e32 v113, 1.0, v113
	v_lshlrev_b32_e32 v112, 16, v154
	v_rcp_f32_e32 v114, v113
	s_nop 0
	v_mul_f32_e32 v113, v126, v114
	v_mul_f32_e32 v112, v113, v112
	v_mul_f32_e32 v113, 0xbfb8aa3b, v127
	v_exp_f32_e32 v113, v113
	v_cvt_pk_bf16_f32 v112, v112, s0
	ds_write_b16 v128, v112 offset:7072
	v_add_f32_e32 v113, 1.0, v113
	v_lshlrev_b32_e32 v112, 16, v155
	v_rcp_f32_e32 v114, v113
	s_nop 0
	v_mul_f32_e32 v113, v127, v114
	v_mul_f32_e32 v112, v113, v112
	v_mul_f32_e32 v113, 0xbfb8aa3b, v96
	v_exp_f32_e32 v113, v113
	v_cvt_pk_bf16_f32 v112, v112, s0
	ds_write_b16 v128, v112 offset:7344
	v_add_f32_e32 v113, 1.0, v113
	v_lshlrev_b32_e32 v112, 16, v156
	v_rcp_f32_e32 v114, v113
	s_nop 0
	v_mul_f32_e32 v96, v96, v114
	v_mul_f32_e32 v96, v96, v112
	v_mul_f32_e32 v112, 0xbfb8aa3b, v97
	v_exp_f32_e32 v112, v112
	v_cvt_pk_bf16_f32 v96, v96, s0
	ds_write_b16 v128, v96 offset:64
	v_add_f32_e32 v112, 1.0, v112
	v_lshlrev_b32_e32 v96, 16, v157
	v_rcp_f32_e32 v113, v112
	s_nop 0
	v_mul_f32_e32 v97, v97, v113
	v_mul_f32_e32 v96, v97, v96
	v_mul_f32_e32 v97, 0xbfb8aa3b, v98
	v_exp_f32_e32 v97, v97
	v_cvt_pk_bf16_f32 v96, v96, s0
	ds_write_b16 v128, v96 offset:336
	v_add_f32_e32 v97, 1.0, v97
	v_lshlrev_b32_e32 v96, 16, v158
	v_rcp_f32_e32 v112, v97
	s_nop 0
	v_mul_f32_e32 v97, v98, v112
	v_mul_f32_e32 v96, v97, v96
	v_mul_f32_e32 v97, 0xbfb8aa3b, v99
	v_exp_f32_e32 v97, v97
	v_cvt_pk_bf16_f32 v96, v96, s0
	ds_write_b16 v128, v96 offset:608
	v_add_f32_e32 v97, 1.0, v97
	v_lshlrev_b32_e32 v96, 16, v159
; DEV u16 f2bf(float f) { return (u16)(pk2bf(f, 0.f) & 0xffffu); }
; DEV float bf2f(u16 h) { return __uint_as_float(((unsigned)h) << 16); }
; DEV float siluf_(float x) { return x / (1.0f + __expf(-x)); }
; template <int MI>
; DEV void p4_tile(const Params& p, int l, int m0, int nt, unsigned char* smem) {
;     ...
;     acc_foreach_t<MI>([&](int mi, int ni, int r, int row, int col) __attribute__((always_inline)) {
;       sC[row * LDC + col] = f2bf(bf2f(sC[row * LDC + col]) * siluf_(acc[mi][ni][r]));
	v_rcp_f32_e32 v98, v97
	s_nop 0
	v_mul_f32_e32 v97, v99, v98
	v_mul_f32_e32 v96, v97, v96
	v_mul_f32_e32 v97, 0xbfb8aa3b, v100
	v_exp_f32_e32 v97, v97
	v_cvt_pk_bf16_f32 v96, v96, s0
	ds_write_b16 v128, v96 offset:880
	v_add_f32_e32 v97, 1.0, v97
	v_lshlrev_b32_e32 v96, 16, v160
	v_rcp_f32_e32 v98, v97
	s_nop 0
	v_mul_f32_e32 v97, v100, v98
	v_mul_f32_e32 v96, v97, v96
	v_mul_f32_e32 v97, 0xbfb8aa3b, v101
	v_exp_f32_e32 v97, v97
	v_cvt_pk_bf16_f32 v96, v96, s0
	ds_write_b16 v128, v96 offset:2240
	v_add_f32_e32 v97, 1.0, v97
	v_lshlrev_b32_e32 v96, 16, v161
	v_rcp_f32_e32 v98, v97
	s_nop 0
	v_mul_f32_e32 v97, v101, v98
	v_mul_f32_e32 v96, v97, v96
	v_mul_f32_e32 v97, 0xbfb8aa3b, v102
	v_exp_f32_e32 v97, v97
	v_cvt_pk_bf16_f32 v96, v96, s0
	ds_write_b16 v128, v96 offset:2512
	v_add_f32_e32 v97, 1.0, v97
	v_lshlrev_b32_e32 v96, 16, v162
	v_rcp_f32_e32 v98, v97
	s_nop 0
	v_mul_f32_e32 v97, v102, v98
	v_mul_f32_e32 v96, v97, v96
	v_mul_f32_e32 v97, 0xbfb8aa3b, v103
	v_exp_f32_e32 v97, v97
	v_cvt_pk_bf16_f32 v96, v96, s0
	ds_write_b16 v128, v96 offset:2784
	v_add_f32_e32 v97, 1.0, v97
	v_lshlrev_b32_e32 v96, 16, v163
	v_rcp_f32_e32 v98, v97
	s_nop 0
	v_mul_f32_e32 v97, v103, v98
	v_mul_f32_e32 v96, v97, v96
	v_mul_f32_e32 v97, 0xbfb8aa3b, v104
	v_exp_f32_e32 v97, v97
	v_cvt_pk_bf16_f32 v96, v96, s0
	ds_write_b16 v128, v96 offset:3056
	v_add_f32_e32 v97, 1.0, v97
	v_lshlrev_b32_e32 v96, 16, v164
	v_rcp_f32_e32 v98, v97
	s_nop 0
	v_mul_f32_e32 v97, v104, v98
	v_mul_f32_e32 v96, v97, v96
	v_mul_f32_e32 v97, 0xbfb8aa3b, v105
	v_exp_f32_e32 v97, v97
	v_cvt_pk_bf16_f32 v96, v96, s0
	ds_write_b16 v128, v96 offset:4416
	v_add_f32_e32 v97, 1.0, v97
	v_lshlrev_b32_e32 v96, 16, v165
	v_rcp_f32_e32 v98, v97
	s_nop 0
	v_mul_f32_e32 v97, v105, v98
	v_mul_f32_e32 v96, v97, v96
	v_mul_f32_e32 v97, 0xbfb8aa3b, v106
	v_exp_f32_e32 v97, v97
	v_cvt_pk_bf16_f32 v96, v96, s0
	ds_write_b16 v128, v96 offset:4688
	v_add_f32_e32 v97, 1.0, v97
	v_lshlrev_b32_e32 v96, 16, v166
	v_rcp_f32_e32 v98, v97
	s_nop 0
	v_mul_f32_e32 v97, v106, v98
	v_mul_f32_e32 v96, v97, v96
	v_mul_f32_e32 v97, 0xbfb8aa3b, v107
	v_exp_f32_e32 v97, v97
	v_cvt_pk_bf16_f32 v96, v96, s0
	ds_write_b16 v128, v96 offset:4960
	v_add_f32_e32 v97, 1.0, v97
	v_lshlrev_b32_e32 v96, 16, v167
	v_rcp_f32_e32 v98, v97
	s_nop 0
	v_mul_f32_e32 v97, v107, v98
	v_mul_f32_e32 v96, v97, v96
	v_mul_f32_e32 v97, 0xbfb8aa3b, v108
	v_exp_f32_e32 v97, v97
	v_cvt_pk_bf16_f32 v96, v96, s0
	ds_write_b16 v128, v96 offset:5232
	v_add_f32_e32 v97, 1.0, v97
	v_lshlrev_b32_e32 v96, 16, v168
	v_rcp_f32_e32 v98, v97
	s_nop 0
	v_mul_f32_e32 v97, v108, v98
	v_mul_f32_e32 v96, v97, v96
	v_mul_f32_e32 v97, 0xbfb8aa3b, v109
	v_exp_f32_e32 v97, v97
	v_cvt_pk_bf16_f32 v96, v96, s0
	ds_write_b16 v128, v96 offset:6592
	v_add_f32_e32 v97, 1.0, v97
	v_lshlrev_b32_e32 v96, 16, v169
	v_rcp_f32_e32 v98, v97
	s_nop 0
	v_mul_f32_e32 v97, v109, v98
	v_mul_f32_e32 v96, v97, v96
	v_mul_f32_e32 v97, 0xbfb8aa3b, v110
	v_exp_f32_e32 v97, v97
	v_cvt_pk_bf16_f32 v96, v96, s0
	ds_write_b16 v128, v96 offset:6864
	v_add_f32_e32 v97, 1.0, v97
	v_lshlrev_b32_e32 v96, 16, v170
	v_rcp_f32_e32 v98, v97
	s_nop 0
	v_mul_f32_e32 v97, v110, v98
	v_mul_f32_e32 v96, v97, v96
	v_mul_f32_e32 v97, 0xbfb8aa3b, v111
	v_exp_f32_e32 v97, v97
	v_cvt_pk_bf16_f32 v96, v96, s0
	ds_write_b16 v128, v96 offset:7136
	v_add_f32_e32 v97, 1.0, v97
	v_lshlrev_b32_e32 v96, 16, v171
	v_rcp_f32_e32 v98, v97
	s_nop 0
	v_mul_f32_e32 v97, v111, v98
	v_mul_f32_e32 v96, v97, v96
	v_mul_f32_e32 v97, 0xbfb8aa3b, v80
	v_exp_f32_e32 v97, v97
	v_cvt_pk_bf16_f32 v96, v96, s0
	ds_write_b16 v128, v96 offset:7408
	v_add_f32_e32 v97, 1.0, v97
	v_lshlrev_b32_e32 v96, 16, v172
	v_rcp_f32_e32 v98, v97
	s_nop 0
	v_mul_f32_e32 v80, v80, v98
	v_mul_f32_e32 v80, v80, v96
	v_mul_f32_e32 v96, 0xbfb8aa3b, v81
	v_exp_f32_e32 v96, v96
	v_cvt_pk_bf16_f32 v80, v80, s0
	ds_write_b16 v128, v80 offset:8704
	v_add_f32_e32 v96, 1.0, v96
	v_lshlrev_b32_e32 v80, 16, v173
	v_rcp_f32_e32 v97, v96
	s_nop 0
	v_mul_f32_e32 v81, v81, v97
	v_mul_f32_e32 v80, v81, v80
	v_mul_f32_e32 v81, 0xbfb8aa3b, v82
	v_exp_f32_e32 v81, v81
	v_cvt_pk_bf16_f32 v80, v80, s0
	ds_write_b16 v128, v80 offset:8976
	v_add_f32_e32 v81, 1.0, v81
	v_lshlrev_b32_e32 v80, 16, v174
	v_rcp_f32_e32 v96, v81
	s_nop 0
	v_mul_f32_e32 v81, v82, v96
	v_mul_f32_e32 v80, v81, v80
	v_mul_f32_e32 v81, 0xbfb8aa3b, v83
	v_exp_f32_e32 v81, v81
	v_cvt_pk_bf16_f32 v80, v80, s0
	ds_write_b16 v128, v80 offset:9248
	v_add_f32_e32 v81, 1.0, v81
	v_lshlrev_b32_e32 v80, 16, v175
	v_rcp_f32_e32 v82, v81
	s_nop 0
	v_mul_f32_e32 v81, v83, v82
	v_mul_f32_e32 v80, v81, v80
	v_mul_f32_e32 v81, 0xbfb8aa3b, v84
	v_exp_f32_e32 v81, v81
	v_cvt_pk_bf16_f32 v80, v80, s0
	ds_write_b16 v128, v80 offset:9520
	v_add_f32_e32 v81, 1.0, v81
	v_lshlrev_b32_e32 v80, 16, v176
	v_rcp_f32_e32 v82, v81
	s_nop 0
	v_mul_f32_e32 v81, v84, v82
	v_mul_f32_e32 v80, v81, v80
	v_mul_f32_e32 v81, 0xbfb8aa3b, v85
	v_exp_f32_e32 v81, v81
	v_cvt_pk_bf16_f32 v80, v80, s0
	ds_write_b16 v128, v80 offset:10880
	v_add_f32_e32 v81, 1.0, v81
	v_lshlrev_b32_e32 v80, 16, v177
	v_rcp_f32_e32 v82, v81
	s_nop 0
	v_mul_f32_e32 v81, v85, v82
	v_mul_f32_e32 v80, v81, v80
	v_mul_f32_e32 v81, 0xbfb8aa3b, v86
	v_exp_f32_e32 v81, v81
	v_cvt_pk_bf16_f32 v80, v80, s0
	ds_write_b16 v128, v80 offset:11152
	v_add_f32_e32 v81, 1.0, v81
	v_lshlrev_b32_e32 v80, 16, v178
	v_rcp_f32_e32 v82, v81
	s_nop 0
	v_mul_f32_e32 v81, v86, v82
	v_mul_f32_e32 v80, v81, v80
	v_mul_f32_e32 v81, 0xbfb8aa3b, v87
	v_exp_f32_e32 v81, v81
	v_cvt_pk_bf16_f32 v80, v80, s0
	ds_write_b16 v128, v80 offset:11424
	v_add_f32_e32 v81, 1.0, v81
	v_lshlrev_b32_e32 v80, 16, v179
; DEV u16 f2bf(float f) { return (u16)(pk2bf(f, 0.f) & 0xffffu); }
; DEV float bf2f(u16 h) { return __uint_as_float(((unsigned)h) << 16); }
; DEV float siluf_(float x) { return x / (1.0f + __expf(-x)); }
; template <int MI>
; DEV void p4_tile(const Params& p, int l, int m0, int nt, unsigned char* smem) {
;     ...
;     acc_foreach_t<MI>([&](int mi, int ni, int r, int row, int col) __attribute__((always_inline)) {
;       sC[row * LDC + col] = f2bf(bf2f(sC[row * LDC + col]) * siluf_(acc[mi][ni][r]));
	v_rcp_f32_e32 v82, v81
	s_nop 0
	v_mul_f32_e32 v81, v87, v82
	v_mul_f32_e32 v80, v81, v80
	v_mul_f32_e32 v81, 0xbfb8aa3b, v88
	v_exp_f32_e32 v81, v81
	v_cvt_pk_bf16_f32 v80, v80, s0
	ds_write_b16 v128, v80 offset:11696
	v_add_f32_e32 v81, 1.0, v81
	v_lshlrev_b32_e32 v80, 16, v180
	v_rcp_f32_e32 v82, v81
	s_nop 0
	v_mul_f32_e32 v81, v88, v82
	v_mul_f32_e32 v80, v81, v80
	v_mul_f32_e32 v81, 0xbfb8aa3b, v89
	v_exp_f32_e32 v81, v81
	v_cvt_pk_bf16_f32 v80, v80, s0
	ds_write_b16 v128, v80 offset:13056
	v_add_f32_e32 v81, 1.0, v81
	v_lshlrev_b32_e32 v80, 16, v181
	v_rcp_f32_e32 v82, v81
	s_nop 0
	v_mul_f32_e32 v81, v89, v82
	v_mul_f32_e32 v80, v81, v80
	v_mul_f32_e32 v81, 0xbfb8aa3b, v90
	v_exp_f32_e32 v81, v81
	v_cvt_pk_bf16_f32 v80, v80, s0
	ds_write_b16 v128, v80 offset:13328
	v_add_f32_e32 v81, 1.0, v81
	v_lshlrev_b32_e32 v80, 16, v182
	v_rcp_f32_e32 v82, v81
	s_nop 0
	v_mul_f32_e32 v81, v90, v82
	v_mul_f32_e32 v80, v81, v80
	v_mul_f32_e32 v81, 0xbfb8aa3b, v91
	v_exp_f32_e32 v81, v81
	v_cvt_pk_bf16_f32 v80, v80, s0
	ds_write_b16 v128, v80 offset:13600
	v_add_f32_e32 v81, 1.0, v81
	v_lshlrev_b32_e32 v80, 16, v183
	v_rcp_f32_e32 v82, v81
	s_nop 0
	v_mul_f32_e32 v81, v91, v82
	v_mul_f32_e32 v80, v81, v80
	v_mul_f32_e32 v81, 0xbfb8aa3b, v92
	v_exp_f32_e32 v81, v81
	v_cvt_pk_bf16_f32 v80, v80, s0
	ds_write_b16 v128, v80 offset:13872
	v_add_f32_e32 v81, 1.0, v81
	v_lshlrev_b32_e32 v80, 16, v184
	v_rcp_f32_e32 v82, v81
	s_nop 0
	v_mul_f32_e32 v81, v92, v82
	v_mul_f32_e32 v80, v81, v80
	v_mul_f32_e32 v81, 0xbfb8aa3b, v93
	v_exp_f32_e32 v81, v81
	v_cvt_pk_bf16_f32 v80, v80, s0
	ds_write_b16 v128, v80 offset:15232
	v_add_f32_e32 v81, 1.0, v81
	v_lshlrev_b32_e32 v80, 16, v185
	v_rcp_f32_e32 v82, v81
	s_nop 0
	v_mul_f32_e32 v81, v93, v82
	v_mul_f32_e32 v80, v81, v80
	v_mul_f32_e32 v81, 0xbfb8aa3b, v94
	v_exp_f32_e32 v81, v81
	v_cvt_pk_bf16_f32 v80, v80, s0
	ds_write_b16 v128, v80 offset:15504
	v_add_f32_e32 v81, 1.0, v81
	v_lshlrev_b32_e32 v80, 16, v186
	v_rcp_f32_e32 v82, v81
	s_nop 0
	v_mul_f32_e32 v81, v94, v82
	v_mul_f32_e32 v80, v81, v80
	v_mul_f32_e32 v81, 0xbfb8aa3b, v95
	v_exp_f32_e32 v81, v81
	v_cvt_pk_bf16_f32 v80, v80, s0
	ds_write_b16 v128, v80 offset:15776
	v_add_f32_e32 v81, 1.0, v81
	v_lshlrev_b32_e32 v80, 16, v187
	v_rcp_f32_e32 v82, v81
	s_nop 0
	v_mul_f32_e32 v81, v95, v82
	v_mul_f32_e32 v80, v81, v80
	v_mul_f32_e32 v81, 0xbfb8aa3b, v64
	v_exp_f32_e32 v81, v81
	v_cvt_pk_bf16_f32 v80, v80, s0
	ds_write_b16 v128, v80 offset:16048
	v_add_f32_e32 v81, 1.0, v81
	v_lshlrev_b32_e32 v80, 16, v188
	v_rcp_f32_e32 v82, v81
	s_nop 0
	v_mul_f32_e32 v64, v64, v82
	v_mul_f32_e32 v64, v64, v80
	v_mul_f32_e32 v80, 0xbfb8aa3b, v65
	v_exp_f32_e32 v80, v80
	v_cvt_pk_bf16_f32 v64, v64, s0
	ds_write_b16 v128, v64 offset:8768
	v_add_f32_e32 v80, 1.0, v80
	v_lshlrev_b32_e32 v64, 16, v189
	v_rcp_f32_e32 v81, v80
	s_nop 0
	v_mul_f32_e32 v65, v65, v81
	v_mul_f32_e32 v64, v65, v64
	v_mul_f32_e32 v65, 0xbfb8aa3b, v66
	v_exp_f32_e32 v65, v65
	v_cvt_pk_bf16_f32 v64, v64, s0
	ds_write_b16 v128, v64 offset:9040
	v_add_f32_e32 v65, 1.0, v65
	v_lshlrev_b32_e32 v64, 16, v190
	v_rcp_f32_e32 v80, v65
	s_nop 0
	v_mul_f32_e32 v65, v66, v80
	v_mul_f32_e32 v64, v65, v64
	v_mul_f32_e32 v65, 0xbfb8aa3b, v67
	v_exp_f32_e32 v65, v65
	v_cvt_pk_bf16_f32 v64, v64, s0
	ds_write_b16 v128, v64 offset:9312
	v_add_f32_e32 v65, 1.0, v65
	v_lshlrev_b32_e32 v64, 16, v191
	v_rcp_f32_e32 v66, v65
	s_nop 0
	v_mul_f32_e32 v65, v67, v66
	v_mul_f32_e32 v64, v65, v64
	v_mul_f32_e32 v65, 0xbfb8aa3b, v68
	v_exp_f32_e32 v65, v65
	v_cvt_pk_bf16_f32 v64, v64, s0
	ds_write_b16 v128, v64 offset:9584
	v_add_f32_e32 v65, 1.0, v65
	v_lshlrev_b32_e32 v64, 16, v192
	v_rcp_f32_e32 v66, v65
	s_nop 0
	v_mul_f32_e32 v65, v68, v66
	v_mul_f32_e32 v64, v65, v64
	v_mul_f32_e32 v65, 0xbfb8aa3b, v69
	v_exp_f32_e32 v65, v65
	v_cvt_pk_bf16_f32 v64, v64, s0
	ds_write_b16 v128, v64 offset:10944
	v_add_f32_e32 v65, 1.0, v65
	v_lshlrev_b32_e32 v64, 16, v193
	v_rcp_f32_e32 v66, v65
	s_nop 0
	v_mul_f32_e32 v65, v69, v66
	v_mul_f32_e32 v64, v65, v64
	v_mul_f32_e32 v65, 0xbfb8aa3b, v70
	v_exp_f32_e32 v65, v65
	v_cvt_pk_bf16_f32 v64, v64, s0
	ds_write_b16 v128, v64 offset:11216
	v_add_f32_e32 v65, 1.0, v65
	v_lshlrev_b32_e32 v64, 16, v194
	v_rcp_f32_e32 v66, v65
	s_nop 0
	v_mul_f32_e32 v65, v70, v66
	v_mul_f32_e32 v64, v65, v64
	v_mul_f32_e32 v65, 0xbfb8aa3b, v71
	v_exp_f32_e32 v65, v65
	v_cvt_pk_bf16_f32 v64, v64, s0
	ds_write_b16 v128, v64 offset:11488
	v_add_f32_e32 v65, 1.0, v65
	v_lshlrev_b32_e32 v64, 16, v195
	v_rcp_f32_e32 v66, v65
	s_nop 0
	v_mul_f32_e32 v65, v71, v66
	v_mul_f32_e32 v64, v65, v64
	v_mul_f32_e32 v65, 0xbfb8aa3b, v72
	v_exp_f32_e32 v65, v65
	v_cvt_pk_bf16_f32 v64, v64, s0
	ds_write_b16 v128, v64 offset:11760
	v_add_f32_e32 v65, 1.0, v65
	v_lshlrev_b32_e32 v64, 16, v196
	v_rcp_f32_e32 v66, v65
	s_nop 0
	v_mul_f32_e32 v65, v72, v66
	v_mul_f32_e32 v64, v65, v64
	v_mul_f32_e32 v65, 0xbfb8aa3b, v73
	v_exp_f32_e32 v65, v65
	v_cvt_pk_bf16_f32 v64, v64, s0
	ds_write_b16 v128, v64 offset:13120
	v_add_f32_e32 v65, 1.0, v65
	v_lshlrev_b32_e32 v64, 16, v197
	v_rcp_f32_e32 v66, v65
	s_nop 0
	v_mul_f32_e32 v65, v73, v66
	v_mul_f32_e32 v64, v65, v64
	v_mul_f32_e32 v65, 0xbfb8aa3b, v74
	v_exp_f32_e32 v65, v65
	v_cvt_pk_bf16_f32 v64, v64, s0
	ds_write_b16 v128, v64 offset:13392
	v_add_f32_e32 v65, 1.0, v65
	v_lshlrev_b32_e32 v64, 16, v198
	v_rcp_f32_e32 v66, v65
	s_nop 0
	v_mul_f32_e32 v65, v74, v66
	v_mul_f32_e32 v64, v65, v64
	v_mul_f32_e32 v65, 0xbfb8aa3b, v75
	v_exp_f32_e32 v65, v65
	v_cvt_pk_bf16_f32 v64, v64, s0
	ds_write_b16 v128, v64 offset:13664
	v_add_f32_e32 v65, 1.0, v65
	v_lshlrev_b32_e32 v64, 16, v199
; DEV u16 f2bf(float f) { return (u16)(pk2bf(f, 0.f) & 0xffffu); }
; DEV float bf2f(u16 h) { return __uint_as_float(((unsigned)h) << 16); }
; DEV float siluf_(float x) { return x / (1.0f + __expf(-x)); }
; template <int MI>
; DEV void p4_tile(const Params& p, int l, int m0, int nt, unsigned char* smem) {
;     ...
;     acc_foreach_t<MI>([&](int mi, int ni, int r, int row, int col) __attribute__((always_inline)) {
;       sC[row * LDC + col] = f2bf(bf2f(sC[row * LDC + col]) * siluf_(acc[mi][ni][r]));
	v_rcp_f32_e32 v66, v65
	s_nop 0
	v_mul_f32_e32 v65, v75, v66
	v_mul_f32_e32 v64, v65, v64
	v_mul_f32_e32 v65, 0xbfb8aa3b, v76
	v_exp_f32_e32 v65, v65
	v_cvt_pk_bf16_f32 v64, v64, s0
	ds_write_b16 v128, v64 offset:13936
	v_add_f32_e32 v65, 1.0, v65
	v_lshlrev_b32_e32 v64, 16, v200
	v_rcp_f32_e32 v66, v65
	s_nop 0
	v_mul_f32_e32 v65, v76, v66
	v_mul_f32_e32 v64, v65, v64
	v_mul_f32_e32 v65, 0xbfb8aa3b, v77
	v_exp_f32_e32 v65, v65
	v_cvt_pk_bf16_f32 v64, v64, s0
	ds_write_b16 v128, v64 offset:15296
	v_add_f32_e32 v65, 1.0, v65
	v_lshlrev_b32_e32 v64, 16, v201
	v_rcp_f32_e32 v66, v65
	s_nop 0
	v_mul_f32_e32 v65, v77, v66
	v_mul_f32_e32 v64, v65, v64
	v_mul_f32_e32 v65, 0xbfb8aa3b, v78
	v_exp_f32_e32 v65, v65
	v_cvt_pk_bf16_f32 v64, v64, s0
	ds_write_b16 v128, v64 offset:15568
	v_add_f32_e32 v65, 1.0, v65
	v_lshlrev_b32_e32 v64, 16, v202
	v_rcp_f32_e32 v66, v65
	s_nop 0
	v_mul_f32_e32 v65, v78, v66
	v_mul_f32_e32 v64, v65, v64
	v_mul_f32_e32 v65, 0xbfb8aa3b, v79
	v_exp_f32_e32 v65, v65
	v_cvt_pk_bf16_f32 v64, v64, s0
	ds_write_b16 v128, v64 offset:15840
	v_add_f32_e32 v65, 1.0, v65
	v_lshlrev_b32_e32 v64, 16, v203
	v_rcp_f32_e32 v66, v65
	s_nop 0
	v_mul_f32_e32 v65, v79, v66
	v_mul_f32_e32 v64, v65, v64
	v_mul_f32_e32 v65, 0xbfb8aa3b, v48
	v_exp_f32_e32 v65, v65
	v_cvt_pk_bf16_f32 v64, v64, s0
	ds_write_b16 v128, v64 offset:16112
	ds_read_u16 v140, v128 offset:17408
	ds_read_u16 v141, v128 offset:17680
	ds_read_u16 v142, v128 offset:17952
	ds_read_u16 v143, v128 offset:18224
	ds_read_u16 v144, v128 offset:19584
	ds_read_u16 v145, v128 offset:19856
	ds_read_u16 v146, v128 offset:20128
	ds_read_u16 v147, v128 offset:20400
	ds_read_u16 v148, v128 offset:21760
	ds_read_u16 v149, v128 offset:22032
	ds_read_u16 v150, v128 offset:22304
	ds_read_u16 v151, v128 offset:22576
	ds_read_u16 v152, v128 offset:23936
	ds_read_u16 v153, v128 offset:24208
	ds_read_u16 v154, v128 offset:24480
	ds_read_u16 v155, v128 offset:24752
	ds_read_u16 v156, v128 offset:17472
	ds_read_u16 v157, v128 offset:17744
	ds_read_u16 v158, v128 offset:18016
	ds_read_u16 v159, v128 offset:18288
	ds_read_u16 v160, v128 offset:19648
	ds_read_u16 v161, v128 offset:19920
	ds_read_u16 v162, v128 offset:20192
	ds_read_u16 v163, v128 offset:20464
	ds_read_u16 v164, v128 offset:21824
	ds_read_u16 v165, v128 offset:22096
	ds_read_u16 v166, v128 offset:22368
	ds_read_u16 v167, v128 offset:22640
	ds_read_u16 v168, v128 offset:24000
	ds_read_u16 v169, v128 offset:24272
	ds_read_u16 v170, v128 offset:24544
	ds_read_u16 v171, v128 offset:24816
	ds_read_u16 v172, v128 offset:26112
	ds_read_u16 v173, v128 offset:26384
	ds_read_u16 v174, v128 offset:26656
	ds_read_u16 v175, v128 offset:26928
	ds_read_u16 v176, v128 offset:28288
	ds_read_u16 v177, v128 offset:28560
	ds_read_u16 v178, v128 offset:28832
	ds_read_u16 v179, v128 offset:29104
	ds_read_u16 v180, v128 offset:30464
	ds_read_u16 v181, v128 offset:30736
	ds_read_u16 v182, v128 offset:31008
	ds_read_u16 v183, v128 offset:31280
	ds_read_u16 v184, v128 offset:32640
	ds_read_u16 v185, v128 offset:32912
	ds_read_u16 v186, v128 offset:33184
	ds_read_u16 v187, v128 offset:33456
	ds_read_u16 v188, v128 offset:26176
	ds_read_u16 v189, v128 offset:26448
	ds_read_u16 v190, v128 offset:26720
	ds_read_u16 v191, v128 offset:26992
	ds_read_u16 v192, v128 offset:28352
	ds_read_u16 v193, v128 offset:28624
	ds_read_u16 v194, v128 offset:28896
	ds_read_u16 v195, v128 offset:29168
	ds_read_u16 v196, v128 offset:30528
	ds_read_u16 v197, v128 offset:30800
	ds_read_u16 v198, v128 offset:31072
	ds_read_u16 v199, v128 offset:31344
	ds_read_u16 v200, v128 offset:32704
	ds_read_u16 v201, v128 offset:32976
	ds_read_u16 v202, v128 offset:33248
	ds_read_u16 v203, v128 offset:33520
	s_waitcnt lgkmcnt(0)
	v_add_f32_e32 v65, 1.0, v65
	v_lshlrev_b32_e32 v64, 16, v140
	v_rcp_f32_e32 v66, v65
	s_nop 0
	v_mul_f32_e32 v48, v48, v66
	v_mul_f32_e32 v48, v48, v64
	v_mul_f32_e32 v64, 0xbfb8aa3b, v49
	v_exp_f32_e32 v64, v64
	v_cvt_pk_bf16_f32 v48, v48, s0
	ds_write_b16 v128, v48 offset:17408
	v_add_f32_e32 v64, 1.0, v64
	v_lshlrev_b32_e32 v48, 16, v141
	v_rcp_f32_e32 v65, v64
	s_nop 0
	v_mul_f32_e32 v49, v49, v65
	v_mul_f32_e32 v48, v49, v48
	v_mul_f32_e32 v49, 0xbfb8aa3b, v50
	v_exp_f32_e32 v49, v49
	v_cvt_pk_bf16_f32 v48, v48, s0
	ds_write_b16 v128, v48 offset:17680
	v_add_f32_e32 v49, 1.0, v49
	v_lshlrev_b32_e32 v48, 16, v142
	v_rcp_f32_e32 v64, v49
	s_nop 0
	v_mul_f32_e32 v49, v50, v64
	v_mul_f32_e32 v48, v49, v48
	v_mul_f32_e32 v49, 0xbfb8aa3b, v51
	v_exp_f32_e32 v49, v49
	v_cvt_pk_bf16_f32 v48, v48, s0
	ds_write_b16 v128, v48 offset:17952
	v_add_f32_e32 v49, 1.0, v49
	v_lshlrev_b32_e32 v48, 16, v143
	v_rcp_f32_e32 v50, v49
	s_nop 0
	v_mul_f32_e32 v49, v51, v50
	v_mul_f32_e32 v48, v49, v48
	v_mul_f32_e32 v49, 0xbfb8aa3b, v52
	v_exp_f32_e32 v49, v49
	v_cvt_pk_bf16_f32 v48, v48, s0
	ds_write_b16 v128, v48 offset:18224
	v_add_f32_e32 v49, 1.0, v49
	v_lshlrev_b32_e32 v48, 16, v144
	v_rcp_f32_e32 v50, v49
	s_nop 0
	v_mul_f32_e32 v49, v52, v50
	v_mul_f32_e32 v48, v49, v48
	v_mul_f32_e32 v49, 0xbfb8aa3b, v53
	v_exp_f32_e32 v49, v49
	v_cvt_pk_bf16_f32 v48, v48, s0
	ds_write_b16 v128, v48 offset:19584
	v_add_f32_e32 v49, 1.0, v49
	v_lshlrev_b32_e32 v48, 16, v145
	v_rcp_f32_e32 v50, v49
	s_nop 0
	v_mul_f32_e32 v49, v53, v50
	v_mul_f32_e32 v48, v49, v48
	v_mul_f32_e32 v49, 0xbfb8aa3b, v54
	v_exp_f32_e32 v49, v49
	v_cvt_pk_bf16_f32 v48, v48, s0
	ds_write_b16 v128, v48 offset:19856
	v_add_f32_e32 v49, 1.0, v49
	v_lshlrev_b32_e32 v48, 16, v146
	v_rcp_f32_e32 v50, v49
	s_nop 0
	v_mul_f32_e32 v49, v54, v50
	v_mul_f32_e32 v48, v49, v48
	v_mul_f32_e32 v49, 0xbfb8aa3b, v55
	v_exp_f32_e32 v49, v49
; DEV u16 f2bf(float f) { return (u16)(pk2bf(f, 0.f) & 0xffffu); }
; DEV float bf2f(u16 h) { return __uint_as_float(((unsigned)h) << 16); }
; DEV float siluf_(float x) { return x / (1.0f + __expf(-x)); }
; template <int MI>
; DEV void p4_tile(const Params& p, int l, int m0, int nt, unsigned char* smem) {
;     ...
;     acc_foreach_t<MI>([&](int mi, int ni, int r, int row, int col) __attribute__((always_inline)) {
;       sC[row * LDC + col] = f2bf(bf2f(sC[row * LDC + col]) * siluf_(acc[mi][ni][r]));
	v_cvt_pk_bf16_f32 v48, v48, s0
	ds_write_b16 v128, v48 offset:20128
	v_add_f32_e32 v49, 1.0, v49
	v_lshlrev_b32_e32 v48, 16, v147
	v_rcp_f32_e32 v50, v49
	s_nop 0
	v_mul_f32_e32 v49, v55, v50
	v_mul_f32_e32 v48, v49, v48
	v_mul_f32_e32 v49, 0xbfb8aa3b, v56
	v_exp_f32_e32 v49, v49
	v_cvt_pk_bf16_f32 v48, v48, s0
	ds_write_b16 v128, v48 offset:20400
	v_add_f32_e32 v49, 1.0, v49
	v_lshlrev_b32_e32 v48, 16, v148
	v_rcp_f32_e32 v50, v49
	s_nop 0
	v_mul_f32_e32 v49, v56, v50
	v_mul_f32_e32 v48, v49, v48
	v_mul_f32_e32 v49, 0xbfb8aa3b, v57
	v_exp_f32_e32 v49, v49
	v_cvt_pk_bf16_f32 v48, v48, s0
	ds_write_b16 v128, v48 offset:21760
	v_add_f32_e32 v49, 1.0, v49
	v_lshlrev_b32_e32 v48, 16, v149
	v_rcp_f32_e32 v50, v49
	s_nop 0
	v_mul_f32_e32 v49, v57, v50
	v_mul_f32_e32 v48, v49, v48
	v_mul_f32_e32 v49, 0xbfb8aa3b, v58
	v_exp_f32_e32 v49, v49
	v_cvt_pk_bf16_f32 v48, v48, s0
	ds_write_b16 v128, v48 offset:22032
	v_add_f32_e32 v49, 1.0, v49
	v_lshlrev_b32_e32 v48, 16, v150
	v_rcp_f32_e32 v50, v49
	s_nop 0
	v_mul_f32_e32 v49, v58, v50
	v_mul_f32_e32 v48, v49, v48
	v_mul_f32_e32 v49, 0xbfb8aa3b, v59
	v_exp_f32_e32 v49, v49
	v_cvt_pk_bf16_f32 v48, v48, s0
	ds_write_b16 v128, v48 offset:22304
	v_add_f32_e32 v49, 1.0, v49
	v_lshlrev_b32_e32 v48, 16, v151
	v_rcp_f32_e32 v50, v49
	s_nop 0
	v_mul_f32_e32 v49, v59, v50
	v_mul_f32_e32 v48, v49, v48
	v_mul_f32_e32 v49, 0xbfb8aa3b, v60
	v_exp_f32_e32 v49, v49
	v_cvt_pk_bf16_f32 v48, v48, s0
	ds_write_b16 v128, v48 offset:22576
	v_add_f32_e32 v49, 1.0, v49
	v_lshlrev_b32_e32 v48, 16, v152
	v_rcp_f32_e32 v50, v49
	s_nop 0
	v_mul_f32_e32 v49, v60, v50
	v_mul_f32_e32 v48, v49, v48
	v_mul_f32_e32 v49, 0xbfb8aa3b, v61
	v_exp_f32_e32 v49, v49
	v_cvt_pk_bf16_f32 v48, v48, s0
	ds_write_b16 v128, v48 offset:23936
	v_add_f32_e32 v49, 1.0, v49
	v_lshlrev_b32_e32 v48, 16, v153
	v_rcp_f32_e32 v50, v49
	s_nop 0
	v_mul_f32_e32 v49, v61, v50
	v_mul_f32_e32 v48, v49, v48
	v_mul_f32_e32 v49, 0xbfb8aa3b, v62
	v_exp_f32_e32 v49, v49
	v_cvt_pk_bf16_f32 v48, v48, s0
	ds_write_b16 v128, v48 offset:24208
	v_add_f32_e32 v49, 1.0, v49
	v_lshlrev_b32_e32 v48, 16, v154
	v_rcp_f32_e32 v50, v49
	s_nop 0
	v_mul_f32_e32 v49, v62, v50
	v_mul_f32_e32 v48, v49, v48
	v_mul_f32_e32 v49, 0xbfb8aa3b, v63
	v_exp_f32_e32 v49, v49
	v_cvt_pk_bf16_f32 v48, v48, s0
	ds_write_b16 v128, v48 offset:24480
	v_add_f32_e32 v49, 1.0, v49
	v_lshlrev_b32_e32 v48, 16, v155
	v_rcp_f32_e32 v50, v49
	s_nop 0
	v_mul_f32_e32 v49, v63, v50
	v_mul_f32_e32 v48, v49, v48
	v_mul_f32_e32 v49, 0xbfb8aa3b, v32
	v_exp_f32_e32 v49, v49
	v_cvt_pk_bf16_f32 v48, v48, s0
	ds_write_b16 v128, v48 offset:24752
	v_add_f32_e32 v49, 1.0, v49
	v_lshlrev_b32_e32 v48, 16, v156
	v_rcp_f32_e32 v50, v49
	s_nop 0
	v_mul_f32_e32 v32, v32, v50
	v_mul_f32_e32 v32, v32, v48
	v_mul_f32_e32 v48, 0xbfb8aa3b, v33
	v_exp_f32_e32 v48, v48
	v_cvt_pk_bf16_f32 v32, v32, s0
	ds_write_b16 v128, v32 offset:17472
	v_add_f32_e32 v48, 1.0, v48
	v_lshlrev_b32_e32 v32, 16, v157
	v_rcp_f32_e32 v49, v48
	s_nop 0
	v_mul_f32_e32 v33, v33, v49
	v_mul_f32_e32 v32, v33, v32
	v_mul_f32_e32 v33, 0xbfb8aa3b, v34
	v_exp_f32_e32 v33, v33
	v_cvt_pk_bf16_f32 v32, v32, s0
	ds_write_b16 v128, v32 offset:17744
	v_add_f32_e32 v33, 1.0, v33
	v_lshlrev_b32_e32 v32, 16, v158
	v_rcp_f32_e32 v48, v33
	s_nop 0
	v_mul_f32_e32 v33, v34, v48
	v_mul_f32_e32 v32, v33, v32
	v_mul_f32_e32 v33, 0xbfb8aa3b, v35
	v_exp_f32_e32 v33, v33
	v_cvt_pk_bf16_f32 v32, v32, s0
	ds_write_b16 v128, v32 offset:18016
	v_add_f32_e32 v33, 1.0, v33
	v_lshlrev_b32_e32 v32, 16, v159
	v_rcp_f32_e32 v34, v33
	s_nop 0
	v_mul_f32_e32 v33, v35, v34
	v_mul_f32_e32 v32, v33, v32
	v_mul_f32_e32 v33, 0xbfb8aa3b, v36
	v_exp_f32_e32 v33, v33
	v_cvt_pk_bf16_f32 v32, v32, s0
	ds_write_b16 v128, v32 offset:18288
	v_add_f32_e32 v33, 1.0, v33
	v_lshlrev_b32_e32 v32, 16, v160
	v_rcp_f32_e32 v34, v33
	s_nop 0
	v_mul_f32_e32 v33, v36, v34
	v_mul_f32_e32 v32, v33, v32
	v_mul_f32_e32 v33, 0xbfb8aa3b, v37
	v_exp_f32_e32 v33, v33
	v_cvt_pk_bf16_f32 v32, v32, s0
	ds_write_b16 v128, v32 offset:19648
	v_add_f32_e32 v33, 1.0, v33
	v_lshlrev_b32_e32 v32, 16, v161
	v_rcp_f32_e32 v34, v33
	s_nop 0
	v_mul_f32_e32 v33, v37, v34
	v_mul_f32_e32 v32, v33, v32
	v_mul_f32_e32 v33, 0xbfb8aa3b, v38
	v_exp_f32_e32 v33, v33
	v_cvt_pk_bf16_f32 v32, v32, s0
	ds_write_b16 v128, v32 offset:19920
	v_add_f32_e32 v33, 1.0, v33
	v_lshlrev_b32_e32 v32, 16, v162
	v_rcp_f32_e32 v34, v33
	s_nop 0
	v_mul_f32_e32 v33, v38, v34
	v_mul_f32_e32 v32, v33, v32
	v_mul_f32_e32 v33, 0xbfb8aa3b, v39
	v_exp_f32_e32 v33, v33
	v_cvt_pk_bf16_f32 v32, v32, s0
	ds_write_b16 v128, v32 offset:20192
	v_add_f32_e32 v33, 1.0, v33
	v_lshlrev_b32_e32 v32, 16, v163
	v_rcp_f32_e32 v34, v33
	s_nop 0
	v_mul_f32_e32 v33, v39, v34
	v_mul_f32_e32 v32, v33, v32
	v_mul_f32_e32 v33, 0xbfb8aa3b, v40
	v_exp_f32_e32 v33, v33
	v_cvt_pk_bf16_f32 v32, v32, s0
	ds_write_b16 v128, v32 offset:20464
	v_add_f32_e32 v33, 1.0, v33
	v_lshlrev_b32_e32 v32, 16, v164
	v_rcp_f32_e32 v34, v33
	s_nop 0
	v_mul_f32_e32 v33, v40, v34
	v_mul_f32_e32 v32, v33, v32
	v_mul_f32_e32 v33, 0xbfb8aa3b, v41
	v_exp_f32_e32 v33, v33
	v_cvt_pk_bf16_f32 v32, v32, s0
	ds_write_b16 v128, v32 offset:21824
	v_add_f32_e32 v33, 1.0, v33
	v_lshlrev_b32_e32 v32, 16, v165
	v_rcp_f32_e32 v34, v33
	s_nop 0
	v_mul_f32_e32 v33, v41, v34
	v_mul_f32_e32 v32, v33, v32
	v_mul_f32_e32 v33, 0xbfb8aa3b, v42
	v_exp_f32_e32 v33, v33
	v_cvt_pk_bf16_f32 v32, v32, s0
	ds_write_b16 v128, v32 offset:22096
	v_add_f32_e32 v33, 1.0, v33
	v_lshlrev_b32_e32 v32, 16, v166
	v_rcp_f32_e32 v34, v33
	s_nop 0
	v_mul_f32_e32 v33, v42, v34
	v_mul_f32_e32 v32, v33, v32
	v_mul_f32_e32 v33, 0xbfb8aa3b, v43
	v_exp_f32_e32 v33, v33
; DEV u16 f2bf(float f) { return (u16)(pk2bf(f, 0.f) & 0xffffu); }
; DEV float bf2f(u16 h) { return __uint_as_float(((unsigned)h) << 16); }
; DEV float siluf_(float x) { return x / (1.0f + __expf(-x)); }
; template <int MI>
; DEV void p4_tile(const Params& p, int l, int m0, int nt, unsigned char* smem) {
;     ...
;     acc_foreach_t<MI>([&](int mi, int ni, int r, int row, int col) __attribute__((always_inline)) {
;       sC[row * LDC + col] = f2bf(bf2f(sC[row * LDC + col]) * siluf_(acc[mi][ni][r]));
	v_cvt_pk_bf16_f32 v32, v32, s0
	ds_write_b16 v128, v32 offset:22368
	v_add_f32_e32 v33, 1.0, v33
	v_lshlrev_b32_e32 v32, 16, v167
	v_rcp_f32_e32 v34, v33
	s_nop 0
	v_mul_f32_e32 v33, v43, v34
	v_mul_f32_e32 v32, v33, v32
	v_mul_f32_e32 v33, 0xbfb8aa3b, v44
	v_exp_f32_e32 v33, v33
	v_cvt_pk_bf16_f32 v32, v32, s0
	ds_write_b16 v128, v32 offset:22640
	v_add_f32_e32 v33, 1.0, v33
	v_lshlrev_b32_e32 v32, 16, v168
	v_rcp_f32_e32 v34, v33
	s_nop 0
	v_mul_f32_e32 v33, v44, v34
	v_mul_f32_e32 v32, v33, v32
	v_mul_f32_e32 v33, 0xbfb8aa3b, v45
	v_exp_f32_e32 v33, v33
	v_cvt_pk_bf16_f32 v32, v32, s0
	ds_write_b16 v128, v32 offset:24000
	v_add_f32_e32 v33, 1.0, v33
	v_lshlrev_b32_e32 v32, 16, v169
	v_rcp_f32_e32 v34, v33
	s_nop 0
	v_mul_f32_e32 v33, v45, v34
	v_mul_f32_e32 v32, v33, v32
	v_mul_f32_e32 v33, 0xbfb8aa3b, v46
	v_exp_f32_e32 v33, v33
	v_cvt_pk_bf16_f32 v32, v32, s0
	ds_write_b16 v128, v32 offset:24272
	v_add_f32_e32 v33, 1.0, v33
	v_lshlrev_b32_e32 v32, 16, v170
	v_rcp_f32_e32 v34, v33
	s_nop 0
	v_mul_f32_e32 v33, v46, v34
	v_mul_f32_e32 v32, v33, v32
	v_mul_f32_e32 v33, 0xbfb8aa3b, v47
	v_exp_f32_e32 v33, v33
	v_cvt_pk_bf16_f32 v32, v32, s0
	ds_write_b16 v128, v32 offset:24544
	v_add_f32_e32 v33, 1.0, v33
	v_lshlrev_b32_e32 v32, 16, v171
	v_rcp_f32_e32 v34, v33
	s_nop 0
	v_mul_f32_e32 v33, v47, v34
	v_mul_f32_e32 v32, v33, v32
	v_mul_f32_e32 v33, 0xbfb8aa3b, v16
	v_exp_f32_e32 v33, v33
	v_cvt_pk_bf16_f32 v32, v32, s0
	ds_write_b16 v128, v32 offset:24816
	v_add_f32_e32 v33, 1.0, v33
	v_lshlrev_b32_e32 v32, 16, v172
	v_rcp_f32_e32 v34, v33
	s_nop 0
	v_mul_f32_e32 v16, v16, v34
	v_mul_f32_e32 v16, v16, v32
	v_mul_f32_e32 v32, 0xbfb8aa3b, v17
	v_exp_f32_e32 v32, v32
	v_cvt_pk_bf16_f32 v16, v16, s0
	ds_write_b16 v128, v16 offset:26112
	v_add_f32_e32 v32, 1.0, v32
	v_lshlrev_b32_e32 v16, 16, v173
	v_rcp_f32_e32 v33, v32
	s_nop 0
	v_mul_f32_e32 v17, v17, v33
	v_mul_f32_e32 v16, v17, v16
	v_mul_f32_e32 v17, 0xbfb8aa3b, v18
	v_exp_f32_e32 v17, v17
	v_cvt_pk_bf16_f32 v16, v16, s0
	ds_write_b16 v128, v16 offset:26384
	v_add_f32_e32 v17, 1.0, v17
	v_lshlrev_b32_e32 v16, 16, v174
	v_rcp_f32_e32 v32, v17
	s_nop 0
	v_mul_f32_e32 v17, v18, v32
	v_mul_f32_e32 v16, v17, v16
	v_mul_f32_e32 v17, 0xbfb8aa3b, v19
	v_exp_f32_e32 v17, v17
	v_cvt_pk_bf16_f32 v16, v16, s0
	ds_write_b16 v128, v16 offset:26656
	v_add_f32_e32 v17, 1.0, v17
	v_lshlrev_b32_e32 v16, 16, v175
	v_rcp_f32_e32 v18, v17
	s_nop 0
	v_mul_f32_e32 v17, v19, v18
	v_mul_f32_e32 v16, v17, v16
	v_mul_f32_e32 v17, 0xbfb8aa3b, v20
	v_exp_f32_e32 v17, v17
	v_cvt_pk_bf16_f32 v16, v16, s0
	ds_write_b16 v128, v16 offset:26928
	v_add_f32_e32 v17, 1.0, v17
	v_lshlrev_b32_e32 v16, 16, v176
	v_rcp_f32_e32 v18, v17
	s_nop 0
	v_mul_f32_e32 v17, v20, v18
	v_mul_f32_e32 v16, v17, v16
	v_mul_f32_e32 v17, 0xbfb8aa3b, v21
	v_exp_f32_e32 v17, v17
	v_cvt_pk_bf16_f32 v16, v16, s0
	ds_write_b16 v128, v16 offset:28288
	v_add_f32_e32 v17, 1.0, v17
	v_lshlrev_b32_e32 v16, 16, v177
	v_rcp_f32_e32 v18, v17
	s_nop 0
	v_mul_f32_e32 v17, v21, v18
	v_mul_f32_e32 v16, v17, v16
	v_mul_f32_e32 v17, 0xbfb8aa3b, v22
	v_exp_f32_e32 v17, v17
	v_cvt_pk_bf16_f32 v16, v16, s0
	ds_write_b16 v128, v16 offset:28560
	v_add_f32_e32 v17, 1.0, v17
	v_lshlrev_b32_e32 v16, 16, v178
	v_rcp_f32_e32 v18, v17
	s_nop 0
	v_mul_f32_e32 v17, v22, v18
	v_mul_f32_e32 v16, v17, v16
	v_mul_f32_e32 v17, 0xbfb8aa3b, v23
	v_exp_f32_e32 v17, v17
	v_cvt_pk_bf16_f32 v16, v16, s0
	ds_write_b16 v128, v16 offset:28832
	v_add_f32_e32 v17, 1.0, v17
	v_lshlrev_b32_e32 v16, 16, v179
	v_rcp_f32_e32 v18, v17
	s_nop 0
	v_mul_f32_e32 v17, v23, v18
	v_mul_f32_e32 v16, v17, v16
	v_mul_f32_e32 v17, 0xbfb8aa3b, v24
	v_exp_f32_e32 v17, v17
	v_cvt_pk_bf16_f32 v16, v16, s0
	ds_write_b16 v128, v16 offset:29104
	v_add_f32_e32 v17, 1.0, v17
	v_lshlrev_b32_e32 v16, 16, v180
	v_rcp_f32_e32 v18, v17
	s_nop 0
	v_mul_f32_e32 v17, v24, v18
	v_mul_f32_e32 v16, v17, v16
	v_mul_f32_e32 v17, 0xbfb8aa3b, v25
	v_exp_f32_e32 v17, v17
	v_cvt_pk_bf16_f32 v16, v16, s0
	ds_write_b16 v128, v16 offset:30464
	v_add_f32_e32 v17, 1.0, v17
	v_lshlrev_b32_e32 v16, 16, v181
	v_rcp_f32_e32 v18, v17
	s_nop 0
	v_mul_f32_e32 v17, v25, v18
	v_mul_f32_e32 v16, v17, v16
	v_mul_f32_e32 v17, 0xbfb8aa3b, v26
	v_exp_f32_e32 v17, v17
	v_cvt_pk_bf16_f32 v16, v16, s0
	ds_write_b16 v128, v16 offset:30736
	v_add_f32_e32 v17, 1.0, v17
	v_lshlrev_b32_e32 v16, 16, v182
	v_rcp_f32_e32 v18, v17
	s_nop 0
	v_mul_f32_e32 v17, v26, v18
	v_mul_f32_e32 v16, v17, v16
	v_mul_f32_e32 v17, 0xbfb8aa3b, v27
	v_exp_f32_e32 v17, v17
	v_cvt_pk_bf16_f32 v16, v16, s0
	ds_write_b16 v128, v16 offset:31008
	v_add_f32_e32 v17, 1.0, v17
	v_lshlrev_b32_e32 v16, 16, v183
	v_rcp_f32_e32 v18, v17
	s_nop 0
	v_mul_f32_e32 v17, v27, v18
	v_mul_f32_e32 v16, v17, v16
	v_mul_f32_e32 v17, 0xbfb8aa3b, v28
	v_exp_f32_e32 v17, v17
	v_cvt_pk_bf16_f32 v16, v16, s0
	ds_write_b16 v128, v16 offset:31280
	v_add_f32_e32 v17, 1.0, v17
	v_lshlrev_b32_e32 v16, 16, v184
	v_rcp_f32_e32 v18, v17
	s_nop 0
	v_mul_f32_e32 v17, v28, v18
	v_mul_f32_e32 v16, v17, v16
	v_mul_f32_e32 v17, 0xbfb8aa3b, v29
	v_exp_f32_e32 v17, v17
	v_cvt_pk_bf16_f32 v16, v16, s0
	ds_write_b16 v128, v16 offset:32640
	v_add_f32_e32 v17, 1.0, v17
	v_lshlrev_b32_e32 v16, 16, v185
; DEV u16 f2bf(float f) { return (u16)(pk2bf(f, 0.f) & 0xffffu); }
; DEV float bf2f(u16 h) { return __uint_as_float(((unsigned)h) << 16); }
; DEV float siluf_(float x) { return x / (1.0f + __expf(-x)); }
; template <int MI>
; DEV void p4_tile(const Params& p, int l, int m0, int nt, unsigned char* smem) {
;     ...
;     acc_foreach_t<MI>([&](int mi, int ni, int r, int row, int col) __attribute__((always_inline)) {
;       sC[row * LDC + col] = f2bf(bf2f(sC[row * LDC + col]) * siluf_(acc[mi][ni][r]));
;     });
;     tile_store_t<MI>(smem, YB + (size_t)m0 * 1024 + nt * 128, 1024);
	v_rcp_f32_e32 v18, v17
	s_nop 0
	v_mul_f32_e32 v17, v29, v18
	v_mul_f32_e32 v16, v17, v16
	v_mul_f32_e32 v17, 0xbfb8aa3b, v30
	v_exp_f32_e32 v17, v17
	v_cvt_pk_bf16_f32 v16, v16, s0
	ds_write_b16 v128, v16 offset:32912
	v_add_f32_e32 v17, 1.0, v17
	v_lshlrev_b32_e32 v16, 16, v186
	v_rcp_f32_e32 v18, v17
	s_nop 0
	v_mul_f32_e32 v17, v30, v18
	v_mul_f32_e32 v16, v17, v16
	v_mul_f32_e32 v17, 0xbfb8aa3b, v31
	v_exp_f32_e32 v17, v17
	v_cvt_pk_bf16_f32 v16, v16, s0
	ds_write_b16 v128, v16 offset:33184
	v_add_f32_e32 v17, 1.0, v17
	v_lshlrev_b32_e32 v16, 16, v187
	v_rcp_f32_e32 v18, v17
	s_nop 0
	v_mul_f32_e32 v17, v31, v18
	v_mul_f32_e32 v16, v17, v16
	v_mul_f32_e32 v17, 0xbfb8aa3b, v0
	v_exp_f32_e32 v17, v17
	v_cvt_pk_bf16_f32 v16, v16, s0
	ds_write_b16 v128, v16 offset:33456
	v_add_f32_e32 v17, 1.0, v17
	v_lshlrev_b32_e32 v16, 16, v188
	v_rcp_f32_e32 v18, v17
	s_nop 0
	v_mul_f32_e32 v0, v0, v18
	v_mul_f32_e32 v0, v0, v16
	v_mul_f32_e32 v16, 0xbfb8aa3b, v1
	v_exp_f32_e32 v16, v16
	v_cvt_pk_bf16_f32 v0, v0, s0
	ds_write_b16 v128, v0 offset:26176
	v_add_f32_e32 v16, 1.0, v16
	v_lshlrev_b32_e32 v0, 16, v189
	v_rcp_f32_e32 v17, v16
	s_nop 0
	v_mul_f32_e32 v1, v1, v17
	v_mul_f32_e32 v0, v1, v0
	v_mul_f32_e32 v1, 0xbfb8aa3b, v2
	v_exp_f32_e32 v1, v1
	v_cvt_pk_bf16_f32 v0, v0, s0
	ds_write_b16 v128, v0 offset:26448
	v_add_f32_e32 v1, 1.0, v1
	v_lshlrev_b32_e32 v0, 16, v190
	v_rcp_f32_e32 v16, v1
	s_nop 0
	v_mul_f32_e32 v1, v2, v16
	v_mul_f32_e32 v0, v1, v0
	v_mul_f32_e32 v1, 0xbfb8aa3b, v3
	v_exp_f32_e32 v1, v1
	v_cvt_pk_bf16_f32 v0, v0, s0
	ds_write_b16 v128, v0 offset:26720
	v_add_f32_e32 v1, 1.0, v1
	v_lshlrev_b32_e32 v0, 16, v191
	v_rcp_f32_e32 v2, v1
	s_nop 0
	v_mul_f32_e32 v1, v3, v2
	v_mul_f32_e32 v0, v1, v0
	v_mul_f32_e32 v1, 0xbfb8aa3b, v4
	v_exp_f32_e32 v1, v1
	v_cvt_pk_bf16_f32 v0, v0, s0
	ds_write_b16 v128, v0 offset:26992
	v_add_f32_e32 v1, 1.0, v1
	v_lshlrev_b32_e32 v0, 16, v192
	v_rcp_f32_e32 v2, v1
	s_nop 0
	v_mul_f32_e32 v1, v4, v2
	v_mul_f32_e32 v0, v1, v0
	v_mul_f32_e32 v1, 0xbfb8aa3b, v5
	v_exp_f32_e32 v1, v1
	v_cvt_pk_bf16_f32 v0, v0, s0
	ds_write_b16 v128, v0 offset:28352
	v_add_f32_e32 v1, 1.0, v1
	v_lshlrev_b32_e32 v0, 16, v193
	v_rcp_f32_e32 v2, v1
	s_nop 0
	v_mul_f32_e32 v1, v5, v2
	v_mul_f32_e32 v0, v1, v0
	v_mul_f32_e32 v1, 0xbfb8aa3b, v6
	v_exp_f32_e32 v1, v1
	v_cvt_pk_bf16_f32 v0, v0, s0
	ds_write_b16 v128, v0 offset:28624
	v_add_f32_e32 v1, 1.0, v1
	v_lshlrev_b32_e32 v0, 16, v194
	v_rcp_f32_e32 v2, v1
	s_nop 0
	v_mul_f32_e32 v1, v6, v2
	v_mul_f32_e32 v0, v1, v0
	v_mul_f32_e32 v1, 0xbfb8aa3b, v7
	v_exp_f32_e32 v1, v1
	v_cvt_pk_bf16_f32 v0, v0, s0
	ds_write_b16 v128, v0 offset:28896
	v_add_f32_e32 v1, 1.0, v1
	v_lshlrev_b32_e32 v0, 16, v195
	v_rcp_f32_e32 v2, v1
	s_nop 0
	v_mul_f32_e32 v1, v7, v2
	v_mul_f32_e32 v0, v1, v0
	v_mul_f32_e32 v1, 0xbfb8aa3b, v8
	v_exp_f32_e32 v1, v1
	v_cvt_pk_bf16_f32 v0, v0, s0
	ds_write_b16 v128, v0 offset:29168
	v_add_f32_e32 v1, 1.0, v1
	v_lshlrev_b32_e32 v0, 16, v196
	v_rcp_f32_e32 v2, v1
	s_nop 0
	v_mul_f32_e32 v1, v8, v2
	v_mul_f32_e32 v0, v1, v0
	v_mul_f32_e32 v1, 0xbfb8aa3b, v9
	v_exp_f32_e32 v1, v1
	v_cvt_pk_bf16_f32 v0, v0, s0
	ds_write_b16 v128, v0 offset:30528
	v_add_f32_e32 v1, 1.0, v1
	v_lshlrev_b32_e32 v0, 16, v197
	v_rcp_f32_e32 v2, v1
	s_nop 0
	v_mul_f32_e32 v1, v9, v2
	v_mul_f32_e32 v0, v1, v0
	v_mul_f32_e32 v1, 0xbfb8aa3b, v10
	v_exp_f32_e32 v1, v1
	v_cvt_pk_bf16_f32 v0, v0, s0
	ds_write_b16 v128, v0 offset:30800
	v_add_f32_e32 v1, 1.0, v1
	v_lshlrev_b32_e32 v0, 16, v198
	v_rcp_f32_e32 v2, v1
	s_nop 0
	v_mul_f32_e32 v1, v10, v2
	v_mul_f32_e32 v0, v1, v0
	v_mul_f32_e32 v1, 0xbfb8aa3b, v11
	v_exp_f32_e32 v1, v1
	v_cvt_pk_bf16_f32 v0, v0, s0
	ds_write_b16 v128, v0 offset:31072
	v_add_f32_e32 v1, 1.0, v1
	v_lshlrev_b32_e32 v0, 16, v199
	v_rcp_f32_e32 v2, v1
	s_nop 0
	v_mul_f32_e32 v1, v11, v2
	v_mul_f32_e32 v0, v1, v0
	v_mul_f32_e32 v1, 0xbfb8aa3b, v12
	v_exp_f32_e32 v1, v1
	v_cvt_pk_bf16_f32 v0, v0, s0
	ds_write_b16 v128, v0 offset:31344
	v_add_f32_e32 v1, 1.0, v1
	v_lshlrev_b32_e32 v0, 16, v200
	v_rcp_f32_e32 v2, v1
	s_nop 0
	v_mul_f32_e32 v1, v12, v2
	v_mul_f32_e32 v0, v1, v0
	v_mul_f32_e32 v1, 0xbfb8aa3b, v13
	v_exp_f32_e32 v1, v1
	v_cvt_pk_bf16_f32 v0, v0, s0
	ds_write_b16 v128, v0 offset:32704
	v_add_f32_e32 v1, 1.0, v1
	v_lshlrev_b32_e32 v0, 16, v201
	v_rcp_f32_e32 v2, v1
	s_nop 0
	v_mul_f32_e32 v1, v13, v2
	v_mul_f32_e32 v0, v1, v0
	v_mul_f32_e32 v1, 0xbfb8aa3b, v14
	v_exp_f32_e32 v1, v1
	v_cvt_pk_bf16_f32 v0, v0, s0
	ds_write_b16 v128, v0 offset:32976
	v_add_f32_e32 v1, 1.0, v1
	v_lshlrev_b32_e32 v0, 16, v202
	v_rcp_f32_e32 v2, v1
	s_nop 0
	v_mul_f32_e32 v1, v14, v2
	v_mul_f32_e32 v0, v1, v0
	v_mul_f32_e32 v1, 0xbfb8aa3b, v15
	v_exp_f32_e32 v1, v1
	v_cvt_pk_bf16_f32 v0, v0, s0
	ds_write_b16 v128, v0 offset:33248
	v_add_f32_e32 v1, 1.0, v1
	v_lshlrev_b32_e32 v0, 16, v203
	v_rcp_f32_e32 v2, v1
	s_nop 0
	v_mul_f32_e32 v1, v15, v2
	v_mul_f32_e32 v0, v1, v0
	v_cvt_pk_bf16_f32 v0, v0, s0
	s_lshl_b64 s[0:1], s[4:5], 1
	s_add_u32 s0, s17, s0
	s_addc_u32 s1, s18, s1
	s_lshl_b32 s4, s37, 8
	s_add_u32 s4, s0, s4
	ds_write_b16 v128, v0 offset:33520
	s_addc_u32 s5, s1, 0
	v_mov_b32_e32 v0, v232
	s_waitcnt lgkmcnt(0)
	s_barrier

; DEV u16 f2bf(float f) { return (u16)(pk2bf(f, 0.f) & 0xffffu); }
; DEV float bf2f(u16 h) { return __uint_as_float(((unsigned)h) << 16); }
; DEV float siluf_(float x) { return x / (1.0f + __expf(-x)); }
; template <int MI>
; DEV void tile_load_t(unsigned char* smem, const u16* src, size_t lds_) {
;   u16* sC = (u16*)smem;
;   const int tid_ = TIDX();
; #pragma unroll
;   for (int i = 0; i < MI * 4; ++i) {
;     const int c = tid_ + 256 * i, row = c >> 4, cc = (c & 15) * 8;
;     *(bf16x8*)(sC + row * LDC + cc) = __builtin_nontemporal_load((const bf16x8*)(src + (size_t)row * lds_ + cc));
;   }
;   __syncthreads();
; }
; template <int MI>
; DEV void p4_tile(const Params& p, int l, int m0, int nt, unsigned char* smem) {
;     ...
;     const int n0 = (nt - 8) * 128;
;     zero_acc_t<MI>(acc);
;     gemm_mm<MI>(acc, H + (size_t)m0 * 1024, 1024, WL + WO_G + (size_t)n0 * 1024, 1024, 1024, smem);
;     tile_load_t<MI>(smem, YA + (size_t)m0 * 1024 + n0, 1024);
;     acc_foreach_t<MI>([&](int mi, int ni, int r, int row, int col) __attribute__((always_inline)) {
;       sC[row * LDC + col] = f2bf(bf2f(sC[row * LDC + col]) * siluf_(acc[mi][ni][r]));
.LBB0_1218:
	s_lshl_b64 s[4:5], s[4:5], 1
	s_add_u32 s1, s15, s4
	s_addc_u32 s6, s16, s5
	s_lshl_b64 s[4:5], s[96:97], 1
	s_waitcnt vmcnt(11)
	v_mov_b32_e32 v136, v232
	s_barrier
	s_add_u32 s4, s1, s4
	s_addc_u32 s5, s6, s5
	s_waitcnt vmcnt(10)
	v_lshlrev_b32_e32 v128, 4, v136
	s_waitcnt vmcnt(9)
	v_ashrrev_i32_e32 v134, 4, v136
	v_and_b32_e32 v224, 0xf0, v128
	v_ashrrev_i32_e32 v135, 31, v134
	v_lshl_add_u64 v[128:129], s[4:5], 0, v[224:225]
	v_lshlrev_b64 v[204:205], 11, v[134:135]
	v_lshl_add_u64 v[204:205], v[128:129], 0, v[204:205]
	v_mad_u64_u32 v[206:207], s[6:7], v134, s42, v[224:225]
	s_mov_b32 s6, 0x8000
	s_mov_b32 s7, 0
	global_load_dwordx4 v[140:143], v[204:205], off nt
	v_lshl_add_u64 v[204:205], v[204:205], 0, s[6:7]
	global_load_dwordx4 v[144:147], v[204:205], off nt
	v_lshl_add_u64 v[204:205], v[204:205], 0, s[6:7]
	global_load_dwordx4 v[148:151], v[204:205], off nt
	v_lshl_add_u64 v[204:205], v[204:205], 0, s[6:7]
	global_load_dwordx4 v[152:155], v[204:205], off nt
	v_lshl_add_u64 v[204:205], v[204:205], 0, s[6:7]
	global_load_dwordx4 v[156:159], v[204:205], off nt
	v_lshl_add_u64 v[204:205], v[204:205], 0, s[6:7]
	global_load_dwordx4 v[160:163], v[204:205], off nt
	v_lshl_add_u64 v[204:205], v[204:205], 0, s[6:7]
	global_load_dwordx4 v[164:167], v[204:205], off nt
	v_lshl_add_u64 v[204:205], v[204:205], 0, s[6:7]
	global_load_dwordx4 v[168:171], v[204:205], off nt
	v_lshl_add_u64 v[204:205], v[204:205], 0, s[6:7]
	global_load_dwordx4 v[172:175], v[204:205], off nt
	v_lshl_add_u64 v[204:205], v[204:205], 0, s[6:7]
	global_load_dwordx4 v[176:179], v[204:205], off nt
	v_lshl_add_u64 v[204:205], v[204:205], 0, s[6:7]
	global_load_dwordx4 v[180:183], v[204:205], off nt
	v_lshl_add_u64 v[204:205], v[204:205], 0, s[6:7]
	global_load_dwordx4 v[184:187], v[204:205], off nt
	v_lshl_add_u64 v[204:205], v[204:205], 0, s[6:7]
	global_load_dwordx4 v[188:191], v[204:205], off nt
	v_lshl_add_u64 v[204:205], v[204:205], 0, s[6:7]
	global_load_dwordx4 v[192:195], v[204:205], off nt
	v_lshl_add_u64 v[204:205], v[204:205], 0, s[6:7]
	global_load_dwordx4 v[196:199], v[204:205], off nt
	v_lshl_add_u64 v[204:205], v[204:205], 0, s[6:7]
	global_load_dwordx4 v[200:203], v[204:205], off nt
	s_waitcnt vmcnt(15)
	ds_write_b128 v206, v[140:143]
	s_waitcnt vmcnt(14)
	ds_write_b128 v206, v[144:147] offset:4352
	s_waitcnt vmcnt(13)
	ds_write_b128 v206, v[148:151] offset:8704
	s_waitcnt vmcnt(12)
	ds_write_b128 v206, v[152:155] offset:13056
	s_waitcnt vmcnt(11)
	ds_write_b128 v206, v[156:159] offset:17408
	s_waitcnt vmcnt(10)
	ds_write_b128 v206, v[160:163] offset:21760
	s_waitcnt vmcnt(9)
	ds_write_b128 v206, v[164:167] offset:26112
	s_waitcnt vmcnt(8)
	ds_write_b128 v206, v[168:171] offset:30464
	s_waitcnt vmcnt(7)
	ds_write_b128 v206, v[172:175] offset:34816
	s_waitcnt vmcnt(6)
	ds_write_b128 v206, v[176:179] offset:39168
	s_waitcnt vmcnt(5)
	ds_write_b128 v206, v[180:183] offset:43520
	s_waitcnt vmcnt(4)
	ds_write_b128 v206, v[184:187] offset:47872
	s_waitcnt vmcnt(3)
	ds_write_b128 v206, v[188:191] offset:52224
	s_waitcnt vmcnt(2)
	ds_write_b128 v206, v[192:195] offset:56576
	s_waitcnt vmcnt(1)
	ds_write_b128 v206, v[196:199] offset:60928
	s_waitcnt vmcnt(0)
	ds_write_b128 v206, v[200:203] offset:65280
	v_mov_b32_e32 v128, v232
	s_waitcnt lgkmcnt(0)
	s_barrier
	s_nop 0
	v_and_b32_e32 v129, 0xfffff80, v128
	v_lshrrev_b32_e32 v130, 3, v128
	v_and_or_b32 v129, v130, 4, v129
	v_mul_f32_e32 v130, 0xbfb8aa3b, v112
	v_exp_f32_e32 v130, v130
	v_and_b32_e32 v128, 0x5f, v128
	v_mul_lo_u32 v129, v129, s42
	v_lshl_add_u32 v128, v128, 1, v129
	v_add_f32_e32 v130, 1.0, v130
	ds_read_u16 v140, v128
	ds_read_u16 v141, v128 offset:272
	ds_read_u16 v142, v128 offset:544
	ds_read_u16 v143, v128 offset:816
	ds_read_u16 v144, v128 offset:2176
	ds_read_u16 v145, v128 offset:2448
	ds_read_u16 v146, v128 offset:2720
	ds_read_u16 v147, v128 offset:2992
	ds_read_u16 v148, v128 offset:4352
	ds_read_u16 v149, v128 offset:4624
	ds_read_u16 v150, v128 offset:4896
	ds_read_u16 v151, v128 offset:5168
	ds_read_u16 v152, v128 offset:6528
	ds_read_u16 v153, v128 offset:6800
	ds_read_u16 v154, v128 offset:7072
	ds_read_u16 v155, v128 offset:7344
	ds_read_u16 v156, v128 offset:64
	ds_read_u16 v157, v128 offset:336
	ds_read_u16 v158, v128 offset:608
	ds_read_u16 v159, v128 offset:880
	ds_read_u16 v160, v128 offset:2240
	ds_read_u16 v161, v128 offset:2512
	ds_read_u16 v162, v128 offset:2784
	ds_read_u16 v163, v128 offset:3056
	ds_read_u16 v164, v128 offset:4416
	ds_read_u16 v165, v128 offset:4688
	ds_read_u16 v166, v128 offset:4960
	ds_read_u16 v167, v128 offset:5232
	ds_read_u16 v168, v128 offset:6592
	ds_read_u16 v169, v128 offset:6864
	ds_read_u16 v170, v128 offset:7136
	ds_read_u16 v171, v128 offset:7408
	ds_read_u16 v172, v128 offset:8704
	ds_read_u16 v173, v128 offset:8976
	ds_read_u16 v174, v128 offset:9248
	ds_read_u16 v175, v128 offset:9520
	ds_read_u16 v176, v128 offset:10880
	ds_read_u16 v177, v128 offset:11152
	ds_read_u16 v178, v128 offset:11424
	ds_read_u16 v179, v128 offset:11696
	ds_read_u16 v180, v128 offset:13056
	ds_read_u16 v181, v128 offset:13328
	ds_read_u16 v182, v128 offset:13600
	ds_read_u16 v183, v128 offset:13872
	ds_read_u16 v184, v128 offset:15232
	ds_read_u16 v185, v128 offset:15504
	ds_read_u16 v186, v128 offset:15776
	ds_read_u16 v187, v128 offset:16048
	ds_read_u16 v188, v128 offset:8768
	ds_read_u16 v189, v128 offset:9040
	ds_read_u16 v190, v128 offset:9312
	ds_read_u16 v191, v128 offset:9584
	ds_read_u16 v192, v128 offset:10944
	ds_read_u16 v193, v128 offset:11216
	ds_read_u16 v194, v128 offset:11488
	ds_read_u16 v195, v128 offset:11760
	ds_read_u16 v196, v128 offset:13120
	ds_read_u16 v197, v128 offset:13392
	ds_read_u16 v198, v128 offset:13664
	ds_read_u16 v199, v128 offset:13936
	ds_read_u16 v200, v128 offset:15296
	ds_read_u16 v201, v128 offset:15568
	ds_read_u16 v202, v128 offset:15840
	ds_read_u16 v203, v128 offset:16112
	s_waitcnt lgkmcnt(0)
; DEV u16 f2bf(float f) { return (u16)(pk2bf(f, 0.f) & 0xffffu); }
; DEV float bf2f(u16 h) { return __uint_as_float(((unsigned)h) << 16); }
; DEV float siluf_(float x) { return x / (1.0f + __expf(-x)); }
; template <int MI>
; DEV void p4_tile(const Params& p, int l, int m0, int nt, unsigned char* smem) {
;     ...
;     acc_foreach_t<MI>([&](int mi, int ni, int r, int row, int col) __attribute__((always_inline)) {
;       sC[row * LDC + col] = f2bf(bf2f(sC[row * LDC + col]) * siluf_(acc[mi][ni][r]));
	v_lshlrev_b32_e32 v129, 16, v140
	v_rcp_f32_e32 v131, v130
	s_nop 0
	v_mul_f32_e32 v112, v112, v131
	v_mul_f32_e32 v112, v112, v129
	v_mul_f32_e32 v129, 0xbfb8aa3b, v113
	v_exp_f32_e32 v129, v129
	v_cvt_pk_bf16_f32 v112, v112, s0
	ds_write_b16 v128, v112
	v_add_f32_e32 v129, 1.0, v129
	v_lshlrev_b32_e32 v112, 16, v141
	v_rcp_f32_e32 v130, v129
	s_nop 0
	v_mul_f32_e32 v113, v113, v130
	v_mul_f32_e32 v112, v113, v112
	v_mul_f32_e32 v113, 0xbfb8aa3b, v114
	v_exp_f32_e32 v113, v113
	v_cvt_pk_bf16_f32 v112, v112, s0
	ds_write_b16 v128, v112 offset:272
	v_add_f32_e32 v113, 1.0, v113
	v_lshlrev_b32_e32 v112, 16, v142
	v_rcp_f32_e32 v129, v113
	s_nop 0
	v_mul_f32_e32 v113, v114, v129
	v_mul_f32_e32 v112, v113, v112
	v_mul_f32_e32 v113, 0xbfb8aa3b, v115
	v_exp_f32_e32 v113, v113
	v_cvt_pk_bf16_f32 v112, v112, s0
	ds_write_b16 v128, v112 offset:544
	v_add_f32_e32 v113, 1.0, v113
	v_lshlrev_b32_e32 v112, 16, v143
	v_rcp_f32_e32 v114, v113
	s_nop 0
	v_mul_f32_e32 v113, v115, v114
	v_mul_f32_e32 v112, v113, v112
	v_mul_f32_e32 v113, 0xbfb8aa3b, v116
	v_exp_f32_e32 v113, v113
	v_cvt_pk_bf16_f32 v112, v112, s0
	ds_write_b16 v128, v112 offset:816
	v_add_f32_e32 v113, 1.0, v113
	v_lshlrev_b32_e32 v112, 16, v144
	v_rcp_f32_e32 v114, v113
	s_nop 0
	v_mul_f32_e32 v113, v116, v114
	v_mul_f32_e32 v112, v113, v112
	v_mul_f32_e32 v113, 0xbfb8aa3b, v117
	v_exp_f32_e32 v113, v113
	v_cvt_pk_bf16_f32 v112, v112, s0
	ds_write_b16 v128, v112 offset:2176
	v_add_f32_e32 v113, 1.0, v113
	v_lshlrev_b32_e32 v112, 16, v145
	v_rcp_f32_e32 v114, v113
	s_nop 0
	v_mul_f32_e32 v113, v117, v114
	v_mul_f32_e32 v112, v113, v112
	v_mul_f32_e32 v113, 0xbfb8aa3b, v118
	v_exp_f32_e32 v113, v113
	v_cvt_pk_bf16_f32 v112, v112, s0
	ds_write_b16 v128, v112 offset:2448
	v_add_f32_e32 v113, 1.0, v113
	v_lshlrev_b32_e32 v112, 16, v146
	v_rcp_f32_e32 v114, v113
	s_nop 0
	v_mul_f32_e32 v113, v118, v114
	v_mul_f32_e32 v112, v113, v112
	v_mul_f32_e32 v113, 0xbfb8aa3b, v119
	v_exp_f32_e32 v113, v113
	v_cvt_pk_bf16_f32 v112, v112, s0
	ds_write_b16 v128, v112 offset:2720
	v_add_f32_e32 v113, 1.0, v113
	v_lshlrev_b32_e32 v112, 16, v147
	v_rcp_f32_e32 v114, v113
	s_nop 0
	v_mul_f32_e32 v113, v119, v114
	v_mul_f32_e32 v112, v113, v112
	v_mul_f32_e32 v113, 0xbfb8aa3b, v120
	v_exp_f32_e32 v113, v113
	v_cvt_pk_bf16_f32 v112, v112, s0
	ds_write_b16 v128, v112 offset:2992
	v_add_f32_e32 v113, 1.0, v113
	v_lshlrev_b32_e32 v112, 16, v148
	v_rcp_f32_e32 v114, v113
	s_nop 0
	v_mul_f32_e32 v113, v120, v114
	v_mul_f32_e32 v112, v113, v112
	v_mul_f32_e32 v113, 0xbfb8aa3b, v121
	v_exp_f32_e32 v113, v113
	v_cvt_pk_bf16_f32 v112, v112, s0
	ds_write_b16 v128, v112 offset:4352
	v_add_f32_e32 v113, 1.0, v113
	v_lshlrev_b32_e32 v112, 16, v149
	v_rcp_f32_e32 v114, v113
	s_nop 0
	v_mul_f32_e32 v113, v121, v114
	v_mul_f32_e32 v112, v113, v112
	v_mul_f32_e32 v113, 0xbfb8aa3b, v122
	v_exp_f32_e32 v113, v113
	v_cvt_pk_bf16_f32 v112, v112, s0
	ds_write_b16 v128, v112 offset:4624
	v_add_f32_e32 v113, 1.0, v113
	v_lshlrev_b32_e32 v112, 16, v150
	v_rcp_f32_e32 v114, v113
	s_nop 0
	v_mul_f32_e32 v113, v122, v114
	v_mul_f32_e32 v112, v113, v112
	v_mul_f32_e32 v113, 0xbfb8aa3b, v123
	v_exp_f32_e32 v113, v113
	v_cvt_pk_bf16_f32 v112, v112, s0
	ds_write_b16 v128, v112 offset:4896
	v_add_f32_e32 v113, 1.0, v113
	v_lshlrev_b32_e32 v112, 16, v151
	v_rcp_f32_e32 v114, v113
	s_nop 0
	v_mul_f32_e32 v113, v123, v114
	v_mul_f32_e32 v112, v113, v112
	v_mul_f32_e32 v113, 0xbfb8aa3b, v124
	v_exp_f32_e32 v113, v113
	v_cvt_pk_bf16_f32 v112, v112, s0
	ds_write_b16 v128, v112 offset:5168
	v_add_f32_e32 v113, 1.0, v113
	v_lshlrev_b32_e32 v112, 16, v152
	v_rcp_f32_e32 v114, v113
	s_nop 0
	v_mul_f32_e32 v113, v124, v114
	v_mul_f32_e32 v112, v113, v112
	v_mul_f32_e32 v113, 0xbfb8aa3b, v125
	v_exp_f32_e32 v113, v113
	v_cvt_pk_bf16_f32 v112, v112, s0
	ds_write_b16 v128, v112 offset:6528
	v_add_f32_e32 v113, 1.0, v113
	v_lshlrev_b32_e32 v112, 16, v153
	v_rcp_f32_e32 v114, v113
	s_nop 0
	v_mul_f32_e32 v113, v125, v114
	v_mul_f32_e32 v112, v113, v112
	v_mul_f32_e32 v113, 0xbfb8aa3b, v126
	v_exp_f32_e32 v113, v113
	v_cvt_pk_bf16_f32 v112, v112, s0
	ds_write_b16 v128, v112 offset:6800
	v_add_f32_e32 v113, 1.0, v113
	v_lshlrev_b32_e32 v112, 16, v154
	v_rcp_f32_e32 v114, v113
	s_nop 0
	v_mul_f32_e32 v113, v126, v114
	v_mul_f32_e32 v112, v113, v112
	v_mul_f32_e32 v113, 0xbfb8aa3b, v127
	v_exp_f32_e32 v113, v113
	v_cvt_pk_bf16_f32 v112, v112, s0
	ds_write_b16 v128, v112 offset:7072
	v_add_f32_e32 v113, 1.0, v113
	v_lshlrev_b32_e32 v112, 16, v155
	v_rcp_f32_e32 v114, v113
	s_nop 0
	v_mul_f32_e32 v113, v127, v114
	v_mul_f32_e32 v112, v113, v112
	v_mul_f32_e32 v113, 0xbfb8aa3b, v96
	v_exp_f32_e32 v113, v113
	v_cvt_pk_bf16_f32 v112, v112, s0
	ds_write_b16 v128, v112 offset:7344
	v_add_f32_e32 v113, 1.0, v113
	v_lshlrev_b32_e32 v112, 16, v156
	v_rcp_f32_e32 v114, v113
	s_nop 0
	v_mul_f32_e32 v96, v96, v114
	v_mul_f32_e32 v96, v96, v112
	v_mul_f32_e32 v112, 0xbfb8aa3b, v97
	v_exp_f32_e32 v112, v112
	v_cvt_pk_bf16_f32 v96, v96, s0
	ds_write_b16 v128, v96 offset:64
	v_add_f32_e32 v112, 1.0, v112
	v_lshlrev_b32_e32 v96, 16, v157
	v_rcp_f32_e32 v113, v112
	s_nop 0
	v_mul_f32_e32 v97, v97, v113
	v_mul_f32_e32 v96, v97, v96
	v_mul_f32_e32 v97, 0xbfb8aa3b, v98
	v_exp_f32_e32 v97, v97
	v_cvt_pk_bf16_f32 v96, v96, s0
	ds_write_b16 v128, v96 offset:336
	v_add_f32_e32 v97, 1.0, v97
	v_lshlrev_b32_e32 v96, 16, v158
	v_rcp_f32_e32 v112, v97
	s_nop 0
	v_mul_f32_e32 v97, v98, v112
	v_mul_f32_e32 v96, v97, v96
	v_mul_f32_e32 v97, 0xbfb8aa3b, v99
	v_exp_f32_e32 v97, v97
	v_cvt_pk_bf16_f32 v96, v96, s0
	ds_write_b16 v128, v96 offset:608
	v_add_f32_e32 v97, 1.0, v97
	v_lshlrev_b32_e32 v96, 16, v159
; DEV u16 f2bf(float f) { return (u16)(pk2bf(f, 0.f) & 0xffffu); }
; DEV float bf2f(u16 h) { return __uint_as_float(((unsigned)h) << 16); }
; DEV float siluf_(float x) { return x / (1.0f + __expf(-x)); }
; template <int MI>
; DEV void p4_tile(const Params& p, int l, int m0, int nt, unsigned char* smem) {
;     ...
;     acc_foreach_t<MI>([&](int mi, int ni, int r, int row, int col) __attribute__((always_inline)) {
;       sC[row * LDC + col] = f2bf(bf2f(sC[row * LDC + col]) * siluf_(acc[mi][ni][r]));
	v_rcp_f32_e32 v98, v97
	s_nop 0
	v_mul_f32_e32 v97, v99, v98
	v_mul_f32_e32 v96, v97, v96
	v_mul_f32_e32 v97, 0xbfb8aa3b, v100
	v_exp_f32_e32 v97, v97
	v_cvt_pk_bf16_f32 v96, v96, s0
	ds_write_b16 v128, v96 offset:880
	v_add_f32_e32 v97, 1.0, v97
	v_lshlrev_b32_e32 v96, 16, v160
	v_rcp_f32_e32 v98, v97
	s_nop 0
	v_mul_f32_e32 v97, v100, v98
	v_mul_f32_e32 v96, v97, v96
	v_mul_f32_e32 v97, 0xbfb8aa3b, v101
	v_exp_f32_e32 v97, v97
	v_cvt_pk_bf16_f32 v96, v96, s0
	ds_write_b16 v128, v96 offset:2240
	v_add_f32_e32 v97, 1.0, v97
	v_lshlrev_b32_e32 v96, 16, v161
	v_rcp_f32_e32 v98, v97
	s_nop 0
	v_mul_f32_e32 v97, v101, v98
	v_mul_f32_e32 v96, v97, v96
	v_mul_f32_e32 v97, 0xbfb8aa3b, v102
	v_exp_f32_e32 v97, v97
	v_cvt_pk_bf16_f32 v96, v96, s0
	ds_write_b16 v128, v96 offset:2512
	v_add_f32_e32 v97, 1.0, v97
	v_lshlrev_b32_e32 v96, 16, v162
	v_rcp_f32_e32 v98, v97
	s_nop 0
	v_mul_f32_e32 v97, v102, v98
	v_mul_f32_e32 v96, v97, v96
	v_mul_f32_e32 v97, 0xbfb8aa3b, v103
	v_exp_f32_e32 v97, v97
	v_cvt_pk_bf16_f32 v96, v96, s0
	ds_write_b16 v128, v96 offset:2784
	v_add_f32_e32 v97, 1.0, v97
	v_lshlrev_b32_e32 v96, 16, v163
	v_rcp_f32_e32 v98, v97
	s_nop 0
	v_mul_f32_e32 v97, v103, v98
	v_mul_f32_e32 v96, v97, v96
	v_mul_f32_e32 v97, 0xbfb8aa3b, v104
	v_exp_f32_e32 v97, v97
	v_cvt_pk_bf16_f32 v96, v96, s0
	ds_write_b16 v128, v96 offset:3056
	v_add_f32_e32 v97, 1.0, v97
	v_lshlrev_b32_e32 v96, 16, v164
	v_rcp_f32_e32 v98, v97
	s_nop 0
	v_mul_f32_e32 v97, v104, v98
	v_mul_f32_e32 v96, v97, v96
	v_mul_f32_e32 v97, 0xbfb8aa3b, v105
	v_exp_f32_e32 v97, v97
	v_cvt_pk_bf16_f32 v96, v96, s0
	ds_write_b16 v128, v96 offset:4416
	v_add_f32_e32 v97, 1.0, v97
	v_lshlrev_b32_e32 v96, 16, v165
	v_rcp_f32_e32 v98, v97
	s_nop 0
	v_mul_f32_e32 v97, v105, v98
	v_mul_f32_e32 v96, v97, v96
	v_mul_f32_e32 v97, 0xbfb8aa3b, v106
	v_exp_f32_e32 v97, v97
	v_cvt_pk_bf16_f32 v96, v96, s0
	ds_write_b16 v128, v96 offset:4688
	v_add_f32_e32 v97, 1.0, v97
	v_lshlrev_b32_e32 v96, 16, v166
	v_rcp_f32_e32 v98, v97
	s_nop 0
	v_mul_f32_e32 v97, v106, v98
	v_mul_f32_e32 v96, v97, v96
	v_mul_f32_e32 v97, 0xbfb8aa3b, v107
	v_exp_f32_e32 v97, v97
	v_cvt_pk_bf16_f32 v96, v96, s0
	ds_write_b16 v128, v96 offset:4960
	v_add_f32_e32 v97, 1.0, v97
	v_lshlrev_b32_e32 v96, 16, v167
	v_rcp_f32_e32 v98, v97
	s_nop 0
	v_mul_f32_e32 v97, v107, v98
	v_mul_f32_e32 v96, v97, v96
	v_mul_f32_e32 v97, 0xbfb8aa3b, v108
	v_exp_f32_e32 v97, v97
	v_cvt_pk_bf16_f32 v96, v96, s0
	ds_write_b16 v128, v96 offset:5232
	v_add_f32_e32 v97, 1.0, v97
	v_lshlrev_b32_e32 v96, 16, v168
	v_rcp_f32_e32 v98, v97
	s_nop 0
	v_mul_f32_e32 v97, v108, v98
	v_mul_f32_e32 v96, v97, v96
	v_mul_f32_e32 v97, 0xbfb8aa3b, v109
	v_exp_f32_e32 v97, v97
	v_cvt_pk_bf16_f32 v96, v96, s0
	ds_write_b16 v128, v96 offset:6592
	v_add_f32_e32 v97, 1.0, v97
	v_lshlrev_b32_e32 v96, 16, v169
	v_rcp_f32_e32 v98, v97
	s_nop 0
	v_mul_f32_e32 v97, v109, v98
	v_mul_f32_e32 v96, v97, v96
	v_mul_f32_e32 v97, 0xbfb8aa3b, v110
	v_exp_f32_e32 v97, v97
	v_cvt_pk_bf16_f32 v96, v96, s0
	ds_write_b16 v128, v96 offset:6864
	v_add_f32_e32 v97, 1.0, v97
	v_lshlrev_b32_e32 v96, 16, v170
	v_rcp_f32_e32 v98, v97
	s_nop 0
	v_mul_f32_e32 v97, v110, v98
	v_mul_f32_e32 v96, v97, v96
	v_mul_f32_e32 v97, 0xbfb8aa3b, v111
	v_exp_f32_e32 v97, v97
	v_cvt_pk_bf16_f32 v96, v96, s0
	ds_write_b16 v128, v96 offset:7136
	v_add_f32_e32 v97, 1.0, v97
	v_lshlrev_b32_e32 v96, 16, v171
	v_rcp_f32_e32 v98, v97
	s_nop 0
	v_mul_f32_e32 v97, v111, v98
	v_mul_f32_e32 v96, v97, v96
	v_mul_f32_e32 v97, 0xbfb8aa3b, v80
	v_exp_f32_e32 v97, v97
	v_cvt_pk_bf16_f32 v96, v96, s0
	ds_write_b16 v128, v96 offset:7408
	v_add_f32_e32 v97, 1.0, v97
	v_lshlrev_b32_e32 v96, 16, v172
	v_rcp_f32_e32 v98, v97
	s_nop 0
	v_mul_f32_e32 v80, v80, v98
	v_mul_f32_e32 v80, v80, v96
	v_mul_f32_e32 v96, 0xbfb8aa3b, v81
	v_exp_f32_e32 v96, v96
	v_cvt_pk_bf16_f32 v80, v80, s0
	ds_write_b16 v128, v80 offset:8704
	v_add_f32_e32 v96, 1.0, v96
	v_lshlrev_b32_e32 v80, 16, v173
	v_rcp_f32_e32 v97, v96
	s_nop 0
	v_mul_f32_e32 v81, v81, v97
	v_mul_f32_e32 v80, v81, v80
	v_mul_f32_e32 v81, 0xbfb8aa3b, v82
	v_exp_f32_e32 v81, v81
	v_cvt_pk_bf16_f32 v80, v80, s0
	ds_write_b16 v128, v80 offset:8976
	v_add_f32_e32 v81, 1.0, v81
	v_lshlrev_b32_e32 v80, 16, v174
	v_rcp_f32_e32 v96, v81
	s_nop 0
	v_mul_f32_e32 v81, v82, v96
	v_mul_f32_e32 v80, v81, v80
	v_mul_f32_e32 v81, 0xbfb8aa3b, v83
	v_exp_f32_e32 v81, v81
	v_cvt_pk_bf16_f32 v80, v80, s0
	ds_write_b16 v128, v80 offset:9248
	v_add_f32_e32 v81, 1.0, v81
	v_lshlrev_b32_e32 v80, 16, v175
	v_rcp_f32_e32 v82, v81
	s_nop 0
	v_mul_f32_e32 v81, v83, v82
	v_mul_f32_e32 v80, v81, v80
	v_mul_f32_e32 v81, 0xbfb8aa3b, v84
	v_exp_f32_e32 v81, v81
	v_cvt_pk_bf16_f32 v80, v80, s0
	ds_write_b16 v128, v80 offset:9520
	v_add_f32_e32 v81, 1.0, v81
	v_lshlrev_b32_e32 v80, 16, v176
	v_rcp_f32_e32 v82, v81
	s_nop 0
	v_mul_f32_e32 v81, v84, v82
	v_mul_f32_e32 v80, v81, v80
	v_mul_f32_e32 v81, 0xbfb8aa3b, v85
	v_exp_f32_e32 v81, v81
	v_cvt_pk_bf16_f32 v80, v80, s0
	ds_write_b16 v128, v80 offset:10880
	v_add_f32_e32 v81, 1.0, v81
	v_lshlrev_b32_e32 v80, 16, v177
	v_rcp_f32_e32 v82, v81
	s_nop 0
	v_mul_f32_e32 v81, v85, v82
	v_mul_f32_e32 v80, v81, v80
	v_mul_f32_e32 v81, 0xbfb8aa3b, v86
	v_exp_f32_e32 v81, v81
	v_cvt_pk_bf16_f32 v80, v80, s0
	ds_write_b16 v128, v80 offset:11152
	v_add_f32_e32 v81, 1.0, v81
	v_lshlrev_b32_e32 v80, 16, v178
	v_rcp_f32_e32 v82, v81
	s_nop 0
	v_mul_f32_e32 v81, v86, v82
	v_mul_f32_e32 v80, v81, v80
	v_mul_f32_e32 v81, 0xbfb8aa3b, v87
	v_exp_f32_e32 v81, v81
	v_cvt_pk_bf16_f32 v80, v80, s0
	ds_write_b16 v128, v80 offset:11424
	v_add_f32_e32 v81, 1.0, v81
	v_lshlrev_b32_e32 v80, 16, v179
; DEV u16 f2bf(float f) { return (u16)(pk2bf(f, 0.f) & 0xffffu); }
; DEV float bf2f(u16 h) { return __uint_as_float(((unsigned)h) << 16); }
; DEV float siluf_(float x) { return x / (1.0f + __expf(-x)); }
; template <int MI>
; DEV void p4_tile(const Params& p, int l, int m0, int nt, unsigned char* smem) {
;     ...
;     acc_foreach_t<MI>([&](int mi, int ni, int r, int row, int col) __attribute__((always_inline)) {
;       sC[row * LDC + col] = f2bf(bf2f(sC[row * LDC + col]) * siluf_(acc[mi][ni][r]));
	v_rcp_f32_e32 v82, v81
	s_nop 0
	v_mul_f32_e32 v81, v87, v82
	v_mul_f32_e32 v80, v81, v80
	v_mul_f32_e32 v81, 0xbfb8aa3b, v88
	v_exp_f32_e32 v81, v81
	v_cvt_pk_bf16_f32 v80, v80, s0
	ds_write_b16 v128, v80 offset:11696
	v_add_f32_e32 v81, 1.0, v81
	v_lshlrev_b32_e32 v80, 16, v180
	v_rcp_f32_e32 v82, v81
	s_nop 0
	v_mul_f32_e32 v81, v88, v82
	v_mul_f32_e32 v80, v81, v80
	v_mul_f32_e32 v81, 0xbfb8aa3b, v89
	v_exp_f32_e32 v81, v81
	v_cvt_pk_bf16_f32 v80, v80, s0
	ds_write_b16 v128, v80 offset:13056
	v_add_f32_e32 v81, 1.0, v81
	v_lshlrev_b32_e32 v80, 16, v181
	v_rcp_f32_e32 v82, v81
	s_nop 0
	v_mul_f32_e32 v81, v89, v82
	v_mul_f32_e32 v80, v81, v80
	v_mul_f32_e32 v81, 0xbfb8aa3b, v90
	v_exp_f32_e32 v81, v81
	v_cvt_pk_bf16_f32 v80, v80, s0
	ds_write_b16 v128, v80 offset:13328
	v_add_f32_e32 v81, 1.0, v81
	v_lshlrev_b32_e32 v80, 16, v182
	v_rcp_f32_e32 v82, v81
	s_nop 0
	v_mul_f32_e32 v81, v90, v82
	v_mul_f32_e32 v80, v81, v80
	v_mul_f32_e32 v81, 0xbfb8aa3b, v91
	v_exp_f32_e32 v81, v81
	v_cvt_pk_bf16_f32 v80, v80, s0
	ds_write_b16 v128, v80 offset:13600
	v_add_f32_e32 v81, 1.0, v81
	v_lshlrev_b32_e32 v80, 16, v183
	v_rcp_f32_e32 v82, v81
	s_nop 0
	v_mul_f32_e32 v81, v91, v82
	v_mul_f32_e32 v80, v81, v80
	v_mul_f32_e32 v81, 0xbfb8aa3b, v92
	v_exp_f32_e32 v81, v81
	v_cvt_pk_bf16_f32 v80, v80, s0
	ds_write_b16 v128, v80 offset:13872
	v_add_f32_e32 v81, 1.0, v81
	v_lshlrev_b32_e32 v80, 16, v184
	v_rcp_f32_e32 v82, v81
	s_nop 0
	v_mul_f32_e32 v81, v92, v82
	v_mul_f32_e32 v80, v81, v80
	v_mul_f32_e32 v81, 0xbfb8aa3b, v93
	v_exp_f32_e32 v81, v81
	v_cvt_pk_bf16_f32 v80, v80, s0
	ds_write_b16 v128, v80 offset:15232
	v_add_f32_e32 v81, 1.0, v81
	v_lshlrev_b32_e32 v80, 16, v185
	v_rcp_f32_e32 v82, v81
	s_nop 0
	v_mul_f32_e32 v81, v93, v82
	v_mul_f32_e32 v80, v81, v80
	v_mul_f32_e32 v81, 0xbfb8aa3b, v94
	v_exp_f32_e32 v81, v81
	v_cvt_pk_bf16_f32 v80, v80, s0
	ds_write_b16 v128, v80 offset:15504
	v_add_f32_e32 v81, 1.0, v81
	v_lshlrev_b32_e32 v80, 16, v186
	v_rcp_f32_e32 v82, v81
	s_nop 0
	v_mul_f32_e32 v81, v94, v82
	v_mul_f32_e32 v80, v81, v80
	v_mul_f32_e32 v81, 0xbfb8aa3b, v95
	v_exp_f32_e32 v81, v81
	v_cvt_pk_bf16_f32 v80, v80, s0
	ds_write_b16 v128, v80 offset:15776
	v_add_f32_e32 v81, 1.0, v81
	v_lshlrev_b32_e32 v80, 16, v187
	v_rcp_f32_e32 v82, v81
	s_nop 0
	v_mul_f32_e32 v81, v95, v82
	v_mul_f32_e32 v80, v81, v80
	v_mul_f32_e32 v81, 0xbfb8aa3b, v64
	v_exp_f32_e32 v81, v81
	v_cvt_pk_bf16_f32 v80, v80, s0
	ds_write_b16 v128, v80 offset:16048
	v_add_f32_e32 v81, 1.0, v81
	v_lshlrev_b32_e32 v80, 16, v188
	v_rcp_f32_e32 v82, v81
	s_nop 0
	v_mul_f32_e32 v64, v64, v82
	v_mul_f32_e32 v64, v64, v80
	v_mul_f32_e32 v80, 0xbfb8aa3b, v65
	v_exp_f32_e32 v80, v80
	v_cvt_pk_bf16_f32 v64, v64, s0
	ds_write_b16 v128, v64 offset:8768
	v_add_f32_e32 v80, 1.0, v80
	v_lshlrev_b32_e32 v64, 16, v189
	v_rcp_f32_e32 v81, v80
	s_nop 0
	v_mul_f32_e32 v65, v65, v81
	v_mul_f32_e32 v64, v65, v64
	v_mul_f32_e32 v65, 0xbfb8aa3b, v66
	v_exp_f32_e32 v65, v65
	v_cvt_pk_bf16_f32 v64, v64, s0
	ds_write_b16 v128, v64 offset:9040
	v_add_f32_e32 v65, 1.0, v65
	v_lshlrev_b32_e32 v64, 16, v190
	v_rcp_f32_e32 v80, v65
	s_nop 0
	v_mul_f32_e32 v65, v66, v80
	v_mul_f32_e32 v64, v65, v64
	v_mul_f32_e32 v65, 0xbfb8aa3b, v67
	v_exp_f32_e32 v65, v65
	v_cvt_pk_bf16_f32 v64, v64, s0
	ds_write_b16 v128, v64 offset:9312
	v_add_f32_e32 v65, 1.0, v65
	v_lshlrev_b32_e32 v64, 16, v191
	v_rcp_f32_e32 v66, v65
	s_nop 0
	v_mul_f32_e32 v65, v67, v66
	v_mul_f32_e32 v64, v65, v64
	v_mul_f32_e32 v65, 0xbfb8aa3b, v68
	v_exp_f32_e32 v65, v65
	v_cvt_pk_bf16_f32 v64, v64, s0
	ds_write_b16 v128, v64 offset:9584
	v_add_f32_e32 v65, 1.0, v65
	v_lshlrev_b32_e32 v64, 16, v192
	v_rcp_f32_e32 v66, v65
	s_nop 0
	v_mul_f32_e32 v65, v68, v66
	v_mul_f32_e32 v64, v65, v64
	v_mul_f32_e32 v65, 0xbfb8aa3b, v69
	v_exp_f32_e32 v65, v65
	v_cvt_pk_bf16_f32 v64, v64, s0
	ds_write_b16 v128, v64 offset:10944
	v_add_f32_e32 v65, 1.0, v65
	v_lshlrev_b32_e32 v64, 16, v193
	v_rcp_f32_e32 v66, v65
	s_nop 0
	v_mul_f32_e32 v65, v69, v66
	v_mul_f32_e32 v64, v65, v64
	v_mul_f32_e32 v65, 0xbfb8aa3b, v70
	v_exp_f32_e32 v65, v65
	v_cvt_pk_bf16_f32 v64, v64, s0
	ds_write_b16 v128, v64 offset:11216
	v_add_f32_e32 v65, 1.0, v65
	v_lshlrev_b32_e32 v64, 16, v194
	v_rcp_f32_e32 v66, v65
	s_nop 0
	v_mul_f32_e32 v65, v70, v66
	v_mul_f32_e32 v64, v65, v64
	v_mul_f32_e32 v65, 0xbfb8aa3b, v71
	v_exp_f32_e32 v65, v65
	v_cvt_pk_bf16_f32 v64, v64, s0
	ds_write_b16 v128, v64 offset:11488
	v_add_f32_e32 v65, 1.0, v65
	v_lshlrev_b32_e32 v64, 16, v195
	v_rcp_f32_e32 v66, v65
	s_nop 0
	v_mul_f32_e32 v65, v71, v66
	v_mul_f32_e32 v64, v65, v64
	v_mul_f32_e32 v65, 0xbfb8aa3b, v72
	v_exp_f32_e32 v65, v65
	v_cvt_pk_bf16_f32 v64, v64, s0
	ds_write_b16 v128, v64 offset:11760
	v_add_f32_e32 v65, 1.0, v65
	v_lshlrev_b32_e32 v64, 16, v196
	v_rcp_f32_e32 v66, v65
	s_nop 0
	v_mul_f32_e32 v65, v72, v66
	v_mul_f32_e32 v64, v65, v64
	v_mul_f32_e32 v65, 0xbfb8aa3b, v73
	v_exp_f32_e32 v65, v65
	v_cvt_pk_bf16_f32 v64, v64, s0
	ds_write_b16 v128, v64 offset:13120
	v_add_f32_e32 v65, 1.0, v65
	v_lshlrev_b32_e32 v64, 16, v197
	v_rcp_f32_e32 v66, v65
	s_nop 0
	v_mul_f32_e32 v65, v73, v66
	v_mul_f32_e32 v64, v65, v64
	v_mul_f32_e32 v65, 0xbfb8aa3b, v74
	v_exp_f32_e32 v65, v65
	v_cvt_pk_bf16_f32 v64, v64, s0
	ds_write_b16 v128, v64 offset:13392
	v_add_f32_e32 v65, 1.0, v65
	v_lshlrev_b32_e32 v64, 16, v198
	v_rcp_f32_e32 v66, v65
	s_nop 0
	v_mul_f32_e32 v65, v74, v66
	v_mul_f32_e32 v64, v65, v64
	v_mul_f32_e32 v65, 0xbfb8aa3b, v75
	v_exp_f32_e32 v65, v65
	v_cvt_pk_bf16_f32 v64, v64, s0
	ds_write_b16 v128, v64 offset:13664
	v_add_f32_e32 v65, 1.0, v65
	v_lshlrev_b32_e32 v64, 16, v199
; DEV u16 f2bf(float f) { return (u16)(pk2bf(f, 0.f) & 0xffffu); }
; DEV float bf2f(u16 h) { return __uint_as_float(((unsigned)h) << 16); }
; DEV float siluf_(float x) { return x / (1.0f + __expf(-x)); }
; template <int MI>
; DEV void p4_tile(const Params& p, int l, int m0, int nt, unsigned char* smem) {
;     ...
;     acc_foreach_t<MI>([&](int mi, int ni, int r, int row, int col) __attribute__((always_inline)) {
;       sC[row * LDC + col] = f2bf(bf2f(sC[row * LDC + col]) * siluf_(acc[mi][ni][r]));
	v_rcp_f32_e32 v66, v65
	s_nop 0
	v_mul_f32_e32 v65, v75, v66
	v_mul_f32_e32 v64, v65, v64
	v_mul_f32_e32 v65, 0xbfb8aa3b, v76
	v_exp_f32_e32 v65, v65
	v_cvt_pk_bf16_f32 v64, v64, s0
	ds_write_b16 v128, v64 offset:13936
	v_add_f32_e32 v65, 1.0, v65
	v_lshlrev_b32_e32 v64, 16, v200
	v_rcp_f32_e32 v66, v65
	s_nop 0
	v_mul_f32_e32 v65, v76, v66
	v_mul_f32_e32 v64, v65, v64
	v_mul_f32_e32 v65, 0xbfb8aa3b, v77
	v_exp_f32_e32 v65, v65
	v_cvt_pk_bf16_f32 v64, v64, s0
	ds_write_b16 v128, v64 offset:15296
	v_add_f32_e32 v65, 1.0, v65
	v_lshlrev_b32_e32 v64, 16, v201
	v_rcp_f32_e32 v66, v65
	s_nop 0
	v_mul_f32_e32 v65, v77, v66
	v_mul_f32_e32 v64, v65, v64
	v_mul_f32_e32 v65, 0xbfb8aa3b, v78
	v_exp_f32_e32 v65, v65
	v_cvt_pk_bf16_f32 v64, v64, s0
	ds_write_b16 v128, v64 offset:15568
	v_add_f32_e32 v65, 1.0, v65
	v_lshlrev_b32_e32 v64, 16, v202
	v_rcp_f32_e32 v66, v65
	s_nop 0
	v_mul_f32_e32 v65, v78, v66
	v_mul_f32_e32 v64, v65, v64
	v_mul_f32_e32 v65, 0xbfb8aa3b, v79
	v_exp_f32_e32 v65, v65
	v_cvt_pk_bf16_f32 v64, v64, s0
	ds_write_b16 v128, v64 offset:15840
	v_add_f32_e32 v65, 1.0, v65
	v_lshlrev_b32_e32 v64, 16, v203
	v_rcp_f32_e32 v66, v65
	s_nop 0
	v_mul_f32_e32 v65, v79, v66
	v_mul_f32_e32 v64, v65, v64
	v_mul_f32_e32 v65, 0xbfb8aa3b, v48
	v_exp_f32_e32 v65, v65
	v_cvt_pk_bf16_f32 v64, v64, s0
	ds_write_b16 v128, v64 offset:16112
	ds_read_u16 v140, v128 offset:17408
	ds_read_u16 v141, v128 offset:17680
	ds_read_u16 v142, v128 offset:17952
	ds_read_u16 v143, v128 offset:18224
	ds_read_u16 v144, v128 offset:19584
	ds_read_u16 v145, v128 offset:19856
	ds_read_u16 v146, v128 offset:20128
	ds_read_u16 v147, v128 offset:20400
	ds_read_u16 v148, v128 offset:21760
	ds_read_u16 v149, v128 offset:22032
	ds_read_u16 v150, v128 offset:22304
	ds_read_u16 v151, v128 offset:22576
	ds_read_u16 v152, v128 offset:23936
	ds_read_u16 v153, v128 offset:24208
	ds_read_u16 v154, v128 offset:24480
	ds_read_u16 v155, v128 offset:24752
	ds_read_u16 v156, v128 offset:17472
	ds_read_u16 v157, v128 offset:17744
	ds_read_u16 v158, v128 offset:18016
	ds_read_u16 v159, v128 offset:18288
	ds_read_u16 v160, v128 offset:19648
	ds_read_u16 v161, v128 offset:19920
	ds_read_u16 v162, v128 offset:20192
	ds_read_u16 v163, v128 offset:20464
	ds_read_u16 v164, v128 offset:21824
	ds_read_u16 v165, v128 offset:22096
	ds_read_u16 v166, v128 offset:22368
	ds_read_u16 v167, v128 offset:22640
	ds_read_u16 v168, v128 offset:24000
	ds_read_u16 v169, v128 offset:24272
	ds_read_u16 v170, v128 offset:24544
	ds_read_u16 v171, v128 offset:24816
	ds_read_u16 v172, v128 offset:26112
	ds_read_u16 v173, v128 offset:26384
	ds_read_u16 v174, v128 offset:26656
	ds_read_u16 v175, v128 offset:26928
	ds_read_u16 v176, v128 offset:28288
	ds_read_u16 v177, v128 offset:28560
	ds_read_u16 v178, v128 offset:28832
	ds_read_u16 v179, v128 offset:29104
	ds_read_u16 v180, v128 offset:30464
	ds_read_u16 v181, v128 offset:30736
	ds_read_u16 v182, v128 offset:31008
	ds_read_u16 v183, v128 offset:31280
	ds_read_u16 v184, v128 offset:32640
	ds_read_u16 v185, v128 offset:32912
	ds_read_u16 v186, v128 offset:33184
	ds_read_u16 v187, v128 offset:33456
	ds_read_u16 v188, v128 offset:26176
	ds_read_u16 v189, v128 offset:26448
	ds_read_u16 v190, v128 offset:26720
	ds_read_u16 v191, v128 offset:26992
	ds_read_u16 v192, v128 offset:28352
	ds_read_u16 v193, v128 offset:28624
	ds_read_u16 v194, v128 offset:28896
	ds_read_u16 v195, v128 offset:29168
	ds_read_u16 v196, v128 offset:30528
	ds_read_u16 v197, v128 offset:30800
	ds_read_u16 v198, v128 offset:31072
	ds_read_u16 v199, v128 offset:31344
	ds_read_u16 v200, v128 offset:32704
	ds_read_u16 v201, v128 offset:32976
	ds_read_u16 v202, v128 offset:33248
	ds_read_u16 v203, v128 offset:33520
	s_waitcnt lgkmcnt(0)
	v_add_f32_e32 v65, 1.0, v65
	v_lshlrev_b32_e32 v64, 16, v140
	v_rcp_f32_e32 v66, v65
	s_nop 0
	v_mul_f32_e32 v48, v48, v66
	v_mul_f32_e32 v48, v48, v64
	v_mul_f32_e32 v64, 0xbfb8aa3b, v49
	v_exp_f32_e32 v64, v64
	v_cvt_pk_bf16_f32 v48, v48, s0
	ds_write_b16 v128, v48 offset:17408
	v_add_f32_e32 v64, 1.0, v64
	v_lshlrev_b32_e32 v48, 16, v141
	v_rcp_f32_e32 v65, v64
	s_nop 0
	v_mul_f32_e32 v49, v49, v65
	v_mul_f32_e32 v48, v49, v48
	v_mul_f32_e32 v49, 0xbfb8aa3b, v50
	v_exp_f32_e32 v49, v49
	v_cvt_pk_bf16_f32 v48, v48, s0
	ds_write_b16 v128, v48 offset:17680
	v_add_f32_e32 v49, 1.0, v49
	v_lshlrev_b32_e32 v48, 16, v142
	v_rcp_f32_e32 v64, v49
	s_nop 0
	v_mul_f32_e32 v49, v50, v64
	v_mul_f32_e32 v48, v49, v48
	v_mul_f32_e32 v49, 0xbfb8aa3b, v51
	v_exp_f32_e32 v49, v49
	v_cvt_pk_bf16_f32 v48, v48, s0
	ds_write_b16 v128, v48 offset:17952
	v_add_f32_e32 v49, 1.0, v49
	v_lshlrev_b32_e32 v48, 16, v143
	v_rcp_f32_e32 v50, v49
	s_nop 0
	v_mul_f32_e32 v49, v51, v50
	v_mul_f32_e32 v48, v49, v48
	v_mul_f32_e32 v49, 0xbfb8aa3b, v52
	v_exp_f32_e32 v49, v49
	v_cvt_pk_bf16_f32 v48, v48, s0
	ds_write_b16 v128, v48 offset:18224
	v_add_f32_e32 v49, 1.0, v49
	v_lshlrev_b32_e32 v48, 16, v144
	v_rcp_f32_e32 v50, v49
	s_nop 0
	v_mul_f32_e32 v49, v52, v50
	v_mul_f32_e32 v48, v49, v48
	v_mul_f32_e32 v49, 0xbfb8aa3b, v53
	v_exp_f32_e32 v49, v49
	v_cvt_pk_bf16_f32 v48, v48, s0
	ds_write_b16 v128, v48 offset:19584
	v_add_f32_e32 v49, 1.0, v49
	v_lshlrev_b32_e32 v48, 16, v145
	v_rcp_f32_e32 v50, v49
	s_nop 0
	v_mul_f32_e32 v49, v53, v50
	v_mul_f32_e32 v48, v49, v48
	v_mul_f32_e32 v49, 0xbfb8aa3b, v54
	v_exp_f32_e32 v49, v49
	v_cvt_pk_bf16_f32 v48, v48, s0
	ds_write_b16 v128, v48 offset:19856
	v_add_f32_e32 v49, 1.0, v49
	v_lshlrev_b32_e32 v48, 16, v146
	v_rcp_f32_e32 v50, v49
	s_nop 0
	v_mul_f32_e32 v49, v54, v50
	v_mul_f32_e32 v48, v49, v48
	v_mul_f32_e32 v49, 0xbfb8aa3b, v55
	v_exp_f32_e32 v49, v49
; DEV u16 f2bf(float f) { return (u16)(pk2bf(f, 0.f) & 0xffffu); }
; DEV float bf2f(u16 h) { return __uint_as_float(((unsigned)h) << 16); }
; DEV float siluf_(float x) { return x / (1.0f + __expf(-x)); }
; template <int MI>
; DEV void p4_tile(const Params& p, int l, int m0, int nt, unsigned char* smem) {
;     ...
;     acc_foreach_t<MI>([&](int mi, int ni, int r, int row, int col) __attribute__((always_inline)) {
;       sC[row * LDC + col] = f2bf(bf2f(sC[row * LDC + col]) * siluf_(acc[mi][ni][r]));
	v_cvt_pk_bf16_f32 v48, v48, s0
	ds_write_b16 v128, v48 offset:20128
	v_add_f32_e32 v49, 1.0, v49
	v_lshlrev_b32_e32 v48, 16, v147
	v_rcp_f32_e32 v50, v49
	s_nop 0
	v_mul_f32_e32 v49, v55, v50
	v_mul_f32_e32 v48, v49, v48
	v_mul_f32_e32 v49, 0xbfb8aa3b, v56
	v_exp_f32_e32 v49, v49
	v_cvt_pk_bf16_f32 v48, v48, s0
	ds_write_b16 v128, v48 offset:20400
	v_add_f32_e32 v49, 1.0, v49
	v_lshlrev_b32_e32 v48, 16, v148
	v_rcp_f32_e32 v50, v49
	s_nop 0
	v_mul_f32_e32 v49, v56, v50
	v_mul_f32_e32 v48, v49, v48
	v_mul_f32_e32 v49, 0xbfb8aa3b, v57
	v_exp_f32_e32 v49, v49
	v_cvt_pk_bf16_f32 v48, v48, s0
	ds_write_b16 v128, v48 offset:21760
	v_add_f32_e32 v49, 1.0, v49
	v_lshlrev_b32_e32 v48, 16, v149
	v_rcp_f32_e32 v50, v49
	s_nop 0
	v_mul_f32_e32 v49, v57, v50
	v_mul_f32_e32 v48, v49, v48
	v_mul_f32_e32 v49, 0xbfb8aa3b, v58
	v_exp_f32_e32 v49, v49
	v_cvt_pk_bf16_f32 v48, v48, s0
	ds_write_b16 v128, v48 offset:22032
	v_add_f32_e32 v49, 1.0, v49
	v_lshlrev_b32_e32 v48, 16, v150
	v_rcp_f32_e32 v50, v49
	s_nop 0
	v_mul_f32_e32 v49, v58, v50
	v_mul_f32_e32 v48, v49, v48
	v_mul_f32_e32 v49, 0xbfb8aa3b, v59
	v_exp_f32_e32 v49, v49
	v_cvt_pk_bf16_f32 v48, v48, s0
	ds_write_b16 v128, v48 offset:22304
	v_add_f32_e32 v49, 1.0, v49
	v_lshlrev_b32_e32 v48, 16, v151
	v_rcp_f32_e32 v50, v49
	s_nop 0
	v_mul_f32_e32 v49, v59, v50
	v_mul_f32_e32 v48, v49, v48
	v_mul_f32_e32 v49, 0xbfb8aa3b, v60
	v_exp_f32_e32 v49, v49
	v_cvt_pk_bf16_f32 v48, v48, s0
	ds_write_b16 v128, v48 offset:22576
	v_add_f32_e32 v49, 1.0, v49
	v_lshlrev_b32_e32 v48, 16, v152
	v_rcp_f32_e32 v50, v49
	s_nop 0
	v_mul_f32_e32 v49, v60, v50
	v_mul_f32_e32 v48, v49, v48
	v_mul_f32_e32 v49, 0xbfb8aa3b, v61
	v_exp_f32_e32 v49, v49
	v_cvt_pk_bf16_f32 v48, v48, s0
	ds_write_b16 v128, v48 offset:23936
	v_add_f32_e32 v49, 1.0, v49
	v_lshlrev_b32_e32 v48, 16, v153
	v_rcp_f32_e32 v50, v49
	s_nop 0
	v_mul_f32_e32 v49, v61, v50
	v_mul_f32_e32 v48, v49, v48
	v_mul_f32_e32 v49, 0xbfb8aa3b, v62
	v_exp_f32_e32 v49, v49
	v_cvt_pk_bf16_f32 v48, v48, s0
	ds_write_b16 v128, v48 offset:24208
	v_add_f32_e32 v49, 1.0, v49
	v_lshlrev_b32_e32 v48, 16, v154
	v_rcp_f32_e32 v50, v49
	s_nop 0
	v_mul_f32_e32 v49, v62, v50
	v_mul_f32_e32 v48, v49, v48
	v_mul_f32_e32 v49, 0xbfb8aa3b, v63
	v_exp_f32_e32 v49, v49
	v_cvt_pk_bf16_f32 v48, v48, s0
	ds_write_b16 v128, v48 offset:24480
	v_add_f32_e32 v49, 1.0, v49
	v_lshlrev_b32_e32 v48, 16, v155
	v_rcp_f32_e32 v50, v49
	s_nop 0
	v_mul_f32_e32 v49, v63, v50
	v_mul_f32_e32 v48, v49, v48
	v_mul_f32_e32 v49, 0xbfb8aa3b, v32
	v_exp_f32_e32 v49, v49
	v_cvt_pk_bf16_f32 v48, v48, s0
	ds_write_b16 v128, v48 offset:24752
	v_add_f32_e32 v49, 1.0, v49
	v_lshlrev_b32_e32 v48, 16, v156
	v_rcp_f32_e32 v50, v49
	s_nop 0
	v_mul_f32_e32 v32, v32, v50
	v_mul_f32_e32 v32, v32, v48
	v_mul_f32_e32 v48, 0xbfb8aa3b, v33
	v_exp_f32_e32 v48, v48
	v_cvt_pk_bf16_f32 v32, v32, s0
	ds_write_b16 v128, v32 offset:17472
	v_add_f32_e32 v48, 1.0, v48
	v_lshlrev_b32_e32 v32, 16, v157
	v_rcp_f32_e32 v49, v48
	s_nop 0
	v_mul_f32_e32 v33, v33, v49
	v_mul_f32_e32 v32, v33, v32
	v_mul_f32_e32 v33, 0xbfb8aa3b, v34
	v_exp_f32_e32 v33, v33
	v_cvt_pk_bf16_f32 v32, v32, s0
	ds_write_b16 v128, v32 offset:17744
	v_add_f32_e32 v33, 1.0, v33
	v_lshlrev_b32_e32 v32, 16, v158
	v_rcp_f32_e32 v48, v33
	s_nop 0
	v_mul_f32_e32 v33, v34, v48
	v_mul_f32_e32 v32, v33, v32
	v_mul_f32_e32 v33, 0xbfb8aa3b, v35
	v_exp_f32_e32 v33, v33
	v_cvt_pk_bf16_f32 v32, v32, s0
	ds_write_b16 v128, v32 offset:18016
	v_add_f32_e32 v33, 1.0, v33
	v_lshlrev_b32_e32 v32, 16, v159
	v_rcp_f32_e32 v34, v33
	s_nop 0
	v_mul_f32_e32 v33, v35, v34
	v_mul_f32_e32 v32, v33, v32
	v_mul_f32_e32 v33, 0xbfb8aa3b, v36
	v_exp_f32_e32 v33, v33
	v_cvt_pk_bf16_f32 v32, v32, s0
	ds_write_b16 v128, v32 offset:18288
	v_add_f32_e32 v33, 1.0, v33
	v_lshlrev_b32_e32 v32, 16, v160
	v_rcp_f32_e32 v34, v33
	s_nop 0
	v_mul_f32_e32 v33, v36, v34
	v_mul_f32_e32 v32, v33, v32
	v_mul_f32_e32 v33, 0xbfb8aa3b, v37
	v_exp_f32_e32 v33, v33
	v_cvt_pk_bf16_f32 v32, v32, s0
	ds_write_b16 v128, v32 offset:19648
	v_add_f32_e32 v33, 1.0, v33
	v_lshlrev_b32_e32 v32, 16, v161
	v_rcp_f32_e32 v34, v33
	s_nop 0
	v_mul_f32_e32 v33, v37, v34
	v_mul_f32_e32 v32, v33, v32
	v_mul_f32_e32 v33, 0xbfb8aa3b, v38
	v_exp_f32_e32 v33, v33
	v_cvt_pk_bf16_f32 v32, v32, s0
	ds_write_b16 v128, v32 offset:19920
	v_add_f32_e32 v33, 1.0, v33
	v_lshlrev_b32_e32 v32, 16, v162
	v_rcp_f32_e32 v34, v33
	s_nop 0
	v_mul_f32_e32 v33, v38, v34
	v_mul_f32_e32 v32, v33, v32
	v_mul_f32_e32 v33, 0xbfb8aa3b, v39
	v_exp_f32_e32 v33, v33
	v_cvt_pk_bf16_f32 v32, v32, s0
	ds_write_b16 v128, v32 offset:20192
	v_add_f32_e32 v33, 1.0, v33
	v_lshlrev_b32_e32 v32, 16, v163
	v_rcp_f32_e32 v34, v33
	s_nop 0
	v_mul_f32_e32 v33, v39, v34
	v_mul_f32_e32 v32, v33, v32
	v_mul_f32_e32 v33, 0xbfb8aa3b, v40
	v_exp_f32_e32 v33, v33
	v_cvt_pk_bf16_f32 v32, v32, s0
	ds_write_b16 v128, v32 offset:20464
	v_add_f32_e32 v33, 1.0, v33
	v_lshlrev_b32_e32 v32, 16, v164
	v_rcp_f32_e32 v34, v33
	s_nop 0
	v_mul_f32_e32 v33, v40, v34
	v_mul_f32_e32 v32, v33, v32
	v_mul_f32_e32 v33, 0xbfb8aa3b, v41
	v_exp_f32_e32 v33, v33
	v_cvt_pk_bf16_f32 v32, v32, s0
	ds_write_b16 v128, v32 offset:21824
	v_add_f32_e32 v33, 1.0, v33
	v_lshlrev_b32_e32 v32, 16, v165
	v_rcp_f32_e32 v34, v33
	s_nop 0
	v_mul_f32_e32 v33, v41, v34
	v_mul_f32_e32 v32, v33, v32
	v_mul_f32_e32 v33, 0xbfb8aa3b, v42
	v_exp_f32_e32 v33, v33
	v_cvt_pk_bf16_f32 v32, v32, s0
	ds_write_b16 v128, v32 offset:22096
	v_add_f32_e32 v33, 1.0, v33
	v_lshlrev_b32_e32 v32, 16, v166
	v_rcp_f32_e32 v34, v33
	s_nop 0
	v_mul_f32_e32 v33, v42, v34
	v_mul_f32_e32 v32, v33, v32
	v_mul_f32_e32 v33, 0xbfb8aa3b, v43
	v_exp_f32_e32 v33, v33
; DEV u16 f2bf(float f) { return (u16)(pk2bf(f, 0.f) & 0xffffu); }
; DEV float bf2f(u16 h) { return __uint_as_float(((unsigned)h) << 16); }
; DEV float siluf_(float x) { return x / (1.0f + __expf(-x)); }
; template <int MI>
; DEV void p4_tile(const Params& p, int l, int m0, int nt, unsigned char* smem) {
;     ...
;     acc_foreach_t<MI>([&](int mi, int ni, int r, int row, int col) __attribute__((always_inline)) {
;       sC[row * LDC + col] = f2bf(bf2f(sC[row * LDC + col]) * siluf_(acc[mi][ni][r]));
	v_cvt_pk_bf16_f32 v32, v32, s0
	ds_write_b16 v128, v32 offset:22368
	v_add_f32_e32 v33, 1.0, v33
	v_lshlrev_b32_e32 v32, 16, v167
	v_rcp_f32_e32 v34, v33
	s_nop 0
	v_mul_f32_e32 v33, v43, v34
	v_mul_f32_e32 v32, v33, v32
	v_mul_f32_e32 v33, 0xbfb8aa3b, v44
	v_exp_f32_e32 v33, v33
	v_cvt_pk_bf16_f32 v32, v32, s0
	ds_write_b16 v128, v32 offset:22640
	v_add_f32_e32 v33, 1.0, v33
	v_lshlrev_b32_e32 v32, 16, v168
	v_rcp_f32_e32 v34, v33
	s_nop 0
	v_mul_f32_e32 v33, v44, v34
	v_mul_f32_e32 v32, v33, v32
	v_mul_f32_e32 v33, 0xbfb8aa3b, v45
	v_exp_f32_e32 v33, v33
	v_cvt_pk_bf16_f32 v32, v32, s0
	ds_write_b16 v128, v32 offset:24000
	v_add_f32_e32 v33, 1.0, v33
	v_lshlrev_b32_e32 v32, 16, v169
	v_rcp_f32_e32 v34, v33
	s_nop 0
	v_mul_f32_e32 v33, v45, v34
	v_mul_f32_e32 v32, v33, v32
	v_mul_f32_e32 v33, 0xbfb8aa3b, v46
	v_exp_f32_e32 v33, v33
	v_cvt_pk_bf16_f32 v32, v32, s0
	ds_write_b16 v128, v32 offset:24272
	v_add_f32_e32 v33, 1.0, v33
	v_lshlrev_b32_e32 v32, 16, v170
	v_rcp_f32_e32 v34, v33
	s_nop 0
	v_mul_f32_e32 v33, v46, v34
	v_mul_f32_e32 v32, v33, v32
	v_mul_f32_e32 v33, 0xbfb8aa3b, v47
	v_exp_f32_e32 v33, v33
	v_cvt_pk_bf16_f32 v32, v32, s0
	ds_write_b16 v128, v32 offset:24544
	v_add_f32_e32 v33, 1.0, v33
	v_lshlrev_b32_e32 v32, 16, v171
	v_rcp_f32_e32 v34, v33
	s_nop 0
	v_mul_f32_e32 v33, v47, v34
	v_mul_f32_e32 v32, v33, v32
	v_mul_f32_e32 v33, 0xbfb8aa3b, v16
	v_exp_f32_e32 v33, v33
	v_cvt_pk_bf16_f32 v32, v32, s0
	ds_write_b16 v128, v32 offset:24816
	v_add_f32_e32 v33, 1.0, v33
	v_lshlrev_b32_e32 v32, 16, v172
	v_rcp_f32_e32 v34, v33
	s_nop 0
	v_mul_f32_e32 v16, v16, v34
	v_mul_f32_e32 v16, v16, v32
	v_mul_f32_e32 v32, 0xbfb8aa3b, v17
	v_exp_f32_e32 v32, v32
	v_cvt_pk_bf16_f32 v16, v16, s0
	ds_write_b16 v128, v16 offset:26112
	v_add_f32_e32 v32, 1.0, v32
	v_lshlrev_b32_e32 v16, 16, v173
	v_rcp_f32_e32 v33, v32
	s_nop 0
	v_mul_f32_e32 v17, v17, v33
	v_mul_f32_e32 v16, v17, v16
	v_mul_f32_e32 v17, 0xbfb8aa3b, v18
	v_exp_f32_e32 v17, v17
	v_cvt_pk_bf16_f32 v16, v16, s0
	ds_write_b16 v128, v16 offset:26384
	v_add_f32_e32 v17, 1.0, v17
	v_lshlrev_b32_e32 v16, 16, v174
	v_rcp_f32_e32 v32, v17
	s_nop 0
	v_mul_f32_e32 v17, v18, v32
	v_mul_f32_e32 v16, v17, v16
	v_mul_f32_e32 v17, 0xbfb8aa3b, v19
	v_exp_f32_e32 v17, v17
	v_cvt_pk_bf16_f32 v16, v16, s0
	ds_write_b16 v128, v16 offset:26656
	v_add_f32_e32 v17, 1.0, v17
	v_lshlrev_b32_e32 v16, 16, v175
	v_rcp_f32_e32 v18, v17
	s_nop 0
	v_mul_f32_e32 v17, v19, v18
	v_mul_f32_e32 v16, v17, v16
	v_mul_f32_e32 v17, 0xbfb8aa3b, v20
	v_exp_f32_e32 v17, v17
	v_cvt_pk_bf16_f32 v16, v16, s0
	ds_write_b16 v128, v16 offset:26928
	v_add_f32_e32 v17, 1.0, v17
	v_lshlrev_b32_e32 v16, 16, v176
	v_rcp_f32_e32 v18, v17
	s_nop 0
	v_mul_f32_e32 v17, v20, v18
	v_mul_f32_e32 v16, v17, v16
	v_mul_f32_e32 v17, 0xbfb8aa3b, v21
	v_exp_f32_e32 v17, v17
	v_cvt_pk_bf16_f32 v16, v16, s0
	ds_write_b16 v128, v16 offset:28288
	v_add_f32_e32 v17, 1.0, v17
	v_lshlrev_b32_e32 v16, 16, v177
	v_rcp_f32_e32 v18, v17
	s_nop 0
	v_mul_f32_e32 v17, v21, v18
	v_mul_f32_e32 v16, v17, v16
	v_mul_f32_e32 v17, 0xbfb8aa3b, v22
	v_exp_f32_e32 v17, v17
	v_cvt_pk_bf16_f32 v16, v16, s0
	ds_write_b16 v128, v16 offset:28560
	v_add_f32_e32 v17, 1.0, v17
	v_lshlrev_b32_e32 v16, 16, v178
	v_rcp_f32_e32 v18, v17
	s_nop 0
	v_mul_f32_e32 v17, v22, v18
	v_mul_f32_e32 v16, v17, v16
	v_mul_f32_e32 v17, 0xbfb8aa3b, v23
	v_exp_f32_e32 v17, v17
	v_cvt_pk_bf16_f32 v16, v16, s0
	ds_write_b16 v128, v16 offset:28832
	v_add_f32_e32 v17, 1.0, v17
	v_lshlrev_b32_e32 v16, 16, v179
	v_rcp_f32_e32 v18, v17
	s_nop 0
	v_mul_f32_e32 v17, v23, v18
	v_mul_f32_e32 v16, v17, v16
	v_mul_f32_e32 v17, 0xbfb8aa3b, v24
	v_exp_f32_e32 v17, v17
	v_cvt_pk_bf16_f32 v16, v16, s0
	ds_write_b16 v128, v16 offset:29104
	v_add_f32_e32 v17, 1.0, v17
	v_lshlrev_b32_e32 v16, 16, v180
	v_rcp_f32_e32 v18, v17
	s_nop 0
	v_mul_f32_e32 v17, v24, v18
	v_mul_f32_e32 v16, v17, v16
	v_mul_f32_e32 v17, 0xbfb8aa3b, v25
	v_exp_f32_e32 v17, v17
	v_cvt_pk_bf16_f32 v16, v16, s0
	ds_write_b16 v128, v16 offset:30464
	v_add_f32_e32 v17, 1.0, v17
	v_lshlrev_b32_e32 v16, 16, v181
	v_rcp_f32_e32 v18, v17
	s_nop 0
	v_mul_f32_e32 v17, v25, v18
	v_mul_f32_e32 v16, v17, v16
	v_mul_f32_e32 v17, 0xbfb8aa3b, v26
	v_exp_f32_e32 v17, v17
	v_cvt_pk_bf16_f32 v16, v16, s0
	ds_write_b16 v128, v16 offset:30736
	v_add_f32_e32 v17, 1.0, v17
	v_lshlrev_b32_e32 v16, 16, v182
	v_rcp_f32_e32 v18, v17
	s_nop 0
	v_mul_f32_e32 v17, v26, v18
	v_mul_f32_e32 v16, v17, v16
	v_mul_f32_e32 v17, 0xbfb8aa3b, v27
	v_exp_f32_e32 v17, v17
	v_cvt_pk_bf16_f32 v16, v16, s0
	ds_write_b16 v128, v16 offset:31008
	v_add_f32_e32 v17, 1.0, v17
	v_lshlrev_b32_e32 v16, 16, v183
	v_rcp_f32_e32 v18, v17
	s_nop 0
	v_mul_f32_e32 v17, v27, v18
	v_mul_f32_e32 v16, v17, v16
	v_mul_f32_e32 v17, 0xbfb8aa3b, v28
	v_exp_f32_e32 v17, v17
	v_cvt_pk_bf16_f32 v16, v16, s0
	ds_write_b16 v128, v16 offset:31280
	v_add_f32_e32 v17, 1.0, v17
	v_lshlrev_b32_e32 v16, 16, v184
	v_rcp_f32_e32 v18, v17
	s_nop 0
	v_mul_f32_e32 v17, v28, v18
	v_mul_f32_e32 v16, v17, v16
	v_mul_f32_e32 v17, 0xbfb8aa3b, v29
	v_exp_f32_e32 v17, v17
	v_cvt_pk_bf16_f32 v16, v16, s0
	ds_write_b16 v128, v16 offset:32640
; DEV u16 f2bf(float f) { return (u16)(pk2bf(f, 0.f) & 0xffffu); }
; DEV float bf2f(u16 h) { return __uint_as_float(((unsigned)h) << 16); }
; DEV float siluf_(float x) { return x / (1.0f + __expf(-x)); }
; template <int MI>
; DEV void p4_tile(const Params& p, int l, int m0, int nt, unsigned char* smem) {
;     ...
;     acc_foreach_t<MI>([&](int mi, int ni, int r, int row, int col) __attribute__((always_inline)) {
;       sC[row * LDC + col] = f2bf(bf2f(sC[row * LDC + col]) * siluf_(acc[mi][ni][r]));
;     });
;     tile_store_t<MI>(smem, YB + (size_t)m0 * 1024 + nt * 128, 1024);
	v_add_f32_e32 v17, 1.0, v17
	v_lshlrev_b32_e32 v16, 16, v185
	v_rcp_f32_e32 v18, v17
	s_nop 0
	v_mul_f32_e32 v17, v29, v18
	v_mul_f32_e32 v16, v17, v16
	v_mul_f32_e32 v17, 0xbfb8aa3b, v30
	v_exp_f32_e32 v17, v17
	v_cvt_pk_bf16_f32 v16, v16, s0
	ds_write_b16 v128, v16 offset:32912
	v_add_f32_e32 v17, 1.0, v17
	v_lshlrev_b32_e32 v16, 16, v186
	v_rcp_f32_e32 v18, v17
	s_nop 0
	v_mul_f32_e32 v17, v30, v18
	v_mul_f32_e32 v16, v17, v16
	v_mul_f32_e32 v17, 0xbfb8aa3b, v31
	v_exp_f32_e32 v17, v17
	v_cvt_pk_bf16_f32 v16, v16, s0
	ds_write_b16 v128, v16 offset:33184
	v_add_f32_e32 v17, 1.0, v17
	v_lshlrev_b32_e32 v16, 16, v187
	v_rcp_f32_e32 v18, v17
	s_nop 0
	v_mul_f32_e32 v17, v31, v18
	v_mul_f32_e32 v16, v17, v16
	v_mul_f32_e32 v17, 0xbfb8aa3b, v0
	v_exp_f32_e32 v17, v17
	v_cvt_pk_bf16_f32 v16, v16, s0
	ds_write_b16 v128, v16 offset:33456
	v_add_f32_e32 v17, 1.0, v17
	v_lshlrev_b32_e32 v16, 16, v188
	v_rcp_f32_e32 v18, v17
	s_nop 0
	v_mul_f32_e32 v0, v0, v18
	v_mul_f32_e32 v0, v0, v16
	v_mul_f32_e32 v16, 0xbfb8aa3b, v1
	v_exp_f32_e32 v16, v16
	v_cvt_pk_bf16_f32 v0, v0, s0
	ds_write_b16 v128, v0 offset:26176
	v_add_f32_e32 v16, 1.0, v16
	v_lshlrev_b32_e32 v0, 16, v189
	v_rcp_f32_e32 v17, v16
	s_nop 0
	v_mul_f32_e32 v1, v1, v17
	v_mul_f32_e32 v0, v1, v0
	v_mul_f32_e32 v1, 0xbfb8aa3b, v2
	v_exp_f32_e32 v1, v1
	v_cvt_pk_bf16_f32 v0, v0, s0
	ds_write_b16 v128, v0 offset:26448
	v_add_f32_e32 v1, 1.0, v1
	v_lshlrev_b32_e32 v0, 16, v190
	v_rcp_f32_e32 v16, v1
	s_nop 0
	v_mul_f32_e32 v1, v2, v16
	v_mul_f32_e32 v0, v1, v0
	v_mul_f32_e32 v1, 0xbfb8aa3b, v3
	v_exp_f32_e32 v1, v1
	v_cvt_pk_bf16_f32 v0, v0, s0
	ds_write_b16 v128, v0 offset:26720
	v_add_f32_e32 v1, 1.0, v1
	v_lshlrev_b32_e32 v0, 16, v191
	v_rcp_f32_e32 v2, v1
	s_nop 0
	v_mul_f32_e32 v1, v3, v2
	v_mul_f32_e32 v0, v1, v0
	v_mul_f32_e32 v1, 0xbfb8aa3b, v4
	v_exp_f32_e32 v1, v1
	v_cvt_pk_bf16_f32 v0, v0, s0
	ds_write_b16 v128, v0 offset:26992
	v_add_f32_e32 v1, 1.0, v1
	v_lshlrev_b32_e32 v0, 16, v192
	v_rcp_f32_e32 v2, v1
	s_nop 0
	v_mul_f32_e32 v1, v4, v2
	v_mul_f32_e32 v0, v1, v0
	v_mul_f32_e32 v1, 0xbfb8aa3b, v5
	v_exp_f32_e32 v1, v1
	v_cvt_pk_bf16_f32 v0, v0, s0
	ds_write_b16 v128, v0 offset:28352
	v_add_f32_e32 v1, 1.0, v1
	v_lshlrev_b32_e32 v0, 16, v193
	v_rcp_f32_e32 v2, v1
	s_nop 0
	v_mul_f32_e32 v1, v5, v2
	v_mul_f32_e32 v0, v1, v0
	v_mul_f32_e32 v1, 0xbfb8aa3b, v6
	v_exp_f32_e32 v1, v1
	v_cvt_pk_bf16_f32 v0, v0, s0
	ds_write_b16 v128, v0 offset:28624
	v_add_f32_e32 v1, 1.0, v1
	v_lshlrev_b32_e32 v0, 16, v194
	v_rcp_f32_e32 v2, v1
	s_nop 0
	v_mul_f32_e32 v1, v6, v2
	v_mul_f32_e32 v0, v1, v0
	v_mul_f32_e32 v1, 0xbfb8aa3b, v7
	v_exp_f32_e32 v1, v1
	v_cvt_pk_bf16_f32 v0, v0, s0
	ds_write_b16 v128, v0 offset:28896
	v_add_f32_e32 v1, 1.0, v1
	v_lshlrev_b32_e32 v0, 16, v195
	v_rcp_f32_e32 v2, v1
	s_nop 0
	v_mul_f32_e32 v1, v7, v2
	v_mul_f32_e32 v0, v1, v0
	v_mul_f32_e32 v1, 0xbfb8aa3b, v8
	v_exp_f32_e32 v1, v1
	v_cvt_pk_bf16_f32 v0, v0, s0
	ds_write_b16 v128, v0 offset:29168
	v_add_f32_e32 v1, 1.0, v1
	v_lshlrev_b32_e32 v0, 16, v196
	v_rcp_f32_e32 v2, v1
	s_nop 0
	v_mul_f32_e32 v1, v8, v2
	v_mul_f32_e32 v0, v1, v0
	v_mul_f32_e32 v1, 0xbfb8aa3b, v9
	v_exp_f32_e32 v1, v1
	v_cvt_pk_bf16_f32 v0, v0, s0
	ds_write_b16 v128, v0 offset:30528
	v_add_f32_e32 v1, 1.0, v1
	v_lshlrev_b32_e32 v0, 16, v197
	v_rcp_f32_e32 v2, v1
	s_nop 0
	v_mul_f32_e32 v1, v9, v2
	v_mul_f32_e32 v0, v1, v0
	v_mul_f32_e32 v1, 0xbfb8aa3b, v10
	v_exp_f32_e32 v1, v1
	v_cvt_pk_bf16_f32 v0, v0, s0
	ds_write_b16 v128, v0 offset:30800
	v_add_f32_e32 v1, 1.0, v1
	v_lshlrev_b32_e32 v0, 16, v198
	v_rcp_f32_e32 v2, v1
	s_nop 0
	v_mul_f32_e32 v1, v10, v2
	v_mul_f32_e32 v0, v1, v0
	v_mul_f32_e32 v1, 0xbfb8aa3b, v11
	v_exp_f32_e32 v1, v1
	v_cvt_pk_bf16_f32 v0, v0, s0
	ds_write_b16 v128, v0 offset:31072
	v_add_f32_e32 v1, 1.0, v1
	v_lshlrev_b32_e32 v0, 16, v199
	v_rcp_f32_e32 v2, v1
	s_nop 0
	v_mul_f32_e32 v1, v11, v2
	v_mul_f32_e32 v0, v1, v0
	v_mul_f32_e32 v1, 0xbfb8aa3b, v12
	v_exp_f32_e32 v1, v1
	v_cvt_pk_bf16_f32 v0, v0, s0
	ds_write_b16 v128, v0 offset:31344
	v_add_f32_e32 v1, 1.0, v1
	v_lshlrev_b32_e32 v0, 16, v200
	v_rcp_f32_e32 v2, v1
	s_nop 0
	v_mul_f32_e32 v1, v12, v2
	v_mul_f32_e32 v0, v1, v0
	v_mul_f32_e32 v1, 0xbfb8aa3b, v13
	v_exp_f32_e32 v1, v1
	v_cvt_pk_bf16_f32 v0, v0, s0
	ds_write_b16 v128, v0 offset:32704
	v_add_f32_e32 v1, 1.0, v1
	v_lshlrev_b32_e32 v0, 16, v201
	v_rcp_f32_e32 v2, v1
	s_nop 0
	v_mul_f32_e32 v1, v13, v2
	v_mul_f32_e32 v0, v1, v0
	v_mul_f32_e32 v1, 0xbfb8aa3b, v14
	v_exp_f32_e32 v1, v1
	v_cvt_pk_bf16_f32 v0, v0, s0
	ds_write_b16 v128, v0 offset:32976
	v_add_f32_e32 v1, 1.0, v1
	v_lshlrev_b32_e32 v0, 16, v202
	v_rcp_f32_e32 v2, v1
	s_nop 0
	v_mul_f32_e32 v1, v14, v2
	v_mul_f32_e32 v0, v1, v0
	v_mul_f32_e32 v1, 0xbfb8aa3b, v15
	v_exp_f32_e32 v1, v1
	v_cvt_pk_bf16_f32 v0, v0, s0
	ds_write_b16 v128, v0 offset:33248
	v_add_f32_e32 v1, 1.0, v1
	v_lshlrev_b32_e32 v0, 16, v203
	s_mov_b64 s[6:7], 0
	v_rcp_f32_e32 v2, v1
	s_nop 0
	v_mul_f32_e32 v1, v15, v2
	v_mul_f32_e32 v0, v1, v0
	v_cvt_pk_bf16_f32 v0, v0, s0
	ds_write_b16 v128, v0 offset:33520
	v_mov_b32_e32 v0, v232
	s_waitcnt lgkmcnt(0)
	s_barrier

; DEV u16 f2bf(float f) { return (u16)(pk2bf(f, 0.f) & 0xffffu); }
; DEV float siluf_(float x) { return x / (1.0f + __expf(-x)); }
; template <int MI>
; DEV void p4_tile(const Params& p, int l, int m0, int nt, unsigned char* smem) {
;     ...
;         acc_foreach_t<MI>([&](int mi, int ni, int r, int row, int col) __attribute__((always_inline)) {
;           sC[row * LDC + col] = f2bf(att[mi][ni][r] * siluf_(acc[mi][ni][r]));
;         });
;         tile_store_t<MI>(smem, YB + (size_t)m0 * 1024 + nt * 128, 1024);
.LBB0_1226:
	s_waitcnt vmcnt(6)
	s_nop 3
	v_mul_f32_e32 v129, 0xbfb8aa3b, v112
	v_exp_f32_e32 v129, v129
	v_mov_b32_e32 v128, v232
	s_barrier
	v_add_f32_e32 v129, 1.0, v129
	s_waitcnt vmcnt(5)
	s_nop 0
	v_lshrrev_b32_e32 v131, 3, v128
	v_lshrrev_b32_e32 v130, 1, v128
	v_and_b32_e32 v131, 4, v131
	v_and_or_b32 v130, v130, s72, v131
	v_mul_f32_e32 v132, 0xbfb8aa3b, v113
	v_exp_f32_e32 v132, v132
	v_rcp_f32_e32 v131, v129
	s_nop 0
	v_mul_f32_e32 v112, v112, v131
	v_mul_f32_e32 v64, v64, v112
	v_add_f32_e32 v129, 1.0, v132
	v_cvt_pk_bf16_f32 v112, v64, s0
	v_div_scale_f32 v131, s[0:1], v129, v129, v113
	v_rcp_f32_e32 v132, v131
	v_and_b32_e32 v128, 0x5f, v128
	v_mul_lo_u32 v64, v130, s42
	v_lshl_add_u32 v64, v128, 1, v64
	ds_write_b16 v64, v112
	v_fma_f32 v112, -v131, v132, 1.0
	v_fmac_f32_e32 v132, v112, v132
	v_div_scale_f32 v112, vcc, v113, v129, v113
	v_mul_f32_e32 v128, v112, v132
	v_fma_f32 v130, -v131, v128, v112
	v_fmac_f32_e32 v128, v130, v132
	v_mul_f32_e32 v130, 0xbfb8aa3b, v114
	v_exp_f32_e32 v130, v130
	v_fma_f32 v112, -v131, v128, v112
	v_div_fmas_f32 v112, v112, v132, v128
	v_div_fixup_f32 v112, v112, v129, v113
	v_add_f32_e32 v113, 1.0, v130
	v_div_scale_f32 v128, s[0:1], v113, v113, v114
	v_rcp_f32_e32 v129, v128
	v_mul_f32_e32 v65, v65, v112
	v_cvt_pk_bf16_f32 v65, v65, s0
	ds_write_b16 v64, v65 offset:272
	v_fma_f32 v65, -v128, v129, 1.0
	v_fmac_f32_e32 v129, v65, v129
	v_div_scale_f32 v65, vcc, v114, v113, v114
	v_mul_f32_e32 v112, v65, v129
	v_fma_f32 v130, -v128, v112, v65
	v_fmac_f32_e32 v112, v130, v129
	v_fma_f32 v65, -v128, v112, v65
	v_mul_f32_e32 v128, 0xbfb8aa3b, v115
	v_exp_f32_e32 v128, v128
	v_div_fmas_f32 v65, v65, v129, v112
	v_div_fixup_f32 v65, v65, v113, v114
	v_mul_f32_e32 v65, v66, v65
	v_add_f32_e32 v112, 1.0, v128
	v_div_scale_f32 v113, s[0:1], v112, v112, v115
	v_rcp_f32_e32 v114, v113
	s_nop 0
	v_cvt_pk_bf16_f32 v65, v65, s0
	ds_write_b16 v64, v65 offset:544
	v_fma_f32 v65, -v113, v114, 1.0
	v_fmac_f32_e32 v114, v65, v114
	v_div_scale_f32 v65, vcc, v115, v112, v115
	v_mul_f32_e32 v66, v65, v114
	v_fma_f32 v128, -v113, v66, v65
	v_fmac_f32_e32 v66, v128, v114
	v_fma_f32 v65, -v113, v66, v65
	v_mul_f32_e32 v113, 0xbfb8aa3b, v116
	v_exp_f32_e32 v113, v113
	v_div_fmas_f32 v65, v65, v114, v66
	v_div_fixup_f32 v65, v65, v112, v115
	v_mul_f32_e32 v65, v67, v65
	v_add_f32_e32 v66, 1.0, v113
	v_div_scale_f32 v112, s[0:1], v66, v66, v116
	v_rcp_f32_e32 v113, v112
	s_nop 0
	v_cvt_pk_bf16_f32 v65, v65, s0
	ds_write_b16 v64, v65 offset:816
	v_fma_f32 v65, -v112, v113, 1.0
	v_fmac_f32_e32 v113, v65, v113
	v_div_scale_f32 v65, vcc, v116, v66, v116
	v_mul_f32_e32 v67, v65, v113
	v_fma_f32 v114, -v112, v67, v65
	v_fmac_f32_e32 v67, v114, v113
	v_fma_f32 v65, -v112, v67, v65
	v_mul_f32_e32 v112, 0xbfb8aa3b, v117
	v_exp_f32_e32 v112, v112
	v_div_fmas_f32 v65, v65, v113, v67
	v_div_fixup_f32 v65, v65, v66, v116
	v_mul_f32_e32 v65, v68, v65
	v_add_f32_e32 v66, 1.0, v112
	v_div_scale_f32 v67, s[0:1], v66, v66, v117
	v_rcp_f32_e32 v112, v67
	s_nop 0
	v_cvt_pk_bf16_f32 v65, v65, s0
	ds_write_b16 v64, v65 offset:2176
	v_fma_f32 v65, -v67, v112, 1.0
	v_fmac_f32_e32 v112, v65, v112
	v_div_scale_f32 v65, vcc, v117, v66, v117
	v_mul_f32_e32 v68, v65, v112
	v_fma_f32 v113, -v67, v68, v65
	v_fmac_f32_e32 v68, v113, v112
	v_fma_f32 v65, -v67, v68, v65
	v_mul_f32_e32 v67, 0xbfb8aa3b, v118
	v_exp_f32_e32 v67, v67
	v_div_fmas_f32 v65, v65, v112, v68
	v_div_fixup_f32 v65, v65, v66, v117
	v_mul_f32_e32 v65, v69, v65
	v_add_f32_e32 v66, 1.0, v67
	v_div_scale_f32 v67, s[0:1], v66, v66, v118
	v_rcp_f32_e32 v68, v67
	s_nop 0
	v_cvt_pk_bf16_f32 v65, v65, s0
	ds_write_b16 v64, v65 offset:2448
	v_fma_f32 v65, -v67, v68, 1.0
	v_fmac_f32_e32 v68, v65, v68
	v_div_scale_f32 v65, vcc, v118, v66, v118
	v_mul_f32_e32 v69, v65, v68
	v_fma_f32 v112, -v67, v69, v65
	v_fmac_f32_e32 v69, v112, v68
	v_fma_f32 v65, -v67, v69, v65
	v_mul_f32_e32 v67, 0xbfb8aa3b, v119
	v_exp_f32_e32 v67, v67
	v_div_fmas_f32 v65, v65, v68, v69
	v_div_fixup_f32 v65, v65, v66, v118
	v_mul_f32_e32 v65, v70, v65
	v_add_f32_e32 v66, 1.0, v67
	v_div_scale_f32 v67, s[0:1], v66, v66, v119
	v_rcp_f32_e32 v68, v67
	s_nop 0
	v_cvt_pk_bf16_f32 v65, v65, s0
	ds_write_b16 v64, v65 offset:2720
	v_fma_f32 v65, -v67, v68, 1.0
	v_fmac_f32_e32 v68, v65, v68
	v_div_scale_f32 v65, vcc, v119, v66, v119
	v_mul_f32_e32 v69, v65, v68
	v_fma_f32 v70, -v67, v69, v65
	v_fmac_f32_e32 v69, v70, v68
	v_fma_f32 v65, -v67, v69, v65
	v_mul_f32_e32 v67, 0xbfb8aa3b, v120
	v_exp_f32_e32 v67, v67
	v_div_fmas_f32 v65, v65, v68, v69
	v_div_fixup_f32 v65, v65, v66, v119
	v_mul_f32_e32 v65, v71, v65
	v_add_f32_e32 v66, 1.0, v67
	v_div_scale_f32 v67, s[0:1], v66, v66, v120
	v_rcp_f32_e32 v68, v67
	s_nop 0
	v_cvt_pk_bf16_f32 v65, v65, s0
	ds_write_b16 v64, v65 offset:2992
	v_fma_f32 v65, -v67, v68, 1.0
	v_fmac_f32_e32 v68, v65, v68
	v_div_scale_f32 v65, vcc, v120, v66, v120
	v_mul_f32_e32 v69, v65, v68
	v_fma_f32 v70, -v67, v69, v65
	v_fmac_f32_e32 v69, v70, v68
	v_fma_f32 v65, -v67, v69, v65
	v_mul_f32_e32 v67, 0xbfb8aa3b, v121
	v_exp_f32_e32 v67, v67
	v_div_fmas_f32 v65, v65, v68, v69
	v_div_fixup_f32 v65, v65, v66, v120
	v_mul_f32_e32 v65, v72, v65
	v_add_f32_e32 v66, 1.0, v67
	v_div_scale_f32 v67, s[0:1], v66, v66, v121
	v_rcp_f32_e32 v68, v67
	s_nop 0
	v_cvt_pk_bf16_f32 v65, v65, s0
	ds_write_b16 v64, v65 offset:4352
	v_fma_f32 v65, -v67, v68, 1.0
	v_fmac_f32_e32 v68, v65, v68
	v_div_scale_f32 v65, vcc, v121, v66, v121
	v_mul_f32_e32 v69, v65, v68
	v_fma_f32 v70, -v67, v69, v65
	v_fmac_f32_e32 v69, v70, v68
	v_fma_f32 v65, -v67, v69, v65
	v_mul_f32_e32 v67, 0xbfb8aa3b, v122
	v_exp_f32_e32 v67, v67
; DEV u16 f2bf(float f) { return (u16)(pk2bf(f, 0.f) & 0xffffu); }
; DEV float siluf_(float x) { return x / (1.0f + __expf(-x)); }
; template <int MI>
; DEV void p4_tile(const Params& p, int l, int m0, int nt, unsigned char* smem) {
;     ...
;         acc_foreach_t<MI>([&](int mi, int ni, int r, int row, int col) __attribute__((always_inline)) {
;           sC[row * LDC + col] = f2bf(att[mi][ni][r] * siluf_(acc[mi][ni][r]));
;         });
	v_div_fmas_f32 v65, v65, v68, v69
	v_div_fixup_f32 v65, v65, v66, v121
	v_mul_f32_e32 v65, v73, v65
	v_add_f32_e32 v66, 1.0, v67
	v_div_scale_f32 v67, s[0:1], v66, v66, v122
	v_rcp_f32_e32 v68, v67
	s_nop 0
	v_cvt_pk_bf16_f32 v65, v65, s0
	ds_write_b16 v64, v65 offset:4624
	v_fma_f32 v65, -v67, v68, 1.0
	v_fmac_f32_e32 v68, v65, v68
	v_div_scale_f32 v65, vcc, v122, v66, v122
	v_mul_f32_e32 v69, v65, v68
	v_fma_f32 v70, -v67, v69, v65
	v_fmac_f32_e32 v69, v70, v68
	v_fma_f32 v65, -v67, v69, v65
	v_mul_f32_e32 v67, 0xbfb8aa3b, v123
	v_exp_f32_e32 v67, v67
	v_div_fmas_f32 v65, v65, v68, v69
	v_div_fixup_f32 v65, v65, v66, v122
	v_mul_f32_e32 v65, v74, v65
	v_add_f32_e32 v66, 1.0, v67
	v_div_scale_f32 v67, s[0:1], v66, v66, v123
	v_rcp_f32_e32 v68, v67
	s_nop 0
	v_cvt_pk_bf16_f32 v65, v65, s0
	ds_write_b16 v64, v65 offset:4896
	v_fma_f32 v65, -v67, v68, 1.0
	v_fmac_f32_e32 v68, v65, v68
	v_div_scale_f32 v65, vcc, v123, v66, v123
	v_mul_f32_e32 v69, v65, v68
	v_fma_f32 v70, -v67, v69, v65
	v_fmac_f32_e32 v69, v70, v68
	v_fma_f32 v65, -v67, v69, v65
	v_mul_f32_e32 v67, 0xbfb8aa3b, v124
	v_exp_f32_e32 v67, v67
	v_div_fmas_f32 v65, v65, v68, v69
	v_div_fixup_f32 v65, v65, v66, v123
	v_mul_f32_e32 v65, v75, v65
	v_add_f32_e32 v66, 1.0, v67
	v_div_scale_f32 v67, s[0:1], v66, v66, v124
	v_rcp_f32_e32 v68, v67
	s_nop 0
	v_cvt_pk_bf16_f32 v65, v65, s0
	ds_write_b16 v64, v65 offset:5168
	v_fma_f32 v65, -v67, v68, 1.0
	v_fmac_f32_e32 v68, v65, v68
	v_div_scale_f32 v65, vcc, v124, v66, v124
	v_mul_f32_e32 v69, v65, v68
	v_fma_f32 v70, -v67, v69, v65
	v_fmac_f32_e32 v69, v70, v68
	v_fma_f32 v65, -v67, v69, v65
	v_mul_f32_e32 v67, 0xbfb8aa3b, v125
	v_exp_f32_e32 v67, v67
	v_div_fmas_f32 v65, v65, v68, v69
	v_div_fixup_f32 v65, v65, v66, v124
	v_mul_f32_e32 v65, v76, v65
	v_add_f32_e32 v66, 1.0, v67
	v_div_scale_f32 v67, s[0:1], v66, v66, v125
	v_rcp_f32_e32 v68, v67
	s_nop 0
	v_cvt_pk_bf16_f32 v65, v65, s0
	ds_write_b16 v64, v65 offset:6528
	v_fma_f32 v65, -v67, v68, 1.0
	v_fmac_f32_e32 v68, v65, v68
	v_div_scale_f32 v65, vcc, v125, v66, v125
	v_mul_f32_e32 v69, v65, v68
	v_fma_f32 v70, -v67, v69, v65
	v_fmac_f32_e32 v69, v70, v68
	v_fma_f32 v65, -v67, v69, v65
	v_mul_f32_e32 v67, 0xbfb8aa3b, v126
	v_exp_f32_e32 v67, v67
	v_div_fmas_f32 v65, v65, v68, v69
	v_div_fixup_f32 v65, v65, v66, v125
	v_mul_f32_e32 v65, v77, v65
	v_add_f32_e32 v66, 1.0, v67
	v_div_scale_f32 v67, s[0:1], v66, v66, v126
	v_rcp_f32_e32 v68, v67
	s_nop 0
	v_cvt_pk_bf16_f32 v65, v65, s0
	ds_write_b16 v64, v65 offset:6800
	v_fma_f32 v65, -v67, v68, 1.0
	v_fmac_f32_e32 v68, v65, v68
	v_div_scale_f32 v65, vcc, v126, v66, v126
	v_mul_f32_e32 v69, v65, v68
	v_fma_f32 v70, -v67, v69, v65
	v_fmac_f32_e32 v69, v70, v68
	v_fma_f32 v65, -v67, v69, v65
	v_mul_f32_e32 v67, 0xbfb8aa3b, v127
	v_exp_f32_e32 v67, v67
	v_div_fmas_f32 v65, v65, v68, v69
	v_div_fixup_f32 v65, v65, v66, v126
	v_mul_f32_e32 v65, v78, v65
	v_add_f32_e32 v66, 1.0, v67
	v_div_scale_f32 v67, s[0:1], v66, v66, v127
	v_rcp_f32_e32 v68, v67
	s_nop 0
	v_cvt_pk_bf16_f32 v65, v65, s0
	ds_write_b16 v64, v65 offset:7072
	v_fma_f32 v65, -v67, v68, 1.0
	v_fmac_f32_e32 v68, v65, v68
	v_div_scale_f32 v65, vcc, v127, v66, v127
	v_mul_f32_e32 v69, v65, v68
	v_fma_f32 v70, -v67, v69, v65
	v_fmac_f32_e32 v69, v70, v68
	v_fma_f32 v65, -v67, v69, v65
	v_mul_f32_e32 v67, 0xbfb8aa3b, v96
	v_exp_f32_e32 v67, v67
	v_div_fmas_f32 v65, v65, v68, v69
	v_div_fixup_f32 v65, v65, v66, v127
	v_mul_f32_e32 v65, v79, v65
	v_add_f32_e32 v66, 1.0, v67
	v_div_scale_f32 v67, s[0:1], v66, v66, v96
	v_rcp_f32_e32 v68, v67
	s_nop 0
	v_cvt_pk_bf16_f32 v65, v65, s0
	ds_write_b16 v64, v65 offset:7344
	v_fma_f32 v65, -v67, v68, 1.0
	v_fmac_f32_e32 v68, v65, v68
	v_div_scale_f32 v65, vcc, v96, v66, v96
	v_mul_f32_e32 v69, v65, v68
	v_fma_f32 v70, -v67, v69, v65
	v_fmac_f32_e32 v69, v70, v68
	v_fma_f32 v65, -v67, v69, v65
	v_mul_f32_e32 v67, 0xbfb8aa3b, v97
	v_exp_f32_e32 v67, v67
	v_div_fmas_f32 v65, v65, v68, v69
	v_div_fixup_f32 v65, v65, v66, v96
	v_mul_f32_e32 v32, v32, v65
	v_add_f32_e32 v66, 1.0, v67
	v_div_scale_f32 v67, s[0:1], v66, v66, v97
	v_rcp_f32_e32 v68, v67
	s_nop 0
	v_cvt_pk_bf16_f32 v32, v32, s0
	ds_write_b16 v64, v32 offset:64
	v_fma_f32 v32, -v67, v68, 1.0
	v_fmac_f32_e32 v68, v32, v68
	v_div_scale_f32 v32, vcc, v97, v66, v97
	v_mul_f32_e32 v65, v32, v68
	v_fma_f32 v69, -v67, v65, v32
	v_fmac_f32_e32 v65, v69, v68
	v_fma_f32 v32, -v67, v65, v32
	v_mul_f32_e32 v67, 0xbfb8aa3b, v98
	v_exp_f32_e32 v67, v67
	v_div_fmas_f32 v32, v32, v68, v65
	v_div_fixup_f32 v32, v32, v66, v97
	v_mul_f32_e32 v32, v33, v32
	v_add_f32_e32 v65, 1.0, v67
	v_div_scale_f32 v66, s[0:1], v65, v65, v98
	v_rcp_f32_e32 v67, v66
	s_nop 0
	v_cvt_pk_bf16_f32 v32, v32, s0
	ds_write_b16 v64, v32 offset:336
	v_fma_f32 v32, -v66, v67, 1.0
	v_fmac_f32_e32 v67, v32, v67
	v_div_scale_f32 v32, vcc, v98, v65, v98
	v_mul_f32_e32 v33, v32, v67
	v_fma_f32 v68, -v66, v33, v32
	v_fmac_f32_e32 v33, v68, v67
	v_fma_f32 v32, -v66, v33, v32
	v_mul_f32_e32 v66, 0xbfb8aa3b, v99
	v_exp_f32_e32 v66, v66
	v_div_fmas_f32 v32, v32, v67, v33
	v_div_fixup_f32 v32, v32, v65, v98
	v_mul_f32_e32 v32, v34, v32
	v_add_f32_e32 v33, 1.0, v66
	v_div_scale_f32 v65, s[0:1], v33, v33, v99
	v_rcp_f32_e32 v66, v65
	s_nop 0
	v_cvt_pk_bf16_f32 v32, v32, s0
	ds_write_b16 v64, v32 offset:608
	v_fma_f32 v32, -v65, v66, 1.0
	v_fmac_f32_e32 v66, v32, v66
	v_div_scale_f32 v32, vcc, v99, v33, v99
	v_mul_f32_e32 v34, v32, v66
	v_fma_f32 v67, -v65, v34, v32
	v_fmac_f32_e32 v34, v67, v66
	v_fma_f32 v32, -v65, v34, v32
	v_mul_f32_e32 v65, 0xbfb8aa3b, v100
	v_exp_f32_e32 v65, v65
	v_div_fmas_f32 v32, v32, v66, v34
; DEV u16 f2bf(float f) { return (u16)(pk2bf(f, 0.f) & 0xffffu); }
; DEV float siluf_(float x) { return x / (1.0f + __expf(-x)); }
; template <int MI>
; DEV void p4_tile(const Params& p, int l, int m0, int nt, unsigned char* smem) {
;     ...
;         acc_foreach_t<MI>([&](int mi, int ni, int r, int row, int col) __attribute__((always_inline)) {
;           sC[row * LDC + col] = f2bf(att[mi][ni][r] * siluf_(acc[mi][ni][r]));
;         });
	v_div_fixup_f32 v32, v32, v33, v99
	v_mul_f32_e32 v32, v35, v32
	v_add_f32_e32 v33, 1.0, v65
	v_div_scale_f32 v34, s[0:1], v33, v33, v100
	v_rcp_f32_e32 v65, v34
	s_nop 0
	v_cvt_pk_bf16_f32 v32, v32, s0
	ds_write_b16 v64, v32 offset:880
	v_fma_f32 v32, -v34, v65, 1.0
	v_fmac_f32_e32 v65, v32, v65
	v_div_scale_f32 v32, vcc, v100, v33, v100
	v_mul_f32_e32 v35, v32, v65
	v_fma_f32 v66, -v34, v35, v32
	v_fmac_f32_e32 v35, v66, v65
	v_fma_f32 v32, -v34, v35, v32
	v_mul_f32_e32 v34, 0xbfb8aa3b, v101
	v_exp_f32_e32 v34, v34
	v_div_fmas_f32 v32, v32, v65, v35
	v_div_fixup_f32 v32, v32, v33, v100
	v_mul_f32_e32 v32, v36, v32
	v_add_f32_e32 v33, 1.0, v34
	v_div_scale_f32 v34, s[0:1], v33, v33, v101
	v_rcp_f32_e32 v35, v34
	s_nop 0
	v_cvt_pk_bf16_f32 v32, v32, s0
	ds_write_b16 v64, v32 offset:2240
	v_fma_f32 v32, -v34, v35, 1.0
	v_fmac_f32_e32 v35, v32, v35
	v_div_scale_f32 v32, vcc, v101, v33, v101
	v_mul_f32_e32 v36, v32, v35
	v_fma_f32 v65, -v34, v36, v32
	v_fmac_f32_e32 v36, v65, v35
	v_fma_f32 v32, -v34, v36, v32
	v_mul_f32_e32 v34, 0xbfb8aa3b, v102
	v_exp_f32_e32 v34, v34
	v_div_fmas_f32 v32, v32, v35, v36
	v_div_fixup_f32 v32, v32, v33, v101
	v_mul_f32_e32 v32, v37, v32
	v_add_f32_e32 v33, 1.0, v34
	v_div_scale_f32 v34, s[0:1], v33, v33, v102
	v_rcp_f32_e32 v35, v34
	s_nop 0
	v_cvt_pk_bf16_f32 v32, v32, s0
	ds_write_b16 v64, v32 offset:2512
	v_fma_f32 v32, -v34, v35, 1.0
	v_fmac_f32_e32 v35, v32, v35
	v_div_scale_f32 v32, vcc, v102, v33, v102
	v_mul_f32_e32 v36, v32, v35
	v_fma_f32 v37, -v34, v36, v32
	v_fmac_f32_e32 v36, v37, v35
	v_fma_f32 v32, -v34, v36, v32
	v_mul_f32_e32 v34, 0xbfb8aa3b, v103
	v_exp_f32_e32 v34, v34
	v_div_fmas_f32 v32, v32, v35, v36
	v_div_fixup_f32 v32, v32, v33, v102
	v_mul_f32_e32 v32, v38, v32
	v_add_f32_e32 v33, 1.0, v34
	v_div_scale_f32 v34, s[0:1], v33, v33, v103
	v_rcp_f32_e32 v35, v34
	s_nop 0
	v_cvt_pk_bf16_f32 v32, v32, s0
	ds_write_b16 v64, v32 offset:2784
	v_fma_f32 v32, -v34, v35, 1.0
	v_fmac_f32_e32 v35, v32, v35
	v_div_scale_f32 v32, vcc, v103, v33, v103
	v_mul_f32_e32 v36, v32, v35
	v_fma_f32 v37, -v34, v36, v32
	v_fmac_f32_e32 v36, v37, v35
	v_fma_f32 v32, -v34, v36, v32
	v_mul_f32_e32 v34, 0xbfb8aa3b, v104
	v_exp_f32_e32 v34, v34
	v_div_fmas_f32 v32, v32, v35, v36
	v_div_fixup_f32 v32, v32, v33, v103
	v_mul_f32_e32 v32, v39, v32
	v_add_f32_e32 v33, 1.0, v34
	v_div_scale_f32 v34, s[0:1], v33, v33, v104
	v_rcp_f32_e32 v35, v34
	s_nop 0
	v_cvt_pk_bf16_f32 v32, v32, s0
	ds_write_b16 v64, v32 offset:3056
	v_fma_f32 v32, -v34, v35, 1.0
	v_fmac_f32_e32 v35, v32, v35
	v_div_scale_f32 v32, vcc, v104, v33, v104
	v_mul_f32_e32 v36, v32, v35
	v_fma_f32 v37, -v34, v36, v32
	v_fmac_f32_e32 v36, v37, v35
	v_fma_f32 v32, -v34, v36, v32
	v_mul_f32_e32 v34, 0xbfb8aa3b, v105
	v_exp_f32_e32 v34, v34
	v_div_fmas_f32 v32, v32, v35, v36
	v_div_fixup_f32 v32, v32, v33, v104
	v_mul_f32_e32 v32, v40, v32
	v_add_f32_e32 v33, 1.0, v34
	v_div_scale_f32 v34, s[0:1], v33, v33, v105
	v_rcp_f32_e32 v35, v34
	s_nop 0
	v_cvt_pk_bf16_f32 v32, v32, s0
	ds_write_b16 v64, v32 offset:4416
	v_fma_f32 v32, -v34, v35, 1.0
	v_fmac_f32_e32 v35, v32, v35
	v_div_scale_f32 v32, vcc, v105, v33, v105
	v_mul_f32_e32 v36, v32, v35
	v_fma_f32 v37, -v34, v36, v32
	v_fmac_f32_e32 v36, v37, v35
	v_fma_f32 v32, -v34, v36, v32
	v_mul_f32_e32 v34, 0xbfb8aa3b, v106
	v_exp_f32_e32 v34, v34
	v_div_fmas_f32 v32, v32, v35, v36
	v_div_fixup_f32 v32, v32, v33, v105
	v_mul_f32_e32 v32, v41, v32
	v_add_f32_e32 v33, 1.0, v34
	v_div_scale_f32 v34, s[0:1], v33, v33, v106
	v_rcp_f32_e32 v35, v34
	s_nop 0
	v_cvt_pk_bf16_f32 v32, v32, s0
	ds_write_b16 v64, v32 offset:4688
	v_fma_f32 v32, -v34, v35, 1.0
	v_fmac_f32_e32 v35, v32, v35
	v_div_scale_f32 v32, vcc, v106, v33, v106
	v_mul_f32_e32 v36, v32, v35
	v_fma_f32 v37, -v34, v36, v32
	v_fmac_f32_e32 v36, v37, v35
	v_fma_f32 v32, -v34, v36, v32
	v_mul_f32_e32 v34, 0xbfb8aa3b, v107
	v_exp_f32_e32 v34, v34
	v_div_fmas_f32 v32, v32, v35, v36
	v_div_fixup_f32 v32, v32, v33, v106
	v_mul_f32_e32 v32, v42, v32
	v_add_f32_e32 v33, 1.0, v34
	v_div_scale_f32 v34, s[0:1], v33, v33, v107
	v_rcp_f32_e32 v35, v34
	s_nop 0
	v_cvt_pk_bf16_f32 v32, v32, s0
	ds_write_b16 v64, v32 offset:4960
	v_fma_f32 v32, -v34, v35, 1.0
	v_fmac_f32_e32 v35, v32, v35
	v_div_scale_f32 v32, vcc, v107, v33, v107
	v_mul_f32_e32 v36, v32, v35
	v_fma_f32 v37, -v34, v36, v32
	v_fmac_f32_e32 v36, v37, v35
	v_fma_f32 v32, -v34, v36, v32
	v_mul_f32_e32 v34, 0xbfb8aa3b, v108
	v_exp_f32_e32 v34, v34
	v_div_fmas_f32 v32, v32, v35, v36
	v_div_fixup_f32 v32, v32, v33, v107
	v_mul_f32_e32 v32, v43, v32
	v_add_f32_e32 v33, 1.0, v34
	v_div_scale_f32 v34, s[0:1], v33, v33, v108
	v_rcp_f32_e32 v35, v34
	s_nop 0
	v_cvt_pk_bf16_f32 v32, v32, s0
	ds_write_b16 v64, v32 offset:5232
	v_fma_f32 v32, -v34, v35, 1.0
	v_fmac_f32_e32 v35, v32, v35
	v_div_scale_f32 v32, vcc, v108, v33, v108
	v_mul_f32_e32 v36, v32, v35
	v_fma_f32 v37, -v34, v36, v32
	v_fmac_f32_e32 v36, v37, v35
	v_fma_f32 v32, -v34, v36, v32
	v_mul_f32_e32 v34, 0xbfb8aa3b, v109
	v_exp_f32_e32 v34, v34
	v_div_fmas_f32 v32, v32, v35, v36
	v_div_fixup_f32 v32, v32, v33, v108
	v_mul_f32_e32 v32, v44, v32
	v_add_f32_e32 v33, 1.0, v34
	v_div_scale_f32 v34, s[0:1], v33, v33, v109
	v_rcp_f32_e32 v35, v34
	s_nop 0
	v_cvt_pk_bf16_f32 v32, v32, s0
	ds_write_b16 v64, v32 offset:6592
	v_fma_f32 v32, -v34, v35, 1.0
	v_fmac_f32_e32 v35, v32, v35
	v_div_scale_f32 v32, vcc, v109, v33, v109
	v_mul_f32_e32 v36, v32, v35
	v_fma_f32 v37, -v34, v36, v32
	v_fmac_f32_e32 v36, v37, v35
	v_fma_f32 v32, -v34, v36, v32
	v_mul_f32_e32 v34, 0xbfb8aa3b, v110
	v_exp_f32_e32 v34, v34
	v_div_fmas_f32 v32, v32, v35, v36
	v_div_fixup_f32 v32, v32, v33, v109
; DEV u16 f2bf(float f) { return (u16)(pk2bf(f, 0.f) & 0xffffu); }
; DEV float siluf_(float x) { return x / (1.0f + __expf(-x)); }
; template <int MI>
; DEV void p4_tile(const Params& p, int l, int m0, int nt, unsigned char* smem) {
;     ...
;         acc_foreach_t<MI>([&](int mi, int ni, int r, int row, int col) __attribute__((always_inline)) {
;           sC[row * LDC + col] = f2bf(att[mi][ni][r] * siluf_(acc[mi][ni][r]));
;         });
	v_mul_f32_e32 v32, v45, v32
	v_add_f32_e32 v33, 1.0, v34
	v_div_scale_f32 v34, s[0:1], v33, v33, v110
	v_rcp_f32_e32 v35, v34
	s_nop 0
	v_cvt_pk_bf16_f32 v32, v32, s0
	ds_write_b16 v64, v32 offset:6864
	v_fma_f32 v32, -v34, v35, 1.0
	v_fmac_f32_e32 v35, v32, v35
	v_div_scale_f32 v32, vcc, v110, v33, v110
	v_mul_f32_e32 v36, v32, v35
	v_fma_f32 v37, -v34, v36, v32
	v_fmac_f32_e32 v36, v37, v35
	v_fma_f32 v32, -v34, v36, v32
	v_mul_f32_e32 v34, 0xbfb8aa3b, v111
	v_exp_f32_e32 v34, v34
	v_div_fmas_f32 v32, v32, v35, v36
	v_div_fixup_f32 v32, v32, v33, v110
	v_mul_f32_e32 v32, v46, v32
	v_add_f32_e32 v33, 1.0, v34
	v_div_scale_f32 v34, s[0:1], v33, v33, v111
	v_rcp_f32_e32 v35, v34
	s_nop 0
	v_cvt_pk_bf16_f32 v32, v32, s0
	ds_write_b16 v64, v32 offset:7136
	v_fma_f32 v32, -v34, v35, 1.0
	v_fmac_f32_e32 v35, v32, v35
	v_div_scale_f32 v32, vcc, v111, v33, v111
	v_mul_f32_e32 v36, v32, v35
	v_fma_f32 v37, -v34, v36, v32
	v_fmac_f32_e32 v36, v37, v35
	v_fma_f32 v32, -v34, v36, v32
	v_mul_f32_e32 v34, 0xbfb8aa3b, v80
	v_exp_f32_e32 v34, v34
	v_div_fmas_f32 v32, v32, v35, v36
	v_div_fixup_f32 v32, v32, v33, v111
	v_mul_f32_e32 v32, v47, v32
	v_add_f32_e32 v33, 1.0, v34
	v_div_scale_f32 v34, s[0:1], v33, v33, v80
	v_rcp_f32_e32 v35, v34
	s_nop 0
	v_cvt_pk_bf16_f32 v32, v32, s0
	ds_write_b16 v64, v32 offset:7408
	v_fma_f32 v32, -v34, v35, 1.0
	v_fmac_f32_e32 v35, v32, v35
	v_div_scale_f32 v32, vcc, v80, v33, v80
	v_mul_f32_e32 v36, v32, v35
	v_fma_f32 v37, -v34, v36, v32
	v_fmac_f32_e32 v36, v37, v35
	v_fma_f32 v32, -v34, v36, v32
	v_mul_f32_e32 v34, 0xbfb8aa3b, v81
	v_exp_f32_e32 v34, v34
	v_div_fmas_f32 v32, v32, v35, v36
	v_div_fixup_f32 v32, v32, v33, v80
	v_mul_f32_e32 v16, v16, v32
	v_add_f32_e32 v33, 1.0, v34
	v_div_scale_f32 v34, s[0:1], v33, v33, v81
	v_rcp_f32_e32 v35, v34
	s_nop 0
	v_cvt_pk_bf16_f32 v16, v16, s0
	ds_write_b16 v64, v16 offset:8704
	v_fma_f32 v16, -v34, v35, 1.0
	v_fmac_f32_e32 v35, v16, v35
	v_div_scale_f32 v16, vcc, v81, v33, v81
	v_mul_f32_e32 v32, v16, v35
	v_fma_f32 v36, -v34, v32, v16
	v_fmac_f32_e32 v32, v36, v35
	v_fma_f32 v16, -v34, v32, v16
	v_mul_f32_e32 v34, 0xbfb8aa3b, v82
	v_exp_f32_e32 v34, v34
	v_div_fmas_f32 v16, v16, v35, v32
	v_div_fixup_f32 v16, v16, v33, v81
	v_mul_f32_e32 v16, v17, v16
	v_add_f32_e32 v32, 1.0, v34
	v_div_scale_f32 v33, s[0:1], v32, v32, v82
	v_rcp_f32_e32 v34, v33
	s_nop 0
	v_cvt_pk_bf16_f32 v16, v16, s0
	ds_write_b16 v64, v16 offset:8976
	v_fma_f32 v16, -v33, v34, 1.0
	v_fmac_f32_e32 v34, v16, v34
	v_div_scale_f32 v16, vcc, v82, v32, v82
	v_mul_f32_e32 v17, v16, v34
	v_fma_f32 v35, -v33, v17, v16
	v_fmac_f32_e32 v17, v35, v34
	v_fma_f32 v16, -v33, v17, v16
	v_mul_f32_e32 v33, 0xbfb8aa3b, v83
	v_exp_f32_e32 v33, v33
	v_div_fmas_f32 v16, v16, v34, v17
	v_div_fixup_f32 v16, v16, v32, v82
	v_mul_f32_e32 v16, v18, v16
	v_add_f32_e32 v17, 1.0, v33
	v_div_scale_f32 v32, s[0:1], v17, v17, v83
	v_rcp_f32_e32 v33, v32
	s_nop 0
	v_cvt_pk_bf16_f32 v16, v16, s0
	ds_write_b16 v64, v16 offset:9248
	v_fma_f32 v16, -v32, v33, 1.0
	v_fmac_f32_e32 v33, v16, v33
	v_div_scale_f32 v16, vcc, v83, v17, v83
	v_mul_f32_e32 v18, v16, v33
	v_fma_f32 v34, -v32, v18, v16
	v_fmac_f32_e32 v18, v34, v33
	v_fma_f32 v16, -v32, v18, v16
	v_mul_f32_e32 v32, 0xbfb8aa3b, v84
	v_exp_f32_e32 v32, v32
	v_div_fmas_f32 v16, v16, v33, v18
	v_div_fixup_f32 v16, v16, v17, v83
	v_mul_f32_e32 v16, v19, v16
	v_add_f32_e32 v17, 1.0, v32
	v_div_scale_f32 v18, s[0:1], v17, v17, v84
	v_rcp_f32_e32 v32, v18
	s_nop 0
	v_cvt_pk_bf16_f32 v16, v16, s0
	ds_write_b16 v64, v16 offset:9520
	v_fma_f32 v16, -v18, v32, 1.0
	v_fmac_f32_e32 v32, v16, v32
	v_div_scale_f32 v16, vcc, v84, v17, v84
	v_mul_f32_e32 v19, v16, v32
	v_fma_f32 v33, -v18, v19, v16
	v_fmac_f32_e32 v19, v33, v32
	v_fma_f32 v16, -v18, v19, v16
	v_mul_f32_e32 v18, 0xbfb8aa3b, v85
	v_exp_f32_e32 v18, v18
	v_div_fmas_f32 v16, v16, v32, v19
	v_div_fixup_f32 v16, v16, v17, v84
	v_mul_f32_e32 v16, v20, v16
	v_add_f32_e32 v17, 1.0, v18
	v_div_scale_f32 v18, s[0:1], v17, v17, v85
	v_rcp_f32_e32 v19, v18
	s_nop 0
	v_cvt_pk_bf16_f32 v16, v16, s0
	ds_write_b16 v64, v16 offset:10880
	v_fma_f32 v16, -v18, v19, 1.0
	v_fmac_f32_e32 v19, v16, v19
	v_div_scale_f32 v16, vcc, v85, v17, v85
	v_mul_f32_e32 v20, v16, v19
	v_fma_f32 v32, -v18, v20, v16
	v_fmac_f32_e32 v20, v32, v19
	v_fma_f32 v16, -v18, v20, v16
	v_mul_f32_e32 v18, 0xbfb8aa3b, v86
	v_exp_f32_e32 v18, v18
	v_div_fmas_f32 v16, v16, v19, v20
	v_div_fixup_f32 v16, v16, v17, v85
	v_mul_f32_e32 v16, v21, v16
	v_add_f32_e32 v17, 1.0, v18
	v_div_scale_f32 v18, s[0:1], v17, v17, v86
	v_rcp_f32_e32 v19, v18
	s_nop 0
	v_cvt_pk_bf16_f32 v16, v16, s0
	ds_write_b16 v64, v16 offset:11152
	v_fma_f32 v16, -v18, v19, 1.0
	v_fmac_f32_e32 v19, v16, v19
	v_div_scale_f32 v16, vcc, v86, v17, v86
	v_mul_f32_e32 v20, v16, v19
	v_fma_f32 v21, -v18, v20, v16
	v_fmac_f32_e32 v20, v21, v19
	v_fma_f32 v16, -v18, v20, v16
	v_mul_f32_e32 v18, 0xbfb8aa3b, v87
	v_exp_f32_e32 v18, v18
	v_div_fmas_f32 v16, v16, v19, v20
	v_div_fixup_f32 v16, v16, v17, v86
	v_mul_f32_e32 v16, v22, v16
	v_add_f32_e32 v17, 1.0, v18
	v_div_scale_f32 v18, s[0:1], v17, v17, v87
	v_rcp_f32_e32 v19, v18
	s_nop 0
	v_cvt_pk_bf16_f32 v16, v16, s0
	ds_write_b16 v64, v16 offset:11424
	v_fma_f32 v16, -v18, v19, 1.0
	v_fmac_f32_e32 v19, v16, v19
	v_div_scale_f32 v16, vcc, v87, v17, v87
	v_mul_f32_e32 v20, v16, v19
	v_fma_f32 v21, -v18, v20, v16
	v_fmac_f32_e32 v20, v21, v19
	v_fma_f32 v16, -v18, v20, v16
	v_mul_f32_e32 v18, 0xbfb8aa3b, v88
	v_exp_f32_e32 v18, v18
	v_div_fmas_f32 v16, v16, v19, v20
	v_div_fixup_f32 v16, v16, v17, v87
	v_mul_f32_e32 v16, v23, v16
	v_add_f32_e32 v17, 1.0, v18
; DEV u16 f2bf(float f) { return (u16)(pk2bf(f, 0.f) & 0xffffu); }
; DEV float siluf_(float x) { return x / (1.0f + __expf(-x)); }
; template <int MI>
; DEV void p4_tile(const Params& p, int l, int m0, int nt, unsigned char* smem) {
;     ...
;         acc_foreach_t<MI>([&](int mi, int ni, int r, int row, int col) __attribute__((always_inline)) {
;           sC[row * LDC + col] = f2bf(att[mi][ni][r] * siluf_(acc[mi][ni][r]));
;         });
	v_div_scale_f32 v18, s[0:1], v17, v17, v88
	v_rcp_f32_e32 v19, v18
	s_nop 0
	v_cvt_pk_bf16_f32 v16, v16, s0
	ds_write_b16 v64, v16 offset:11696
	v_fma_f32 v16, -v18, v19, 1.0
	v_fmac_f32_e32 v19, v16, v19
	v_div_scale_f32 v16, vcc, v88, v17, v88
	v_mul_f32_e32 v20, v16, v19
	v_fma_f32 v21, -v18, v20, v16
	v_fmac_f32_e32 v20, v21, v19
	v_fma_f32 v16, -v18, v20, v16
	v_mul_f32_e32 v18, 0xbfb8aa3b, v89
	v_exp_f32_e32 v18, v18
	v_div_fmas_f32 v16, v16, v19, v20
	v_div_fixup_f32 v16, v16, v17, v88
	v_mul_f32_e32 v16, v24, v16
	v_add_f32_e32 v17, 1.0, v18
	v_div_scale_f32 v18, s[0:1], v17, v17, v89
	v_rcp_f32_e32 v19, v18
	s_nop 0
	v_cvt_pk_bf16_f32 v16, v16, s0
	ds_write_b16 v64, v16 offset:13056
	v_fma_f32 v16, -v18, v19, 1.0
	v_fmac_f32_e32 v19, v16, v19
	v_div_scale_f32 v16, vcc, v89, v17, v89
	v_mul_f32_e32 v20, v16, v19
	v_fma_f32 v21, -v18, v20, v16
	v_fmac_f32_e32 v20, v21, v19
	v_fma_f32 v16, -v18, v20, v16
	v_mul_f32_e32 v18, 0xbfb8aa3b, v90
	v_exp_f32_e32 v18, v18
	v_div_fmas_f32 v16, v16, v19, v20
	v_div_fixup_f32 v16, v16, v17, v89
	v_mul_f32_e32 v16, v25, v16
	v_add_f32_e32 v17, 1.0, v18
	v_div_scale_f32 v18, s[0:1], v17, v17, v90
	v_rcp_f32_e32 v19, v18
	s_nop 0
	v_cvt_pk_bf16_f32 v16, v16, s0
	ds_write_b16 v64, v16 offset:13328
	v_fma_f32 v16, -v18, v19, 1.0
	v_fmac_f32_e32 v19, v16, v19
	v_div_scale_f32 v16, vcc, v90, v17, v90
	v_mul_f32_e32 v20, v16, v19
	v_fma_f32 v21, -v18, v20, v16
	v_fmac_f32_e32 v20, v21, v19
	v_fma_f32 v16, -v18, v20, v16
	v_mul_f32_e32 v18, 0xbfb8aa3b, v91
	v_exp_f32_e32 v18, v18
	v_div_fmas_f32 v16, v16, v19, v20
	v_div_fixup_f32 v16, v16, v17, v90
	v_mul_f32_e32 v16, v26, v16
	v_add_f32_e32 v17, 1.0, v18
	v_div_scale_f32 v18, s[0:1], v17, v17, v91
	v_rcp_f32_e32 v19, v18
	s_nop 0
	v_cvt_pk_bf16_f32 v16, v16, s0
	ds_write_b16 v64, v16 offset:13600
	v_fma_f32 v16, -v18, v19, 1.0
	v_fmac_f32_e32 v19, v16, v19
	v_div_scale_f32 v16, vcc, v91, v17, v91
	v_mul_f32_e32 v20, v16, v19
	v_fma_f32 v21, -v18, v20, v16
	v_fmac_f32_e32 v20, v21, v19
	v_fma_f32 v16, -v18, v20, v16
	v_mul_f32_e32 v18, 0xbfb8aa3b, v92
	v_exp_f32_e32 v18, v18
	v_div_fmas_f32 v16, v16, v19, v20
	v_div_fixup_f32 v16, v16, v17, v91
	v_mul_f32_e32 v16, v27, v16
	v_add_f32_e32 v17, 1.0, v18
	v_div_scale_f32 v18, s[0:1], v17, v17, v92
	v_rcp_f32_e32 v19, v18
	s_nop 0
	v_cvt_pk_bf16_f32 v16, v16, s0
	ds_write_b16 v64, v16 offset:13872
	v_fma_f32 v16, -v18, v19, 1.0
	v_fmac_f32_e32 v19, v16, v19
	v_div_scale_f32 v16, vcc, v92, v17, v92
	v_mul_f32_e32 v20, v16, v19
	v_fma_f32 v21, -v18, v20, v16
	v_fmac_f32_e32 v20, v21, v19
	v_fma_f32 v16, -v18, v20, v16
	v_mul_f32_e32 v18, 0xbfb8aa3b, v93
	v_exp_f32_e32 v18, v18
	v_div_fmas_f32 v16, v16, v19, v20
	v_div_fixup_f32 v16, v16, v17, v92
	v_mul_f32_e32 v16, v28, v16
	v_add_f32_e32 v17, 1.0, v18
	v_div_scale_f32 v18, s[0:1], v17, v17, v93
	v_rcp_f32_e32 v19, v18
	s_nop 0
	v_cvt_pk_bf16_f32 v16, v16, s0
	ds_write_b16 v64, v16 offset:15232
	v_fma_f32 v16, -v18, v19, 1.0
	v_fmac_f32_e32 v19, v16, v19
	v_div_scale_f32 v16, vcc, v93, v17, v93
	v_mul_f32_e32 v20, v16, v19
	v_fma_f32 v21, -v18, v20, v16
	v_fmac_f32_e32 v20, v21, v19
	v_fma_f32 v16, -v18, v20, v16
	v_mul_f32_e32 v18, 0xbfb8aa3b, v94
	v_exp_f32_e32 v18, v18
	v_div_fmas_f32 v16, v16, v19, v20
	v_div_fixup_f32 v16, v16, v17, v93
	v_mul_f32_e32 v16, v29, v16
	v_add_f32_e32 v17, 1.0, v18
	v_div_scale_f32 v18, s[0:1], v17, v17, v94
	v_rcp_f32_e32 v19, v18
	s_nop 0
	v_cvt_pk_bf16_f32 v16, v16, s0
	ds_write_b16 v64, v16 offset:15504
	v_fma_f32 v16, -v18, v19, 1.0
	v_fmac_f32_e32 v19, v16, v19
	v_div_scale_f32 v16, vcc, v94, v17, v94
	v_mul_f32_e32 v20, v16, v19
	v_fma_f32 v21, -v18, v20, v16
	v_fmac_f32_e32 v20, v21, v19
	v_fma_f32 v16, -v18, v20, v16
	v_mul_f32_e32 v18, 0xbfb8aa3b, v95
	v_exp_f32_e32 v18, v18
	v_div_fmas_f32 v16, v16, v19, v20
	v_div_fixup_f32 v16, v16, v17, v94
	v_mul_f32_e32 v16, v30, v16
	v_add_f32_e32 v17, 1.0, v18
	v_div_scale_f32 v18, s[0:1], v17, v17, v95
	v_rcp_f32_e32 v19, v18
	s_nop 0
	v_cvt_pk_bf16_f32 v16, v16, s0
	ds_write_b16 v64, v16 offset:15776
	v_fma_f32 v16, -v18, v19, 1.0
	v_fmac_f32_e32 v19, v16, v19
	v_div_scale_f32 v16, vcc, v95, v17, v95
	v_mul_f32_e32 v20, v16, v19
	v_fma_f32 v21, -v18, v20, v16
	v_fmac_f32_e32 v20, v21, v19
	v_fma_f32 v16, -v18, v20, v16
	v_mul_f32_e32 v18, 0xbfb8aa3b, v48
	v_exp_f32_e32 v18, v18
	v_div_fmas_f32 v16, v16, v19, v20
	v_div_fixup_f32 v16, v16, v17, v95
	v_mul_f32_e32 v16, v31, v16
	v_add_f32_e32 v17, 1.0, v18
	v_div_scale_f32 v18, s[0:1], v17, v17, v48
	v_rcp_f32_e32 v19, v18
	s_nop 0
	v_cvt_pk_bf16_f32 v16, v16, s0
	ds_write_b16 v64, v16 offset:16048
	v_fma_f32 v16, -v18, v19, 1.0
	v_fmac_f32_e32 v19, v16, v19
	v_div_scale_f32 v16, vcc, v48, v17, v48
	v_mul_f32_e32 v20, v16, v19
	v_fma_f32 v21, -v18, v20, v16
	v_fmac_f32_e32 v20, v21, v19
	v_fma_f32 v16, -v18, v20, v16
	v_mul_f32_e32 v18, 0xbfb8aa3b, v49
	v_exp_f32_e32 v18, v18
	v_div_fmas_f32 v16, v16, v19, v20
	v_div_fixup_f32 v16, v16, v17, v48
	v_mul_f32_e32 v0, v0, v16
	v_add_f32_e32 v17, 1.0, v18
	v_div_scale_f32 v18, s[0:1], v17, v17, v49
	v_rcp_f32_e32 v19, v18
	s_nop 0
	v_cvt_pk_bf16_f32 v0, v0, s0
	ds_write_b16 v64, v0 offset:8768
	v_fma_f32 v0, -v18, v19, 1.0
	v_fmac_f32_e32 v19, v0, v19
	v_div_scale_f32 v0, vcc, v49, v17, v49
	v_mul_f32_e32 v16, v0, v19
	v_fma_f32 v20, -v18, v16, v0
	v_fmac_f32_e32 v16, v20, v19
	v_fma_f32 v0, -v18, v16, v0
	v_mul_f32_e32 v18, 0xbfb8aa3b, v50
	v_exp_f32_e32 v18, v18
	v_div_fmas_f32 v0, v0, v19, v16
	v_div_fixup_f32 v0, v0, v17, v49
	v_mul_f32_e32 v0, v1, v0
	v_add_f32_e32 v16, 1.0, v18
	v_div_scale_f32 v17, s[0:1], v16, v16, v50
	v_rcp_f32_e32 v18, v17
	s_nop 0
; DEV u16 f2bf(float f) { return (u16)(pk2bf(f, 0.f) & 0xffffu); }
; DEV float siluf_(float x) { return x / (1.0f + __expf(-x)); }
; template <int MI>
; DEV void p4_tile(const Params& p, int l, int m0, int nt, unsigned char* smem) {
;     ...
;         acc_foreach_t<MI>([&](int mi, int ni, int r, int row, int col) __attribute__((always_inline)) {
;           sC[row * LDC + col] = f2bf(att[mi][ni][r] * siluf_(acc[mi][ni][r]));
;         });
	v_cvt_pk_bf16_f32 v0, v0, s0
	ds_write_b16 v64, v0 offset:9040
	v_fma_f32 v0, -v17, v18, 1.0
	v_fmac_f32_e32 v18, v0, v18
	v_div_scale_f32 v0, vcc, v50, v16, v50
	v_mul_f32_e32 v1, v0, v18
	v_fma_f32 v19, -v17, v1, v0
	v_fmac_f32_e32 v1, v19, v18
	v_fma_f32 v0, -v17, v1, v0
	v_mul_f32_e32 v17, 0xbfb8aa3b, v51
	v_exp_f32_e32 v17, v17
	v_div_fmas_f32 v0, v0, v18, v1
	v_div_fixup_f32 v0, v0, v16, v50
	v_mul_f32_e32 v0, v2, v0
	v_add_f32_e32 v1, 1.0, v17
	v_div_scale_f32 v16, s[0:1], v1, v1, v51
	v_rcp_f32_e32 v17, v16
	s_nop 0
	v_cvt_pk_bf16_f32 v0, v0, s0
	ds_write_b16 v64, v0 offset:9312
	v_fma_f32 v0, -v16, v17, 1.0
	v_fmac_f32_e32 v17, v0, v17
	v_div_scale_f32 v0, vcc, v51, v1, v51
	v_mul_f32_e32 v2, v0, v17
	v_fma_f32 v18, -v16, v2, v0
	v_fmac_f32_e32 v2, v18, v17
	v_fma_f32 v0, -v16, v2, v0
	v_mul_f32_e32 v16, 0xbfb8aa3b, v52
	v_exp_f32_e32 v16, v16
	v_div_fmas_f32 v0, v0, v17, v2
	v_div_fixup_f32 v0, v0, v1, v51
	v_mul_f32_e32 v0, v3, v0
	v_add_f32_e32 v1, 1.0, v16
	v_div_scale_f32 v2, s[0:1], v1, v1, v52
	v_rcp_f32_e32 v16, v2
	s_nop 0
	v_cvt_pk_bf16_f32 v0, v0, s0
	ds_write_b16 v64, v0 offset:9584
	v_fma_f32 v0, -v2, v16, 1.0
	v_fmac_f32_e32 v16, v0, v16
	v_div_scale_f32 v0, vcc, v52, v1, v52
	v_mul_f32_e32 v3, v0, v16
	v_fma_f32 v17, -v2, v3, v0
	v_fmac_f32_e32 v3, v17, v16
	v_fma_f32 v0, -v2, v3, v0
	v_mul_f32_e32 v2, 0xbfb8aa3b, v53
	v_exp_f32_e32 v2, v2
	v_div_fmas_f32 v0, v0, v16, v3
	v_div_fixup_f32 v0, v0, v1, v52
	v_mul_f32_e32 v0, v4, v0
	v_add_f32_e32 v1, 1.0, v2
	v_div_scale_f32 v2, s[0:1], v1, v1, v53
	v_rcp_f32_e32 v3, v2
	s_nop 0
	v_cvt_pk_bf16_f32 v0, v0, s0
	ds_write_b16 v64, v0 offset:10944
	v_fma_f32 v0, -v2, v3, 1.0
	v_fmac_f32_e32 v3, v0, v3
	v_div_scale_f32 v0, vcc, v53, v1, v53
	v_mul_f32_e32 v4, v0, v3
	v_fma_f32 v16, -v2, v4, v0
	v_fmac_f32_e32 v4, v16, v3
	v_fma_f32 v0, -v2, v4, v0
	v_mul_f32_e32 v2, 0xbfb8aa3b, v54
	v_exp_f32_e32 v2, v2
	v_div_fmas_f32 v0, v0, v3, v4
	v_div_fixup_f32 v0, v0, v1, v53
	v_mul_f32_e32 v0, v5, v0
	v_add_f32_e32 v1, 1.0, v2
	v_div_scale_f32 v2, s[0:1], v1, v1, v54
	v_rcp_f32_e32 v3, v2
	s_nop 0
	v_cvt_pk_bf16_f32 v0, v0, s0
	ds_write_b16 v64, v0 offset:11216
	v_fma_f32 v0, -v2, v3, 1.0
	v_fmac_f32_e32 v3, v0, v3
	v_div_scale_f32 v0, vcc, v54, v1, v54
	v_mul_f32_e32 v4, v0, v3
	v_fma_f32 v5, -v2, v4, v0
	v_fmac_f32_e32 v4, v5, v3
	v_fma_f32 v0, -v2, v4, v0
	v_mul_f32_e32 v2, 0xbfb8aa3b, v55
	v_exp_f32_e32 v2, v2
	v_div_fmas_f32 v0, v0, v3, v4
	v_div_fixup_f32 v0, v0, v1, v54
	v_mul_f32_e32 v0, v6, v0
	v_add_f32_e32 v1, 1.0, v2
	v_div_scale_f32 v2, s[0:1], v1, v1, v55
	v_rcp_f32_e32 v3, v2
	s_nop 0
	v_cvt_pk_bf16_f32 v0, v0, s0
	ds_write_b16 v64, v0 offset:11488
	v_fma_f32 v0, -v2, v3, 1.0
	v_fmac_f32_e32 v3, v0, v3
	v_div_scale_f32 v0, vcc, v55, v1, v55
	v_mul_f32_e32 v4, v0, v3
	v_fma_f32 v5, -v2, v4, v0
	v_fmac_f32_e32 v4, v5, v3
	v_fma_f32 v0, -v2, v4, v0
	v_mul_f32_e32 v2, 0xbfb8aa3b, v56
	v_exp_f32_e32 v2, v2
	v_div_fmas_f32 v0, v0, v3, v4
	v_div_fixup_f32 v0, v0, v1, v55
	v_mul_f32_e32 v0, v7, v0
	v_add_f32_e32 v1, 1.0, v2
	v_div_scale_f32 v2, s[0:1], v1, v1, v56
	v_rcp_f32_e32 v3, v2
	s_nop 0
	v_cvt_pk_bf16_f32 v0, v0, s0
	ds_write_b16 v64, v0 offset:11760
	v_fma_f32 v0, -v2, v3, 1.0
	v_fmac_f32_e32 v3, v0, v3
	v_div_scale_f32 v0, vcc, v56, v1, v56
	v_mul_f32_e32 v4, v0, v3
	v_fma_f32 v5, -v2, v4, v0
	v_fmac_f32_e32 v4, v5, v3
	v_fma_f32 v0, -v2, v4, v0
	v_mul_f32_e32 v2, 0xbfb8aa3b, v57
	v_exp_f32_e32 v2, v2
	v_div_fmas_f32 v0, v0, v3, v4
	v_div_fixup_f32 v0, v0, v1, v56
	v_mul_f32_e32 v0, v8, v0
	v_add_f32_e32 v1, 1.0, v2
	v_div_scale_f32 v2, s[0:1], v1, v1, v57
	v_rcp_f32_e32 v3, v2
	s_nop 0
	v_cvt_pk_bf16_f32 v0, v0, s0
; DEV u16 f2bf(float f) { return (u16)(pk2bf(f, 0.f) & 0xffffu); }
; DEV float siluf_(float x) { return x / (1.0f + __expf(-x)); }
; template <int MI>
; DEV void p4_tile(const Params& p, int l, int m0, int nt, unsigned char* smem) {
;     ...
;         acc_foreach_t<MI>([&](int mi, int ni, int r, int row, int col) __attribute__((always_inline)) {
;           sC[row * LDC + col] = f2bf(att[mi][ni][r] * siluf_(acc[mi][ni][r]));
;         });
;         tile_store_t<MI>(smem, YB + (size_t)m0 * 1024 + nt * 128, 1024);
	ds_write_b16 v64, v0 offset:13120
	v_fma_f32 v0, -v2, v3, 1.0
	v_fmac_f32_e32 v3, v0, v3
	v_div_scale_f32 v0, vcc, v57, v1, v57
	v_mul_f32_e32 v4, v0, v3
	v_fma_f32 v5, -v2, v4, v0
	v_fmac_f32_e32 v4, v5, v3
	v_fma_f32 v0, -v2, v4, v0
	v_mul_f32_e32 v2, 0xbfb8aa3b, v58
	v_exp_f32_e32 v2, v2
	v_div_fmas_f32 v0, v0, v3, v4
	v_div_fixup_f32 v0, v0, v1, v57
	v_mul_f32_e32 v0, v9, v0
	v_add_f32_e32 v1, 1.0, v2
	v_div_scale_f32 v2, s[0:1], v1, v1, v58
	v_rcp_f32_e32 v3, v2
	s_nop 0
	v_cvt_pk_bf16_f32 v0, v0, s0
	ds_write_b16 v64, v0 offset:13392
	v_fma_f32 v0, -v2, v3, 1.0
	v_fmac_f32_e32 v3, v0, v3
	v_div_scale_f32 v0, vcc, v58, v1, v58
	v_mul_f32_e32 v4, v0, v3
	v_fma_f32 v5, -v2, v4, v0
	v_fmac_f32_e32 v4, v5, v3
	v_fma_f32 v0, -v2, v4, v0
	v_mul_f32_e32 v2, 0xbfb8aa3b, v59
	v_exp_f32_e32 v2, v2
	v_div_fmas_f32 v0, v0, v3, v4
	v_div_fixup_f32 v0, v0, v1, v58
	v_mul_f32_e32 v0, v10, v0
	v_add_f32_e32 v1, 1.0, v2
	v_div_scale_f32 v2, s[0:1], v1, v1, v59
	v_rcp_f32_e32 v3, v2
	s_nop 0
	v_cvt_pk_bf16_f32 v0, v0, s0
	ds_write_b16 v64, v0 offset:13664
	v_fma_f32 v0, -v2, v3, 1.0
	v_fmac_f32_e32 v3, v0, v3
	v_div_scale_f32 v0, vcc, v59, v1, v59
	v_mul_f32_e32 v4, v0, v3
	v_fma_f32 v5, -v2, v4, v0
	v_fmac_f32_e32 v4, v5, v3
	v_fma_f32 v0, -v2, v4, v0
	v_mul_f32_e32 v2, 0xbfb8aa3b, v60
	v_exp_f32_e32 v2, v2
	v_div_fmas_f32 v0, v0, v3, v4
	v_div_fixup_f32 v0, v0, v1, v59
	v_mul_f32_e32 v0, v11, v0
	v_add_f32_e32 v1, 1.0, v2
	v_div_scale_f32 v2, s[0:1], v1, v1, v60
	v_rcp_f32_e32 v3, v2
	s_nop 0
	v_cvt_pk_bf16_f32 v0, v0, s0
	ds_write_b16 v64, v0 offset:13936
	v_fma_f32 v0, -v2, v3, 1.0
	v_fmac_f32_e32 v3, v0, v3
	v_div_scale_f32 v0, vcc, v60, v1, v60
	v_mul_f32_e32 v4, v0, v3
	v_fma_f32 v5, -v2, v4, v0
	v_fmac_f32_e32 v4, v5, v3
	v_fma_f32 v0, -v2, v4, v0
	v_mul_f32_e32 v2, 0xbfb8aa3b, v61
	v_exp_f32_e32 v2, v2
	v_div_fmas_f32 v0, v0, v3, v4
	v_div_fixup_f32 v0, v0, v1, v60
	v_mul_f32_e32 v0, v12, v0
	v_add_f32_e32 v1, 1.0, v2
	v_div_scale_f32 v2, s[0:1], v1, v1, v61
	v_rcp_f32_e32 v3, v2
	s_nop 0
	v_cvt_pk_bf16_f32 v0, v0, s0
	ds_write_b16 v64, v0 offset:15296
	v_fma_f32 v0, -v2, v3, 1.0
	v_fmac_f32_e32 v3, v0, v3
	v_div_scale_f32 v0, vcc, v61, v1, v61
	v_mul_f32_e32 v4, v0, v3
	v_fma_f32 v5, -v2, v4, v0
	v_fmac_f32_e32 v4, v5, v3
	v_fma_f32 v0, -v2, v4, v0
	v_mul_f32_e32 v2, 0xbfb8aa3b, v62
	v_exp_f32_e32 v2, v2
	v_div_fmas_f32 v0, v0, v3, v4
	v_div_fixup_f32 v0, v0, v1, v61
	v_mul_f32_e32 v0, v13, v0
	v_add_f32_e32 v1, 1.0, v2
	v_div_scale_f32 v2, s[0:1], v1, v1, v62
	v_rcp_f32_e32 v3, v2
	s_nop 0
	v_cvt_pk_bf16_f32 v0, v0, s0
	ds_write_b16 v64, v0 offset:15568
	v_fma_f32 v0, -v2, v3, 1.0
	v_fmac_f32_e32 v3, v0, v3
	v_div_scale_f32 v0, vcc, v62, v1, v62
	v_mul_f32_e32 v4, v0, v3
	v_fma_f32 v5, -v2, v4, v0
	v_fmac_f32_e32 v4, v5, v3
	v_fma_f32 v0, -v2, v4, v0
	v_mul_f32_e32 v2, 0xbfb8aa3b, v63
	v_exp_f32_e32 v2, v2
	v_div_fmas_f32 v0, v0, v3, v4
	v_div_fixup_f32 v0, v0, v1, v62
	v_mul_f32_e32 v0, v14, v0
	v_add_f32_e32 v1, 1.0, v2
	v_div_scale_f32 v2, s[0:1], v1, v1, v63
	v_rcp_f32_e32 v3, v2
	s_nop 0
	v_cvt_pk_bf16_f32 v0, v0, s0
	ds_write_b16 v64, v0 offset:15840
	v_fma_f32 v0, -v2, v3, 1.0
	v_fmac_f32_e32 v3, v0, v3
	v_div_scale_f32 v0, vcc, v63, v1, v63
	v_mul_f32_e32 v4, v0, v3
	v_fma_f32 v5, -v2, v4, v0
	v_fmac_f32_e32 v4, v5, v3
	v_fma_f32 v0, -v2, v4, v0
	v_div_fmas_f32 v0, v0, v3, v4
	v_div_fixup_f32 v0, v0, v1, v63
	v_mul_f32_e32 v0, v15, v0
	v_cvt_pk_bf16_f32 v0, v0, s0
	s_lshl_b64 s[0:1], s[4:5], 1
	s_add_u32 s0, s17, s0
	s_addc_u32 s1, s18, s1
	s_lshl_b32 s4, s85, 8
	s_add_u32 s4, s0, s4
	ds_write_b16 v64, v0 offset:16112
	s_addc_u32 s5, s1, 0
	v_mov_b32_e32 v0, v232
	s_waitcnt lgkmcnt(0)
	s_barrier

; DEV u16 f2bf(float f) { return (u16)(pk2bf(f, 0.f) & 0xffffu); }
; DEV float bf2f(u16 h) { return __uint_as_float(((unsigned)h) << 16); }
; DEV float siluf_(float x) { return x / (1.0f + __expf(-x)); }
; template <int MI>
; DEV void tile_load_t(unsigned char* smem, const u16* src, size_t lds_) {
;   u16* sC = (u16*)smem;
;   const int tid_ = TIDX();
; #pragma unroll
;   for (int i = 0; i < MI * 4; ++i) {
;     const int c = tid_ + 256 * i, row = c >> 4, cc = (c & 15) * 8;
;     *(bf16x8*)(sC + row * LDC + cc) = __builtin_nontemporal_load((const bf16x8*)(src + (size_t)row * lds_ + cc));
;   }
;   __syncthreads();
; template <int MI>
; DEV void p4_tile(const Params& p, int l, int m0, int nt, unsigned char* smem) {
;     ...
;     tile_load_t<MI>(smem, YA + (size_t)m0 * 1024 + n0, 1024);
;     acc_foreach_t<MI>([&](int mi, int ni, int r, int row, int col) __attribute__((always_inline)) {
;       sC[row * LDC + col] = f2bf(bf2f(sC[row * LDC + col]) * siluf_(acc[mi][ni][r]));
;     });
.LBB0_1233:
	s_lshl_b64 s[4:5], s[4:5], 1
	s_add_u32 s1, s37, s4
	s_addc_u32 s6, s38, s5
	s_lshl_b64 s[4:5], s[96:97], 1
	s_waitcnt vmcnt(5)
	v_mov_b32_e32 v72, v232
	s_barrier
	s_add_u32 s4, s1, s4
	s_addc_u32 s5, s6, s5
	v_lshlrev_b32_e32 v64, 4, v72
	v_ashrrev_i32_e32 v70, 4, v72
	v_and_b32_e32 v224, 0xf0, v64
	v_ashrrev_i32_e32 v71, 31, v70
	v_lshl_add_u64 v[68:69], s[4:5], 0, v[224:225]
	v_lshlrev_b64 v[64:65], 11, v[70:71]
	v_lshl_add_u64 v[64:65], v[68:69], 0, v[64:65]
	global_load_dwordx4 v[64:67], v[64:65], off nt
	v_mad_u64_u32 v[70:71], s[6:7], v70, s42, v[224:225]
	s_waitcnt vmcnt(0)
	ds_write_b128 v70, v[64:67]
	v_add_u32_e32 v64, 0x100, v72
	v_ashrrev_i32_e32 v70, 4, v64
	v_ashrrev_i32_e32 v71, 31, v70
	v_lshlrev_b64 v[64:65], 11, v[70:71]
	v_lshl_add_u64 v[64:65], v[68:69], 0, v[64:65]
	global_load_dwordx4 v[64:67], v[64:65], off nt
	v_mad_u64_u32 v[70:71], s[6:7], v70, s42, v[224:225]
	s_waitcnt vmcnt(0)
	ds_write_b128 v70, v[64:67]
	v_add_u32_e32 v64, 0x200, v72
	v_ashrrev_i32_e32 v70, 4, v64
	v_ashrrev_i32_e32 v71, 31, v70
	v_lshlrev_b64 v[64:65], 11, v[70:71]
	v_lshl_add_u64 v[64:65], v[68:69], 0, v[64:65]
	global_load_dwordx4 v[64:67], v[64:65], off nt
	v_mad_u64_u32 v[70:71], s[6:7], v70, s42, v[224:225]
	s_waitcnt vmcnt(0)
	ds_write_b128 v70, v[64:67]
	v_add_u32_e32 v64, 0x300, v72
	v_ashrrev_i32_e32 v70, 4, v64
	v_ashrrev_i32_e32 v71, 31, v70
	v_lshlrev_b64 v[64:65], 11, v[70:71]
	v_lshl_add_u64 v[64:65], v[68:69], 0, v[64:65]
	global_load_dwordx4 v[64:67], v[64:65], off nt
	v_mad_u64_u32 v[70:71], s[6:7], v70, s42, v[224:225]
	s_waitcnt vmcnt(0)
	ds_write_b128 v70, v[64:67]
	v_add_u32_e32 v64, 0x400, v72
	v_ashrrev_i32_e32 v70, 4, v64
	v_ashrrev_i32_e32 v71, 31, v70
	v_lshlrev_b64 v[64:65], 11, v[70:71]
	v_lshl_add_u64 v[64:65], v[68:69], 0, v[64:65]
	global_load_dwordx4 v[64:67], v[64:65], off nt
	v_mad_u64_u32 v[70:71], s[6:7], v70, s42, v[224:225]
	s_waitcnt vmcnt(0)
	ds_write_b128 v70, v[64:67]
	v_add_u32_e32 v64, 0x500, v72
	v_ashrrev_i32_e32 v70, 4, v64
	v_ashrrev_i32_e32 v71, 31, v70
	v_lshlrev_b64 v[64:65], 11, v[70:71]
	v_lshl_add_u64 v[64:65], v[68:69], 0, v[64:65]
	global_load_dwordx4 v[64:67], v[64:65], off nt
	v_mad_u64_u32 v[70:71], s[6:7], v70, s42, v[224:225]
	s_waitcnt vmcnt(0)
	ds_write_b128 v70, v[64:67]
	v_add_u32_e32 v64, 0x600, v72
	v_ashrrev_i32_e32 v70, 4, v64
	v_ashrrev_i32_e32 v71, 31, v70
	v_lshlrev_b64 v[64:65], 11, v[70:71]
	v_lshl_add_u64 v[64:65], v[68:69], 0, v[64:65]
	global_load_dwordx4 v[64:67], v[64:65], off nt
	v_mad_u64_u32 v[70:71], s[6:7], v70, s42, v[224:225]
	s_waitcnt vmcnt(0)
	ds_write_b128 v70, v[64:67]
	v_add_u32_e32 v64, 0x700, v72
	v_ashrrev_i32_e32 v70, 4, v64
	v_ashrrev_i32_e32 v71, 31, v70
	v_lshlrev_b64 v[64:65], 11, v[70:71]
	v_lshl_add_u64 v[64:65], v[68:69], 0, v[64:65]
	global_load_dwordx4 v[64:67], v[64:65], off nt
	v_mad_u64_u32 v[68:69], s[6:7], v70, s42, v[224:225]
	s_waitcnt vmcnt(0)
	ds_write_b128 v68, v[64:67]
	v_mov_b32_e32 v64, v232
	s_waitcnt lgkmcnt(0)
	s_barrier
	s_nop 0
	v_lshrrev_b32_e32 v66, 3, v64
	v_lshrrev_b32_e32 v65, 1, v64
	v_and_b32_e32 v66, 4, v66
	v_and_or_b32 v65, v65, s72, v66
	v_mul_f32_e32 v66, 0xbfb8aa3b, v48
	v_exp_f32_e32 v66, v66
	v_and_b32_e32 v64, 0x5f, v64
	v_mul_lo_u32 v65, v65, s42
	v_lshl_add_u32 v64, v64, 1, v65
	v_add_f32_e32 v66, 1.0, v66
	ds_read_u16 v65, v64
	s_waitcnt lgkmcnt(0)
	v_lshlrev_b32_e32 v65, 16, v65
	v_rcp_f32_e32 v67, v66
	s_nop 0
	v_mul_f32_e32 v48, v48, v67
	v_mul_f32_e32 v48, v48, v65
	v_mul_f32_e32 v65, 0xbfb8aa3b, v49
	v_exp_f32_e32 v65, v65
	v_cvt_pk_bf16_f32 v48, v48, s0
	ds_write_b16 v64, v48
	ds_read_u16 v48, v64 offset:272
	v_add_f32_e32 v65, 1.0, v65
	s_waitcnt lgkmcnt(0)
	v_lshlrev_b32_e32 v48, 16, v48
	v_rcp_f32_e32 v66, v65
	s_nop 0
	v_mul_f32_e32 v49, v49, v66
	v_mul_f32_e32 v48, v49, v48
	v_mul_f32_e32 v49, 0xbfb8aa3b, v50
	v_exp_f32_e32 v49, v49
	v_cvt_pk_bf16_f32 v48, v48, s0
	ds_write_b16 v64, v48 offset:272
	ds_read_u16 v48, v64 offset:544
	v_add_f32_e32 v49, 1.0, v49
	s_waitcnt lgkmcnt(0)
	v_lshlrev_b32_e32 v48, 16, v48
	v_rcp_f32_e32 v65, v49
	s_nop 0
	v_mul_f32_e32 v49, v50, v65
	v_mul_f32_e32 v48, v49, v48
	v_mul_f32_e32 v49, 0xbfb8aa3b, v51
	v_exp_f32_e32 v49, v49
	v_cvt_pk_bf16_f32 v48, v48, s0
	ds_write_b16 v64, v48 offset:544
	ds_read_u16 v48, v64 offset:816
	v_add_f32_e32 v49, 1.0, v49
	s_waitcnt lgkmcnt(0)
	v_lshlrev_b32_e32 v48, 16, v48
	v_rcp_f32_e32 v50, v49
	s_nop 0
	v_mul_f32_e32 v49, v51, v50
	v_mul_f32_e32 v48, v49, v48
	v_mul_f32_e32 v49, 0xbfb8aa3b, v52
	v_exp_f32_e32 v49, v49
	v_cvt_pk_bf16_f32 v48, v48, s0
	ds_write_b16 v64, v48 offset:816
	ds_read_u16 v48, v64 offset:2176
	v_add_f32_e32 v49, 1.0, v49
	s_waitcnt lgkmcnt(0)
	v_lshlrev_b32_e32 v48, 16, v48
	v_rcp_f32_e32 v50, v49
	s_nop 0
	v_mul_f32_e32 v49, v52, v50
	v_mul_f32_e32 v48, v49, v48
	v_mul_f32_e32 v49, 0xbfb8aa3b, v53
	v_exp_f32_e32 v49, v49
	v_cvt_pk_bf16_f32 v48, v48, s0
	ds_write_b16 v64, v48 offset:2176
	ds_read_u16 v48, v64 offset:2448
	v_add_f32_e32 v49, 1.0, v49
	s_waitcnt lgkmcnt(0)
	v_lshlrev_b32_e32 v48, 16, v48
	v_rcp_f32_e32 v50, v49
	s_nop 0
	v_mul_f32_e32 v49, v53, v50
	v_mul_f32_e32 v48, v49, v48
	v_mul_f32_e32 v49, 0xbfb8aa3b, v54
	v_exp_f32_e32 v49, v49
	v_cvt_pk_bf16_f32 v48, v48, s0
	ds_write_b16 v64, v48 offset:2448
	ds_read_u16 v48, v64 offset:2720
	v_add_f32_e32 v49, 1.0, v49
	s_waitcnt lgkmcnt(0)
	v_lshlrev_b32_e32 v48, 16, v48
	v_rcp_f32_e32 v50, v49
	s_nop 0
	v_mul_f32_e32 v49, v54, v50
	v_mul_f32_e32 v48, v49, v48
	v_mul_f32_e32 v49, 0xbfb8aa3b, v55
	v_exp_f32_e32 v49, v49
	v_cvt_pk_bf16_f32 v48, v48, s0
	ds_write_b16 v64, v48 offset:2720
	ds_read_u16 v48, v64 offset:2992
	v_add_f32_e32 v49, 1.0, v49
	s_waitcnt lgkmcnt(0)
; DEV u16 f2bf(float f) { return (u16)(pk2bf(f, 0.f) & 0xffffu); }
; DEV float bf2f(u16 h) { return __uint_as_float(((unsigned)h) << 16); }
; DEV float siluf_(float x) { return x / (1.0f + __expf(-x)); }
; template <int MI>
; DEV void p4_tile(const Params& p, int l, int m0, int nt, unsigned char* smem) {
;     ...
;     acc_foreach_t<MI>([&](int mi, int ni, int r, int row, int col) __attribute__((always_inline)) {
;       sC[row * LDC + col] = f2bf(bf2f(sC[row * LDC + col]) * siluf_(acc[mi][ni][r]));
;     });
	v_lshlrev_b32_e32 v48, 16, v48
	v_rcp_f32_e32 v50, v49
	s_nop 0
	v_mul_f32_e32 v49, v55, v50
	v_mul_f32_e32 v48, v49, v48
	v_mul_f32_e32 v49, 0xbfb8aa3b, v56
	v_exp_f32_e32 v49, v49
	v_cvt_pk_bf16_f32 v48, v48, s0
	ds_write_b16 v64, v48 offset:2992
	ds_read_u16 v48, v64 offset:4352
	v_add_f32_e32 v49, 1.0, v49
	s_waitcnt lgkmcnt(0)
	v_lshlrev_b32_e32 v48, 16, v48
	v_rcp_f32_e32 v50, v49
	s_nop 0
	v_mul_f32_e32 v49, v56, v50
	v_mul_f32_e32 v48, v49, v48
	v_mul_f32_e32 v49, 0xbfb8aa3b, v57
	v_exp_f32_e32 v49, v49
	v_cvt_pk_bf16_f32 v48, v48, s0
	ds_write_b16 v64, v48 offset:4352
	ds_read_u16 v48, v64 offset:4624
	v_add_f32_e32 v49, 1.0, v49
	s_waitcnt lgkmcnt(0)
	v_lshlrev_b32_e32 v48, 16, v48
	v_rcp_f32_e32 v50, v49
	s_nop 0
	v_mul_f32_e32 v49, v57, v50
	v_mul_f32_e32 v48, v49, v48
	v_mul_f32_e32 v49, 0xbfb8aa3b, v58
	v_exp_f32_e32 v49, v49
	v_cvt_pk_bf16_f32 v48, v48, s0
	ds_write_b16 v64, v48 offset:4624
	ds_read_u16 v48, v64 offset:4896
	v_add_f32_e32 v49, 1.0, v49
	s_waitcnt lgkmcnt(0)
	v_lshlrev_b32_e32 v48, 16, v48
	v_rcp_f32_e32 v50, v49
	s_nop 0
	v_mul_f32_e32 v49, v58, v50
	v_mul_f32_e32 v48, v49, v48
	v_mul_f32_e32 v49, 0xbfb8aa3b, v59
	v_exp_f32_e32 v49, v49
	v_cvt_pk_bf16_f32 v48, v48, s0
	ds_write_b16 v64, v48 offset:4896
	ds_read_u16 v48, v64 offset:5168
	v_add_f32_e32 v49, 1.0, v49
	s_waitcnt lgkmcnt(0)
	v_lshlrev_b32_e32 v48, 16, v48
	v_rcp_f32_e32 v50, v49
	s_nop 0
	v_mul_f32_e32 v49, v59, v50
	v_mul_f32_e32 v48, v49, v48
	v_mul_f32_e32 v49, 0xbfb8aa3b, v60
	v_exp_f32_e32 v49, v49
	v_cvt_pk_bf16_f32 v48, v48, s0
	ds_write_b16 v64, v48 offset:5168
	ds_read_u16 v48, v64 offset:6528
	v_add_f32_e32 v49, 1.0, v49
	s_waitcnt lgkmcnt(0)
	v_lshlrev_b32_e32 v48, 16, v48
	v_rcp_f32_e32 v50, v49
	s_nop 0
	v_mul_f32_e32 v49, v60, v50
	v_mul_f32_e32 v48, v49, v48
	v_mul_f32_e32 v49, 0xbfb8aa3b, v61
	v_exp_f32_e32 v49, v49
	v_cvt_pk_bf16_f32 v48, v48, s0
	ds_write_b16 v64, v48 offset:6528
	ds_read_u16 v48, v64 offset:6800
	v_add_f32_e32 v49, 1.0, v49
	s_waitcnt lgkmcnt(0)
	v_lshlrev_b32_e32 v48, 16, v48
	v_rcp_f32_e32 v50, v49
	s_nop 0
	v_mul_f32_e32 v49, v61, v50
	v_mul_f32_e32 v48, v49, v48
	v_mul_f32_e32 v49, 0xbfb8aa3b, v62
	v_exp_f32_e32 v49, v49
	v_cvt_pk_bf16_f32 v48, v48, s0
	ds_write_b16 v64, v48 offset:6800
	ds_read_u16 v48, v64 offset:7072
	v_add_f32_e32 v49, 1.0, v49
	s_waitcnt lgkmcnt(0)
	v_lshlrev_b32_e32 v48, 16, v48
	v_rcp_f32_e32 v50, v49
	s_nop 0
	v_mul_f32_e32 v49, v62, v50
	v_mul_f32_e32 v48, v49, v48
	v_mul_f32_e32 v49, 0xbfb8aa3b, v63
	v_exp_f32_e32 v49, v49
	v_cvt_pk_bf16_f32 v48, v48, s0
	ds_write_b16 v64, v48 offset:7072
	ds_read_u16 v48, v64 offset:7344
	v_add_f32_e32 v49, 1.0, v49
	s_waitcnt lgkmcnt(0)
	v_lshlrev_b32_e32 v48, 16, v48
	v_rcp_f32_e32 v50, v49
	s_nop 0
	v_mul_f32_e32 v49, v63, v50
	v_mul_f32_e32 v48, v49, v48
	v_mul_f32_e32 v49, 0xbfb8aa3b, v32
	v_exp_f32_e32 v49, v49
	v_cvt_pk_bf16_f32 v48, v48, s0
	ds_write_b16 v64, v48 offset:7344
	ds_read_u16 v48, v64 offset:64
	v_add_f32_e32 v49, 1.0, v49
	s_waitcnt lgkmcnt(0)
	v_lshlrev_b32_e32 v48, 16, v48
	v_rcp_f32_e32 v50, v49
	s_nop 0
	v_mul_f32_e32 v32, v32, v50
	v_mul_f32_e32 v32, v32, v48
	v_mul_f32_e32 v48, 0xbfb8aa3b, v33
	v_exp_f32_e32 v48, v48
	v_cvt_pk_bf16_f32 v32, v32, s0
	ds_write_b16 v64, v32 offset:64
	ds_read_u16 v32, v64 offset:336
	v_add_f32_e32 v48, 1.0, v48
	s_waitcnt lgkmcnt(0)
	v_lshlrev_b32_e32 v32, 16, v32
	v_rcp_f32_e32 v49, v48
	s_nop 0
	v_mul_f32_e32 v33, v33, v49
	v_mul_f32_e32 v32, v33, v32
	v_mul_f32_e32 v33, 0xbfb8aa3b, v34
	v_exp_f32_e32 v33, v33
	v_cvt_pk_bf16_f32 v32, v32, s0
	ds_write_b16 v64, v32 offset:336
	ds_read_u16 v32, v64 offset:608
	v_add_f32_e32 v33, 1.0, v33
	s_waitcnt lgkmcnt(0)
	v_lshlrev_b32_e32 v32, 16, v32
	v_rcp_f32_e32 v48, v33
	s_nop 0
	v_mul_f32_e32 v33, v34, v48
	v_mul_f32_e32 v32, v33, v32
	v_mul_f32_e32 v33, 0xbfb8aa3b, v35
	v_exp_f32_e32 v33, v33
	v_cvt_pk_bf16_f32 v32, v32, s0
	ds_write_b16 v64, v32 offset:608
	ds_read_u16 v32, v64 offset:880
	v_add_f32_e32 v33, 1.0, v33
	s_waitcnt lgkmcnt(0)
	v_lshlrev_b32_e32 v32, 16, v32
	v_rcp_f32_e32 v34, v33
	s_nop 0
	v_mul_f32_e32 v33, v35, v34
	v_mul_f32_e32 v32, v33, v32
	v_mul_f32_e32 v33, 0xbfb8aa3b, v36
	v_exp_f32_e32 v33, v33
	v_cvt_pk_bf16_f32 v32, v32, s0
	ds_write_b16 v64, v32 offset:880
	ds_read_u16 v32, v64 offset:2240
	v_add_f32_e32 v33, 1.0, v33
	s_waitcnt lgkmcnt(0)
	v_lshlrev_b32_e32 v32, 16, v32
	v_rcp_f32_e32 v34, v33
	s_nop 0
	v_mul_f32_e32 v33, v36, v34
	v_mul_f32_e32 v32, v33, v32
	v_mul_f32_e32 v33, 0xbfb8aa3b, v37
	v_exp_f32_e32 v33, v33
	v_cvt_pk_bf16_f32 v32, v32, s0
	ds_write_b16 v64, v32 offset:2240
	ds_read_u16 v32, v64 offset:2512
	v_add_f32_e32 v33, 1.0, v33
	s_waitcnt lgkmcnt(0)
	v_lshlrev_b32_e32 v32, 16, v32
	v_rcp_f32_e32 v34, v33
	s_nop 0
	v_mul_f32_e32 v33, v37, v34
	v_mul_f32_e32 v32, v33, v32
	v_mul_f32_e32 v33, 0xbfb8aa3b, v38
	v_exp_f32_e32 v33, v33
	v_cvt_pk_bf16_f32 v32, v32, s0
	ds_write_b16 v64, v32 offset:2512
	ds_read_u16 v32, v64 offset:2784
	v_add_f32_e32 v33, 1.0, v33
	s_waitcnt lgkmcnt(0)
	v_lshlrev_b32_e32 v32, 16, v32
	v_rcp_f32_e32 v34, v33
	s_nop 0
	v_mul_f32_e32 v33, v38, v34
	v_mul_f32_e32 v32, v33, v32
	v_mul_f32_e32 v33, 0xbfb8aa3b, v39
	v_exp_f32_e32 v33, v33
	v_cvt_pk_bf16_f32 v32, v32, s0
	ds_write_b16 v64, v32 offset:2784
	ds_read_u16 v32, v64 offset:3056
	v_add_f32_e32 v33, 1.0, v33
	s_waitcnt lgkmcnt(0)
	v_lshlrev_b32_e32 v32, 16, v32
	v_rcp_f32_e32 v34, v33
	s_nop 0
	v_mul_f32_e32 v33, v39, v34
	v_mul_f32_e32 v32, v33, v32
	v_mul_f32_e32 v33, 0xbfb8aa3b, v40
	v_exp_f32_e32 v33, v33
	v_cvt_pk_bf16_f32 v32, v32, s0
	ds_write_b16 v64, v32 offset:3056
	ds_read_u16 v32, v64 offset:4416
	v_add_f32_e32 v33, 1.0, v33
	s_waitcnt lgkmcnt(0)
; DEV u16 f2bf(float f) { return (u16)(pk2bf(f, 0.f) & 0xffffu); }
; DEV float bf2f(u16 h) { return __uint_as_float(((unsigned)h) << 16); }
; DEV float siluf_(float x) { return x / (1.0f + __expf(-x)); }
; template <int MI>
; DEV void p4_tile(const Params& p, int l, int m0, int nt, unsigned char* smem) {
;     ...
;     acc_foreach_t<MI>([&](int mi, int ni, int r, int row, int col) __attribute__((always_inline)) {
;       sC[row * LDC + col] = f2bf(bf2f(sC[row * LDC + col]) * siluf_(acc[mi][ni][r]));
;     });
	v_lshlrev_b32_e32 v32, 16, v32
	v_rcp_f32_e32 v34, v33
	s_nop 0
	v_mul_f32_e32 v33, v40, v34
	v_mul_f32_e32 v32, v33, v32
	v_mul_f32_e32 v33, 0xbfb8aa3b, v41
	v_exp_f32_e32 v33, v33
	v_cvt_pk_bf16_f32 v32, v32, s0
	ds_write_b16 v64, v32 offset:4416
	ds_read_u16 v32, v64 offset:4688
	v_add_f32_e32 v33, 1.0, v33
	s_waitcnt lgkmcnt(0)
	v_lshlrev_b32_e32 v32, 16, v32
	v_rcp_f32_e32 v34, v33
	s_nop 0
	v_mul_f32_e32 v33, v41, v34
	v_mul_f32_e32 v32, v33, v32
	v_mul_f32_e32 v33, 0xbfb8aa3b, v42
	v_exp_f32_e32 v33, v33
	v_cvt_pk_bf16_f32 v32, v32, s0
	ds_write_b16 v64, v32 offset:4688
	ds_read_u16 v32, v64 offset:4960
	v_add_f32_e32 v33, 1.0, v33
	s_waitcnt lgkmcnt(0)
	v_lshlrev_b32_e32 v32, 16, v32
	v_rcp_f32_e32 v34, v33
	s_nop 0
	v_mul_f32_e32 v33, v42, v34
	v_mul_f32_e32 v32, v33, v32
	v_mul_f32_e32 v33, 0xbfb8aa3b, v43
	v_exp_f32_e32 v33, v33
	v_cvt_pk_bf16_f32 v32, v32, s0
	ds_write_b16 v64, v32 offset:4960
	ds_read_u16 v32, v64 offset:5232
	v_add_f32_e32 v33, 1.0, v33
	s_waitcnt lgkmcnt(0)
	v_lshlrev_b32_e32 v32, 16, v32
	v_rcp_f32_e32 v34, v33
	s_nop 0
	v_mul_f32_e32 v33, v43, v34
	v_mul_f32_e32 v32, v33, v32
	v_mul_f32_e32 v33, 0xbfb8aa3b, v44
	v_exp_f32_e32 v33, v33
	v_cvt_pk_bf16_f32 v32, v32, s0
	ds_write_b16 v64, v32 offset:5232
	ds_read_u16 v32, v64 offset:6592
	v_add_f32_e32 v33, 1.0, v33
	s_waitcnt lgkmcnt(0)
	v_lshlrev_b32_e32 v32, 16, v32
	v_rcp_f32_e32 v34, v33
	s_nop 0
	v_mul_f32_e32 v33, v44, v34
	v_mul_f32_e32 v32, v33, v32
	v_mul_f32_e32 v33, 0xbfb8aa3b, v45
	v_exp_f32_e32 v33, v33
	v_cvt_pk_bf16_f32 v32, v32, s0
	ds_write_b16 v64, v32 offset:6592
	ds_read_u16 v32, v64 offset:6864
	v_add_f32_e32 v33, 1.0, v33
	s_waitcnt lgkmcnt(0)
	v_lshlrev_b32_e32 v32, 16, v32
	v_rcp_f32_e32 v34, v33
	s_nop 0
	v_mul_f32_e32 v33, v45, v34
	v_mul_f32_e32 v32, v33, v32
	v_mul_f32_e32 v33, 0xbfb8aa3b, v46
	v_exp_f32_e32 v33, v33
	v_cvt_pk_bf16_f32 v32, v32, s0
	ds_write_b16 v64, v32 offset:6864
	ds_read_u16 v32, v64 offset:7136
	v_add_f32_e32 v33, 1.0, v33
	s_waitcnt lgkmcnt(0)
	v_lshlrev_b32_e32 v32, 16, v32
	v_rcp_f32_e32 v34, v33
	s_nop 0
	v_mul_f32_e32 v33, v46, v34
	v_mul_f32_e32 v32, v33, v32
	v_mul_f32_e32 v33, 0xbfb8aa3b, v47
	v_exp_f32_e32 v33, v33
	v_cvt_pk_bf16_f32 v32, v32, s0
	ds_write_b16 v64, v32 offset:7136
	ds_read_u16 v32, v64 offset:7408
	v_add_f32_e32 v33, 1.0, v33
	s_waitcnt lgkmcnt(0)
	v_lshlrev_b32_e32 v32, 16, v32
	v_rcp_f32_e32 v34, v33
	s_nop 0
	v_mul_f32_e32 v33, v47, v34
	v_mul_f32_e32 v32, v33, v32
	v_mul_f32_e32 v33, 0xbfb8aa3b, v16
	v_exp_f32_e32 v33, v33
	v_cvt_pk_bf16_f32 v32, v32, s0
	ds_write_b16 v64, v32 offset:7408
	ds_read_u16 v32, v64 offset:8704
	v_add_f32_e32 v33, 1.0, v33
	s_waitcnt lgkmcnt(0)
	v_lshlrev_b32_e32 v32, 16, v32
	v_rcp_f32_e32 v34, v33
	s_nop 0
	v_mul_f32_e32 v16, v16, v34
	v_mul_f32_e32 v16, v16, v32
	v_mul_f32_e32 v32, 0xbfb8aa3b, v17
	v_exp_f32_e32 v32, v32
	v_cvt_pk_bf16_f32 v16, v16, s0
	ds_write_b16 v64, v16 offset:8704
	ds_read_u16 v16, v64 offset:8976
	v_add_f32_e32 v32, 1.0, v32
	s_waitcnt lgkmcnt(0)
	v_lshlrev_b32_e32 v16, 16, v16
	v_rcp_f32_e32 v33, v32
	s_nop 0
	v_mul_f32_e32 v17, v17, v33
	v_mul_f32_e32 v16, v17, v16
	v_mul_f32_e32 v17, 0xbfb8aa3b, v18
	v_exp_f32_e32 v17, v17
	v_cvt_pk_bf16_f32 v16, v16, s0
	ds_write_b16 v64, v16 offset:8976
	ds_read_u16 v16, v64 offset:9248
	v_add_f32_e32 v17, 1.0, v17
	s_waitcnt lgkmcnt(0)
	v_lshlrev_b32_e32 v16, 16, v16
	v_rcp_f32_e32 v32, v17
	s_nop 0
	v_mul_f32_e32 v17, v18, v32
	v_mul_f32_e32 v16, v17, v16
	v_mul_f32_e32 v17, 0xbfb8aa3b, v19
	v_exp_f32_e32 v17, v17
	v_cvt_pk_bf16_f32 v16, v16, s0
	ds_write_b16 v64, v16 offset:9248
	ds_read_u16 v16, v64 offset:9520
	v_add_f32_e32 v17, 1.0, v17
	s_waitcnt lgkmcnt(0)
	v_lshlrev_b32_e32 v16, 16, v16
	v_rcp_f32_e32 v18, v17
	s_nop 0
	v_mul_f32_e32 v17, v19, v18
	v_mul_f32_e32 v16, v17, v16
	v_mul_f32_e32 v17, 0xbfb8aa3b, v20
	v_exp_f32_e32 v17, v17
	v_cvt_pk_bf16_f32 v16, v16, s0
	ds_write_b16 v64, v16 offset:9520
	ds_read_u16 v16, v64 offset:10880
	v_add_f32_e32 v17, 1.0, v17
	s_waitcnt lgkmcnt(0)
	v_lshlrev_b32_e32 v16, 16, v16
	v_rcp_f32_e32 v18, v17
	s_nop 0
	v_mul_f32_e32 v17, v20, v18
	v_mul_f32_e32 v16, v17, v16
	v_mul_f32_e32 v17, 0xbfb8aa3b, v21
	v_exp_f32_e32 v17, v17
	v_cvt_pk_bf16_f32 v16, v16, s0
	ds_write_b16 v64, v16 offset:10880
	ds_read_u16 v16, v64 offset:11152
	v_add_f32_e32 v17, 1.0, v17
	s_waitcnt lgkmcnt(0)
	v_lshlrev_b32_e32 v16, 16, v16
	v_rcp_f32_e32 v18, v17
	s_nop 0
	v_mul_f32_e32 v17, v21, v18
	v_mul_f32_e32 v16, v17, v16
	v_mul_f32_e32 v17, 0xbfb8aa3b, v22
	v_exp_f32_e32 v17, v17
	v_cvt_pk_bf16_f32 v16, v16, s0
	ds_write_b16 v64, v16 offset:11152
	ds_read_u16 v16, v64 offset:11424
	v_add_f32_e32 v17, 1.0, v17
	s_waitcnt lgkmcnt(0)
	v_lshlrev_b32_e32 v16, 16, v16
	v_rcp_f32_e32 v18, v17
	s_nop 0
	v_mul_f32_e32 v17, v22, v18
	v_mul_f32_e32 v16, v17, v16
	v_mul_f32_e32 v17, 0xbfb8aa3b, v23
	v_exp_f32_e32 v17, v17
	v_cvt_pk_bf16_f32 v16, v16, s0
	ds_write_b16 v64, v16 offset:11424
	ds_read_u16 v16, v64 offset:11696
	v_add_f32_e32 v17, 1.0, v17
	s_waitcnt lgkmcnt(0)
	v_lshlrev_b32_e32 v16, 16, v16
	v_rcp_f32_e32 v18, v17
	s_nop 0
	v_mul_f32_e32 v17, v23, v18
	v_mul_f32_e32 v16, v17, v16
	v_mul_f32_e32 v17, 0xbfb8aa3b, v24
	v_exp_f32_e32 v17, v17
	v_cvt_pk_bf16_f32 v16, v16, s0
	ds_write_b16 v64, v16 offset:11696
	ds_read_u16 v16, v64 offset:13056
	v_add_f32_e32 v17, 1.0, v17
	s_waitcnt lgkmcnt(0)
	v_lshlrev_b32_e32 v16, 16, v16
	v_rcp_f32_e32 v18, v17
	s_nop 0
	v_mul_f32_e32 v17, v24, v18
	v_mul_f32_e32 v16, v17, v16
	v_mul_f32_e32 v17, 0xbfb8aa3b, v25
	v_exp_f32_e32 v17, v17
	v_cvt_pk_bf16_f32 v16, v16, s0
	ds_write_b16 v64, v16 offset:13056
	ds_read_u16 v16, v64 offset:13328
	v_add_f32_e32 v17, 1.0, v17
	s_waitcnt lgkmcnt(0)
; DEV u16 f2bf(float f) { return (u16)(pk2bf(f, 0.f) & 0xffffu); }
; DEV float bf2f(u16 h) { return __uint_as_float(((unsigned)h) << 16); }
; DEV float siluf_(float x) { return x / (1.0f + __expf(-x)); }
; template <int MI>
; DEV void p4_tile(const Params& p, int l, int m0, int nt, unsigned char* smem) {
;     ...
;     acc_foreach_t<MI>([&](int mi, int ni, int r, int row, int col) __attribute__((always_inline)) {
;       sC[row * LDC + col] = f2bf(bf2f(sC[row * LDC + col]) * siluf_(acc[mi][ni][r]));
;     });
	v_lshlrev_b32_e32 v16, 16, v16
	v_rcp_f32_e32 v18, v17
	s_nop 0
	v_mul_f32_e32 v17, v25, v18
	v_mul_f32_e32 v16, v17, v16
	v_mul_f32_e32 v17, 0xbfb8aa3b, v26
	v_exp_f32_e32 v17, v17
	v_cvt_pk_bf16_f32 v16, v16, s0
	ds_write_b16 v64, v16 offset:13328
	ds_read_u16 v16, v64 offset:13600
	v_add_f32_e32 v17, 1.0, v17
	s_waitcnt lgkmcnt(0)
	v_lshlrev_b32_e32 v16, 16, v16
	v_rcp_f32_e32 v18, v17
	s_nop 0
	v_mul_f32_e32 v17, v26, v18
	v_mul_f32_e32 v16, v17, v16
	v_mul_f32_e32 v17, 0xbfb8aa3b, v27
	v_exp_f32_e32 v17, v17
	v_cvt_pk_bf16_f32 v16, v16, s0
	ds_write_b16 v64, v16 offset:13600
	ds_read_u16 v16, v64 offset:13872
	v_add_f32_e32 v17, 1.0, v17
	s_waitcnt lgkmcnt(0)
	v_lshlrev_b32_e32 v16, 16, v16
	v_rcp_f32_e32 v18, v17
	s_nop 0
	v_mul_f32_e32 v17, v27, v18
	v_mul_f32_e32 v16, v17, v16
	v_mul_f32_e32 v17, 0xbfb8aa3b, v28
	v_exp_f32_e32 v17, v17
	v_cvt_pk_bf16_f32 v16, v16, s0
	ds_write_b16 v64, v16 offset:13872
	ds_read_u16 v16, v64 offset:15232
	v_add_f32_e32 v17, 1.0, v17
	s_waitcnt lgkmcnt(0)
	v_lshlrev_b32_e32 v16, 16, v16
	v_rcp_f32_e32 v18, v17
	s_nop 0
	v_mul_f32_e32 v17, v28, v18
	v_mul_f32_e32 v16, v17, v16
	v_mul_f32_e32 v17, 0xbfb8aa3b, v29
	v_exp_f32_e32 v17, v17
	v_cvt_pk_bf16_f32 v16, v16, s0
	ds_write_b16 v64, v16 offset:15232
	ds_read_u16 v16, v64 offset:15504
	v_add_f32_e32 v17, 1.0, v17
	s_waitcnt lgkmcnt(0)
	v_lshlrev_b32_e32 v16, 16, v16
	v_rcp_f32_e32 v18, v17
	s_nop 0
	v_mul_f32_e32 v17, v29, v18
	v_mul_f32_e32 v16, v17, v16
	v_mul_f32_e32 v17, 0xbfb8aa3b, v30
	v_exp_f32_e32 v17, v17
	v_cvt_pk_bf16_f32 v16, v16, s0
	ds_write_b16 v64, v16 offset:15504
	ds_read_u16 v16, v64 offset:15776
	v_add_f32_e32 v17, 1.0, v17
	s_waitcnt lgkmcnt(0)
	v_lshlrev_b32_e32 v16, 16, v16
	v_rcp_f32_e32 v18, v17
	s_nop 0
	v_mul_f32_e32 v17, v30, v18
	v_mul_f32_e32 v16, v17, v16
	v_mul_f32_e32 v17, 0xbfb8aa3b, v31
	v_exp_f32_e32 v17, v17
	v_cvt_pk_bf16_f32 v16, v16, s0
	ds_write_b16 v64, v16 offset:15776
	ds_read_u16 v16, v64 offset:16048
	v_add_f32_e32 v17, 1.0, v17
	s_waitcnt lgkmcnt(0)
	v_lshlrev_b32_e32 v16, 16, v16
	v_rcp_f32_e32 v18, v17
	s_nop 0
	v_mul_f32_e32 v17, v31, v18
	v_mul_f32_e32 v16, v17, v16
	v_mul_f32_e32 v17, 0xbfb8aa3b, v0
	v_exp_f32_e32 v17, v17
	v_cvt_pk_bf16_f32 v16, v16, s0
	ds_write_b16 v64, v16 offset:16048
	ds_read_u16 v16, v64 offset:8768
	v_add_f32_e32 v17, 1.0, v17
	s_waitcnt lgkmcnt(0)
	v_lshlrev_b32_e32 v16, 16, v16
	v_rcp_f32_e32 v18, v17
	s_nop 0
	v_mul_f32_e32 v0, v0, v18
	v_mul_f32_e32 v0, v0, v16
	v_mul_f32_e32 v16, 0xbfb8aa3b, v1
	v_exp_f32_e32 v16, v16
	v_cvt_pk_bf16_f32 v0, v0, s0
	ds_write_b16 v64, v0 offset:8768
	ds_read_u16 v0, v64 offset:9040
	v_add_f32_e32 v16, 1.0, v16
	s_waitcnt lgkmcnt(0)
	v_lshlrev_b32_e32 v0, 16, v0
	v_rcp_f32_e32 v17, v16
	s_nop 0
	v_mul_f32_e32 v1, v1, v17
	v_mul_f32_e32 v0, v1, v0
	v_mul_f32_e32 v1, 0xbfb8aa3b, v2
	v_exp_f32_e32 v1, v1
	v_cvt_pk_bf16_f32 v0, v0, s0
	ds_write_b16 v64, v0 offset:9040
	ds_read_u16 v0, v64 offset:9312
	v_add_f32_e32 v1, 1.0, v1
	s_waitcnt lgkmcnt(0)
	v_lshlrev_b32_e32 v0, 16, v0
	v_rcp_f32_e32 v16, v1
	s_nop 0
	v_mul_f32_e32 v1, v2, v16
	v_mul_f32_e32 v0, v1, v0
	v_mul_f32_e32 v1, 0xbfb8aa3b, v3
	v_exp_f32_e32 v1, v1
	v_cvt_pk_bf16_f32 v0, v0, s0
	ds_write_b16 v64, v0 offset:9312
	ds_read_u16 v0, v64 offset:9584
	v_add_f32_e32 v1, 1.0, v1
	s_waitcnt lgkmcnt(0)
	v_lshlrev_b32_e32 v0, 16, v0
	v_rcp_f32_e32 v2, v1
	s_nop 0
	v_mul_f32_e32 v1, v3, v2
	v_mul_f32_e32 v0, v1, v0
	v_mul_f32_e32 v1, 0xbfb8aa3b, v4
	v_exp_f32_e32 v1, v1
	v_cvt_pk_bf16_f32 v0, v0, s0
	ds_write_b16 v64, v0 offset:9584
	ds_read_u16 v0, v64 offset:10944
	v_add_f32_e32 v1, 1.0, v1
	s_waitcnt lgkmcnt(0)
; DEV u16 f2bf(float f) { return (u16)(pk2bf(f, 0.f) & 0xffffu); }
; DEV float bf2f(u16 h) { return __uint_as_float(((unsigned)h) << 16); }
; DEV float siluf_(float x) { return x / (1.0f + __expf(-x)); }
; template <int MI>
; DEV void p4_tile(const Params& p, int l, int m0, int nt, unsigned char* smem) {
;     ...
;     acc_foreach_t<MI>([&](int mi, int ni, int r, int row, int col) __attribute__((always_inline)) {
;       sC[row * LDC + col] = f2bf(bf2f(sC[row * LDC + col]) * siluf_(acc[mi][ni][r]));
;     });
;     tile_store_t<MI>(smem, YA + (size_t)m0 * 1024 + n0, 1024);
	v_lshlrev_b32_e32 v0, 16, v0
	v_rcp_f32_e32 v2, v1
	s_nop 0
	v_mul_f32_e32 v1, v4, v2
	v_mul_f32_e32 v0, v1, v0
	v_mul_f32_e32 v1, 0xbfb8aa3b, v5
	v_exp_f32_e32 v1, v1
	v_cvt_pk_bf16_f32 v0, v0, s0
	ds_write_b16 v64, v0 offset:10944
	ds_read_u16 v0, v64 offset:11216
	v_add_f32_e32 v1, 1.0, v1
	s_waitcnt lgkmcnt(0)
	v_lshlrev_b32_e32 v0, 16, v0
	v_rcp_f32_e32 v2, v1
	s_nop 0
	v_mul_f32_e32 v1, v5, v2
	v_mul_f32_e32 v0, v1, v0
	v_mul_f32_e32 v1, 0xbfb8aa3b, v6
	v_exp_f32_e32 v1, v1
	v_cvt_pk_bf16_f32 v0, v0, s0
	ds_write_b16 v64, v0 offset:11216
	ds_read_u16 v0, v64 offset:11488
	v_add_f32_e32 v1, 1.0, v1
	s_waitcnt lgkmcnt(0)
	v_lshlrev_b32_e32 v0, 16, v0
	v_rcp_f32_e32 v2, v1
	s_nop 0
	v_mul_f32_e32 v1, v6, v2
	v_mul_f32_e32 v0, v1, v0
	v_mul_f32_e32 v1, 0xbfb8aa3b, v7
	v_exp_f32_e32 v1, v1
	v_cvt_pk_bf16_f32 v0, v0, s0
	ds_write_b16 v64, v0 offset:11488
	ds_read_u16 v0, v64 offset:11760
	v_add_f32_e32 v1, 1.0, v1
	s_waitcnt lgkmcnt(0)
	v_lshlrev_b32_e32 v0, 16, v0
	v_rcp_f32_e32 v2, v1
	s_nop 0
	v_mul_f32_e32 v1, v7, v2
	v_mul_f32_e32 v0, v1, v0
	v_mul_f32_e32 v1, 0xbfb8aa3b, v8
	v_exp_f32_e32 v1, v1
	v_cvt_pk_bf16_f32 v0, v0, s0
	ds_write_b16 v64, v0 offset:11760
	ds_read_u16 v0, v64 offset:13120
	v_add_f32_e32 v1, 1.0, v1
	s_waitcnt lgkmcnt(0)
	v_lshlrev_b32_e32 v0, 16, v0
	v_rcp_f32_e32 v2, v1
	s_nop 0
	v_mul_f32_e32 v1, v8, v2
	v_mul_f32_e32 v0, v1, v0
	v_mul_f32_e32 v1, 0xbfb8aa3b, v9
	v_exp_f32_e32 v1, v1
	v_cvt_pk_bf16_f32 v0, v0, s0
	ds_write_b16 v64, v0 offset:13120
	ds_read_u16 v0, v64 offset:13392
	v_add_f32_e32 v1, 1.0, v1
	s_waitcnt lgkmcnt(0)
	v_lshlrev_b32_e32 v0, 16, v0
	v_rcp_f32_e32 v2, v1
	s_nop 0
	v_mul_f32_e32 v1, v9, v2
	v_mul_f32_e32 v0, v1, v0
	v_mul_f32_e32 v1, 0xbfb8aa3b, v10
	v_exp_f32_e32 v1, v1
	v_cvt_pk_bf16_f32 v0, v0, s0
	ds_write_b16 v64, v0 offset:13392
	ds_read_u16 v0, v64 offset:13664
	v_add_f32_e32 v1, 1.0, v1
	s_waitcnt lgkmcnt(0)
	v_lshlrev_b32_e32 v0, 16, v0
	v_rcp_f32_e32 v2, v1
	s_nop 0
	v_mul_f32_e32 v1, v10, v2
	v_mul_f32_e32 v0, v1, v0
	v_mul_f32_e32 v1, 0xbfb8aa3b, v11
	v_exp_f32_e32 v1, v1
	v_cvt_pk_bf16_f32 v0, v0, s0
	ds_write_b16 v64, v0 offset:13664
	ds_read_u16 v0, v64 offset:13936
	v_add_f32_e32 v1, 1.0, v1
	s_waitcnt lgkmcnt(0)
	v_lshlrev_b32_e32 v0, 16, v0
	v_rcp_f32_e32 v2, v1
	s_nop 0
	v_mul_f32_e32 v1, v11, v2
	v_mul_f32_e32 v0, v1, v0
	v_mul_f32_e32 v1, 0xbfb8aa3b, v12
	v_exp_f32_e32 v1, v1
	v_cvt_pk_bf16_f32 v0, v0, s0
	ds_write_b16 v64, v0 offset:13936
	ds_read_u16 v0, v64 offset:15296
	v_add_f32_e32 v1, 1.0, v1
	s_waitcnt lgkmcnt(0)
	v_lshlrev_b32_e32 v0, 16, v0
	v_rcp_f32_e32 v2, v1
	s_nop 0
	v_mul_f32_e32 v1, v12, v2
	v_mul_f32_e32 v0, v1, v0
	v_mul_f32_e32 v1, 0xbfb8aa3b, v13
	v_exp_f32_e32 v1, v1
	v_cvt_pk_bf16_f32 v0, v0, s0
	ds_write_b16 v64, v0 offset:15296
	ds_read_u16 v0, v64 offset:15568
	v_add_f32_e32 v1, 1.0, v1
	s_waitcnt lgkmcnt(0)
	v_lshlrev_b32_e32 v0, 16, v0
	v_rcp_f32_e32 v2, v1
	s_nop 0
	v_mul_f32_e32 v1, v13, v2
	v_mul_f32_e32 v0, v1, v0
	v_mul_f32_e32 v1, 0xbfb8aa3b, v14
	v_exp_f32_e32 v1, v1
	v_cvt_pk_bf16_f32 v0, v0, s0
	ds_write_b16 v64, v0 offset:15568
	ds_read_u16 v0, v64 offset:15840
	v_add_f32_e32 v1, 1.0, v1
	s_waitcnt lgkmcnt(0)
	v_lshlrev_b32_e32 v0, 16, v0
	v_rcp_f32_e32 v2, v1
	s_nop 0
	v_mul_f32_e32 v1, v14, v2
	v_mul_f32_e32 v0, v1, v0
	v_mul_f32_e32 v1, 0xbfb8aa3b, v15
	v_exp_f32_e32 v1, v1
	v_cvt_pk_bf16_f32 v0, v0, s0
	ds_write_b16 v64, v0 offset:15840
	ds_read_u16 v0, v64 offset:16112
	v_add_f32_e32 v1, 1.0, v1
	s_waitcnt lgkmcnt(0)
	v_lshlrev_b32_e32 v0, 16, v0
	s_mov_b64 s[6:7], 0
	v_rcp_f32_e32 v2, v1
	s_nop 0
	v_mul_f32_e32 v1, v15, v2
	v_mul_f32_e32 v0, v1, v0
	v_cvt_pk_bf16_f32 v0, v0, s0
	ds_write_b16 v64, v0 offset:16112
	v_mov_b32_e32 v0, v232
	s_waitcnt lgkmcnt(0)
	s_barrier

; DEV u16 f2bf(float f) { return (u16)(pk2bf(f, 0.f) & 0xffffu); }
; DEV float bf2f(u16 h) { return __uint_as_float(((unsigned)h) << 16); }
; DEV float siluf_(float x) { return x / (1.0f + __expf(-x)); }
; template <int MI>
; DEV void tile_load_t(unsigned char* smem, const u16* src, size_t lds_) {
;   u16* sC = (u16*)smem;
;   const int tid_ = TIDX();
; #pragma unroll
;   for (int i = 0; i < MI * 4; ++i) {
;     const int c = tid_ + 256 * i, row = c >> 4, cc = (c & 15) * 8;
;     *(bf16x8*)(sC + row * LDC + cc) = __builtin_nontemporal_load((const bf16x8*)(src + (size_t)row * lds_ + cc));
;   }
;   __syncthreads();
; template <int MI>
; DEV void p4_tile(const Params& p, int l, int m0, int nt, unsigned char* smem) {
;     ...
;     tile_load_t<MI>(smem, Q + (size_t)m0 * 1536 + nt * 192, 1536);
;     acc_foreach_t<MI>([&](int mi, int ni, int r, int row, int col) __attribute__((always_inline)) {
;       sC[row * LDC + col] = f2bf(bf2f(sC[row * LDC + col]) * siluf_(acc[mi][ni][r]));
.LBB0_1240:
	s_mul_i32 s6, s0, 0xc00
	s_mul_hi_i32 s1, s0, 0xc00
	s_add_u32 s6, s13, s6
	s_addc_u32 s1, s14, s1
	s_mul_i32 s7, s85, 0x180
	s_waitcnt vmcnt(7)
	v_mov_b32_e32 v72, v232
	s_barrier
	s_add_u32 s6, s6, s7
	s_addc_u32 s7, s1, 0
	s_waitcnt vmcnt(6)
	v_lshlrev_b32_e32 v64, 4, v72
	v_and_b32_e32 v224, 0xf0, v64
	s_waitcnt vmcnt(5)
	v_lshl_add_u64 v[68:69], s[6:7], 0, v[224:225]
	v_ashrrev_i32_e32 v70, 4, v72
	v_mad_i64_i32 v[64:65], s[6:7], v70, s41, v[68:69]
	global_load_dwordx4 v[64:67], v[64:65], off nt
	v_mad_u64_u32 v[70:71], s[6:7], v70, s42, v[224:225]
	s_lshl_b64 s[4:5], s[4:5], 1
	s_add_u32 s1, s17, s4
	s_addc_u32 s5, s18, s5
	s_lshl_b32 s4, s85, 8
	s_add_u32 s4, s1, s4
	s_addc_u32 s5, s5, 0
	s_waitcnt vmcnt(0)
	ds_write_b128 v70, v[64:67]
	v_add_u32_e32 v64, 0x100, v72
	v_ashrrev_i32_e32 v70, 4, v64
	v_mad_i64_i32 v[64:65], s[6:7], v70, s41, v[68:69]
	global_load_dwordx4 v[64:67], v[64:65], off nt
	v_mad_u64_u32 v[70:71], s[6:7], v70, s42, v[224:225]
	s_waitcnt vmcnt(0)
	ds_write_b128 v70, v[64:67]
	v_add_u32_e32 v64, 0x200, v72
	v_ashrrev_i32_e32 v70, 4, v64
	v_mad_i64_i32 v[64:65], s[6:7], v70, s41, v[68:69]
	global_load_dwordx4 v[64:67], v[64:65], off nt
	v_mad_u64_u32 v[70:71], s[6:7], v70, s42, v[224:225]
	s_waitcnt vmcnt(0)
	ds_write_b128 v70, v[64:67]
	v_add_u32_e32 v64, 0x300, v72
	v_ashrrev_i32_e32 v70, 4, v64
	v_mad_i64_i32 v[64:65], s[6:7], v70, s41, v[68:69]
	global_load_dwordx4 v[64:67], v[64:65], off nt
	v_mad_u64_u32 v[70:71], s[6:7], v70, s42, v[224:225]
	s_waitcnt vmcnt(0)
	ds_write_b128 v70, v[64:67]
	v_add_u32_e32 v64, 0x400, v72
	v_ashrrev_i32_e32 v70, 4, v64
	v_mad_i64_i32 v[64:65], s[6:7], v70, s41, v[68:69]
	global_load_dwordx4 v[64:67], v[64:65], off nt
	v_mad_u64_u32 v[70:71], s[6:7], v70, s42, v[224:225]
	s_waitcnt vmcnt(0)
	ds_write_b128 v70, v[64:67]
	v_add_u32_e32 v64, 0x500, v72
	v_ashrrev_i32_e32 v70, 4, v64
	v_mad_i64_i32 v[64:65], s[6:7], v70, s41, v[68:69]
	global_load_dwordx4 v[64:67], v[64:65], off nt
	v_mad_u64_u32 v[70:71], s[6:7], v70, s42, v[224:225]
	s_waitcnt vmcnt(0)
	ds_write_b128 v70, v[64:67]
	v_add_u32_e32 v64, 0x600, v72
	v_ashrrev_i32_e32 v70, 4, v64
	v_mad_i64_i32 v[64:65], s[6:7], v70, s41, v[68:69]
	global_load_dwordx4 v[64:67], v[64:65], off nt
	v_mad_u64_u32 v[70:71], s[6:7], v70, s42, v[224:225]
	s_waitcnt vmcnt(0)
	ds_write_b128 v70, v[64:67]
	v_add_u32_e32 v64, 0x700, v72
	v_ashrrev_i32_e32 v70, 4, v64
	v_mad_i64_i32 v[64:65], s[6:7], v70, s41, v[68:69]
	global_load_dwordx4 v[64:67], v[64:65], off nt
	v_mad_u64_u32 v[68:69], s[6:7], v70, s42, v[224:225]
	s_waitcnt vmcnt(0)
	ds_write_b128 v68, v[64:67]
	v_mov_b32_e32 v64, v232
	s_waitcnt lgkmcnt(0)
	s_barrier
	s_nop 0
	v_lshrrev_b32_e32 v66, 3, v64
	v_lshrrev_b32_e32 v65, 1, v64
	v_and_b32_e32 v66, 4, v66
	v_and_or_b32 v65, v65, s72, v66
	v_mul_f32_e32 v66, 0xbfb8aa3b, v48
	v_exp_f32_e32 v66, v66
	v_and_b32_e32 v64, 0x5f, v64
	v_mul_lo_u32 v65, v65, s42
	v_lshl_add_u32 v64, v64, 1, v65
	v_add_f32_e32 v66, 1.0, v66
	ds_read_u16 v65, v64
	s_waitcnt lgkmcnt(0)
	v_lshlrev_b32_e32 v65, 16, v65
	v_rcp_f32_e32 v67, v66
	s_nop 0
	v_mul_f32_e32 v48, v48, v67
	v_mul_f32_e32 v48, v48, v65
	v_mul_f32_e32 v65, 0xbfb8aa3b, v49
	v_exp_f32_e32 v65, v65
	v_cvt_pk_bf16_f32 v48, v48, s0
	ds_write_b16 v64, v48
	ds_read_u16 v48, v64 offset:272
	v_add_f32_e32 v65, 1.0, v65
	s_waitcnt lgkmcnt(0)
	v_lshlrev_b32_e32 v48, 16, v48
	v_rcp_f32_e32 v66, v65
	s_nop 0
	v_mul_f32_e32 v49, v49, v66
	v_mul_f32_e32 v48, v49, v48
	v_mul_f32_e32 v49, 0xbfb8aa3b, v50
	v_exp_f32_e32 v49, v49
	v_cvt_pk_bf16_f32 v48, v48, s0
	ds_write_b16 v64, v48 offset:272
	ds_read_u16 v48, v64 offset:544
	v_add_f32_e32 v49, 1.0, v49
	s_waitcnt lgkmcnt(0)
	v_lshlrev_b32_e32 v48, 16, v48
	v_rcp_f32_e32 v65, v49
	s_nop 0
	v_mul_f32_e32 v49, v50, v65
	v_mul_f32_e32 v48, v49, v48
	v_mul_f32_e32 v49, 0xbfb8aa3b, v51
	v_exp_f32_e32 v49, v49
	v_cvt_pk_bf16_f32 v48, v48, s0
	ds_write_b16 v64, v48 offset:544
	ds_read_u16 v48, v64 offset:816
	v_add_f32_e32 v49, 1.0, v49
	s_waitcnt lgkmcnt(0)
	v_lshlrev_b32_e32 v48, 16, v48
	v_rcp_f32_e32 v50, v49
	s_nop 0
	v_mul_f32_e32 v49, v51, v50
	v_mul_f32_e32 v48, v49, v48
	v_mul_f32_e32 v49, 0xbfb8aa3b, v52
	v_exp_f32_e32 v49, v49
	v_cvt_pk_bf16_f32 v48, v48, s0
	ds_write_b16 v64, v48 offset:816
	ds_read_u16 v48, v64 offset:2176
	v_add_f32_e32 v49, 1.0, v49
	s_waitcnt lgkmcnt(0)
	v_lshlrev_b32_e32 v48, 16, v48
	v_rcp_f32_e32 v50, v49
	s_nop 0
	v_mul_f32_e32 v49, v52, v50
	v_mul_f32_e32 v48, v49, v48
	v_mul_f32_e32 v49, 0xbfb8aa3b, v53
	v_exp_f32_e32 v49, v49
	v_cvt_pk_bf16_f32 v48, v48, s0
	ds_write_b16 v64, v48 offset:2176
	ds_read_u16 v48, v64 offset:2448
	v_add_f32_e32 v49, 1.0, v49
	s_waitcnt lgkmcnt(0)
	v_lshlrev_b32_e32 v48, 16, v48
	v_rcp_f32_e32 v50, v49
	s_nop 0
	v_mul_f32_e32 v49, v53, v50
	v_mul_f32_e32 v48, v49, v48
	v_mul_f32_e32 v49, 0xbfb8aa3b, v54
	v_exp_f32_e32 v49, v49
	v_cvt_pk_bf16_f32 v48, v48, s0
	ds_write_b16 v64, v48 offset:2448
	ds_read_u16 v48, v64 offset:2720
	v_add_f32_e32 v49, 1.0, v49
	s_waitcnt lgkmcnt(0)
	v_lshlrev_b32_e32 v48, 16, v48
	v_rcp_f32_e32 v50, v49
	s_nop 0
	v_mul_f32_e32 v49, v54, v50
	v_mul_f32_e32 v48, v49, v48
	v_mul_f32_e32 v49, 0xbfb8aa3b, v55
	v_exp_f32_e32 v49, v49
	v_cvt_pk_bf16_f32 v48, v48, s0
	ds_write_b16 v64, v48 offset:2720
	ds_read_u16 v48, v64 offset:2992
	v_add_f32_e32 v49, 1.0, v49
	s_waitcnt lgkmcnt(0)
	v_lshlrev_b32_e32 v48, 16, v48
	v_rcp_f32_e32 v50, v49
	s_nop 0
	v_mul_f32_e32 v49, v55, v50
	v_mul_f32_e32 v48, v49, v48
	v_mul_f32_e32 v49, 0xbfb8aa3b, v56
	v_exp_f32_e32 v49, v49
	v_cvt_pk_bf16_f32 v48, v48, s0
	ds_write_b16 v64, v48 offset:2992
	ds_read_u16 v48, v64 offset:4352
	v_add_f32_e32 v49, 1.0, v49
	s_waitcnt lgkmcnt(0)
; DEV u16 f2bf(float f) { return (u16)(pk2bf(f, 0.f) & 0xffffu); }
; DEV float bf2f(u16 h) { return __uint_as_float(((unsigned)h) << 16); }
; DEV float siluf_(float x) { return x / (1.0f + __expf(-x)); }
; template <int MI>
; DEV void p4_tile(const Params& p, int l, int m0, int nt, unsigned char* smem) {
;     ...
;     acc_foreach_t<MI>([&](int mi, int ni, int r, int row, int col) __attribute__((always_inline)) {
;       sC[row * LDC + col] = f2bf(bf2f(sC[row * LDC + col]) * siluf_(acc[mi][ni][r]));
	v_lshlrev_b32_e32 v48, 16, v48
	v_rcp_f32_e32 v50, v49
	s_nop 0
	v_mul_f32_e32 v49, v56, v50
	v_mul_f32_e32 v48, v49, v48
	v_mul_f32_e32 v49, 0xbfb8aa3b, v57
	v_exp_f32_e32 v49, v49
	v_cvt_pk_bf16_f32 v48, v48, s0
	ds_write_b16 v64, v48 offset:4352
	ds_read_u16 v48, v64 offset:4624
	v_add_f32_e32 v49, 1.0, v49
	s_waitcnt lgkmcnt(0)
	v_lshlrev_b32_e32 v48, 16, v48
	v_rcp_f32_e32 v50, v49
	s_nop 0
	v_mul_f32_e32 v49, v57, v50
	v_mul_f32_e32 v48, v49, v48
	v_mul_f32_e32 v49, 0xbfb8aa3b, v58
	v_exp_f32_e32 v49, v49
	v_cvt_pk_bf16_f32 v48, v48, s0
	ds_write_b16 v64, v48 offset:4624
	ds_read_u16 v48, v64 offset:4896
	v_add_f32_e32 v49, 1.0, v49
	s_waitcnt lgkmcnt(0)
	v_lshlrev_b32_e32 v48, 16, v48
	v_rcp_f32_e32 v50, v49
	s_nop 0
	v_mul_f32_e32 v49, v58, v50
	v_mul_f32_e32 v48, v49, v48
	v_mul_f32_e32 v49, 0xbfb8aa3b, v59
	v_exp_f32_e32 v49, v49
	v_cvt_pk_bf16_f32 v48, v48, s0
	ds_write_b16 v64, v48 offset:4896
	ds_read_u16 v48, v64 offset:5168
	v_add_f32_e32 v49, 1.0, v49
	s_waitcnt lgkmcnt(0)
	v_lshlrev_b32_e32 v48, 16, v48
	v_rcp_f32_e32 v50, v49
	s_nop 0
	v_mul_f32_e32 v49, v59, v50
	v_mul_f32_e32 v48, v49, v48
	v_mul_f32_e32 v49, 0xbfb8aa3b, v60
	v_exp_f32_e32 v49, v49
	v_cvt_pk_bf16_f32 v48, v48, s0
	ds_write_b16 v64, v48 offset:5168
	ds_read_u16 v48, v64 offset:6528
	v_add_f32_e32 v49, 1.0, v49
	s_waitcnt lgkmcnt(0)
	v_lshlrev_b32_e32 v48, 16, v48
	v_rcp_f32_e32 v50, v49
	s_nop 0
	v_mul_f32_e32 v49, v60, v50
	v_mul_f32_e32 v48, v49, v48
	v_mul_f32_e32 v49, 0xbfb8aa3b, v61
	v_exp_f32_e32 v49, v49
	v_cvt_pk_bf16_f32 v48, v48, s0
	ds_write_b16 v64, v48 offset:6528
	ds_read_u16 v48, v64 offset:6800
	v_add_f32_e32 v49, 1.0, v49
	s_waitcnt lgkmcnt(0)
	v_lshlrev_b32_e32 v48, 16, v48
	v_rcp_f32_e32 v50, v49
	s_nop 0
	v_mul_f32_e32 v49, v61, v50
	v_mul_f32_e32 v48, v49, v48
	v_mul_f32_e32 v49, 0xbfb8aa3b, v62
	v_exp_f32_e32 v49, v49
	v_cvt_pk_bf16_f32 v48, v48, s0
	ds_write_b16 v64, v48 offset:6800
	ds_read_u16 v48, v64 offset:7072
	v_add_f32_e32 v49, 1.0, v49
	s_waitcnt lgkmcnt(0)
	v_lshlrev_b32_e32 v48, 16, v48
	v_rcp_f32_e32 v50, v49
	s_nop 0
	v_mul_f32_e32 v49, v62, v50
	v_mul_f32_e32 v48, v49, v48
	v_mul_f32_e32 v49, 0xbfb8aa3b, v63
	v_exp_f32_e32 v49, v49
	v_cvt_pk_bf16_f32 v48, v48, s0
	ds_write_b16 v64, v48 offset:7072
	ds_read_u16 v48, v64 offset:7344
	v_add_f32_e32 v49, 1.0, v49
	s_waitcnt lgkmcnt(0)
	v_lshlrev_b32_e32 v48, 16, v48
	v_rcp_f32_e32 v50, v49
	s_nop 0
	v_mul_f32_e32 v49, v63, v50
	v_mul_f32_e32 v48, v49, v48
	v_mul_f32_e32 v49, 0xbfb8aa3b, v32
	v_exp_f32_e32 v49, v49
	v_cvt_pk_bf16_f32 v48, v48, s0
	ds_write_b16 v64, v48 offset:7344
	ds_read_u16 v48, v64 offset:64
	v_add_f32_e32 v49, 1.0, v49
	s_waitcnt lgkmcnt(0)
	v_lshlrev_b32_e32 v48, 16, v48
	v_rcp_f32_e32 v50, v49
	s_nop 0
	v_mul_f32_e32 v32, v32, v50
	v_mul_f32_e32 v32, v32, v48
	v_mul_f32_e32 v48, 0xbfb8aa3b, v33
	v_exp_f32_e32 v48, v48
	v_cvt_pk_bf16_f32 v32, v32, s0
	ds_write_b16 v64, v32 offset:64
	ds_read_u16 v32, v64 offset:336
	v_add_f32_e32 v48, 1.0, v48
	s_waitcnt lgkmcnt(0)
	v_lshlrev_b32_e32 v32, 16, v32
	v_rcp_f32_e32 v49, v48
	s_nop 0
	v_mul_f32_e32 v33, v33, v49
	v_mul_f32_e32 v32, v33, v32
	v_mul_f32_e32 v33, 0xbfb8aa3b, v34
	v_exp_f32_e32 v33, v33
	v_cvt_pk_bf16_f32 v32, v32, s0
	ds_write_b16 v64, v32 offset:336
	ds_read_u16 v32, v64 offset:608
	v_add_f32_e32 v33, 1.0, v33
	s_waitcnt lgkmcnt(0)
	v_lshlrev_b32_e32 v32, 16, v32
	v_rcp_f32_e32 v48, v33
	s_nop 0
	v_mul_f32_e32 v33, v34, v48
	v_mul_f32_e32 v32, v33, v32
	v_mul_f32_e32 v33, 0xbfb8aa3b, v35
	v_exp_f32_e32 v33, v33
	v_cvt_pk_bf16_f32 v32, v32, s0
	ds_write_b16 v64, v32 offset:608
	ds_read_u16 v32, v64 offset:880
	v_add_f32_e32 v33, 1.0, v33
	s_waitcnt lgkmcnt(0)
	v_lshlrev_b32_e32 v32, 16, v32
	v_rcp_f32_e32 v34, v33
	s_nop 0
	v_mul_f32_e32 v33, v35, v34
	v_mul_f32_e32 v32, v33, v32
	v_mul_f32_e32 v33, 0xbfb8aa3b, v36
	v_exp_f32_e32 v33, v33
	v_cvt_pk_bf16_f32 v32, v32, s0
	ds_write_b16 v64, v32 offset:880
	ds_read_u16 v32, v64 offset:2240
	v_add_f32_e32 v33, 1.0, v33
	s_waitcnt lgkmcnt(0)
	v_lshlrev_b32_e32 v32, 16, v32
	v_rcp_f32_e32 v34, v33
	s_nop 0
	v_mul_f32_e32 v33, v36, v34
	v_mul_f32_e32 v32, v33, v32
	v_mul_f32_e32 v33, 0xbfb8aa3b, v37
	v_exp_f32_e32 v33, v33
	v_cvt_pk_bf16_f32 v32, v32, s0
	ds_write_b16 v64, v32 offset:2240
	ds_read_u16 v32, v64 offset:2512
	v_add_f32_e32 v33, 1.0, v33
	s_waitcnt lgkmcnt(0)
	v_lshlrev_b32_e32 v32, 16, v32
	v_rcp_f32_e32 v34, v33
	s_nop 0
	v_mul_f32_e32 v33, v37, v34
	v_mul_f32_e32 v32, v33, v32
	v_mul_f32_e32 v33, 0xbfb8aa3b, v38
	v_exp_f32_e32 v33, v33
	v_cvt_pk_bf16_f32 v32, v32, s0
	ds_write_b16 v64, v32 offset:2512
	ds_read_u16 v32, v64 offset:2784
	v_add_f32_e32 v33, 1.0, v33
	s_waitcnt lgkmcnt(0)
	v_lshlrev_b32_e32 v32, 16, v32
	v_rcp_f32_e32 v34, v33
	s_nop 0
	v_mul_f32_e32 v33, v38, v34
	v_mul_f32_e32 v32, v33, v32
	v_mul_f32_e32 v33, 0xbfb8aa3b, v39
	v_exp_f32_e32 v33, v33
	v_cvt_pk_bf16_f32 v32, v32, s0
	ds_write_b16 v64, v32 offset:2784
	ds_read_u16 v32, v64 offset:3056
	v_add_f32_e32 v33, 1.0, v33
	s_waitcnt lgkmcnt(0)
	v_lshlrev_b32_e32 v32, 16, v32
	v_rcp_f32_e32 v34, v33
	s_nop 0
	v_mul_f32_e32 v33, v39, v34
	v_mul_f32_e32 v32, v33, v32
	v_mul_f32_e32 v33, 0xbfb8aa3b, v40
	v_exp_f32_e32 v33, v33
	v_cvt_pk_bf16_f32 v32, v32, s0
	ds_write_b16 v64, v32 offset:3056
	ds_read_u16 v32, v64 offset:4416
	v_add_f32_e32 v33, 1.0, v33
	s_waitcnt lgkmcnt(0)
	v_lshlrev_b32_e32 v32, 16, v32
	v_rcp_f32_e32 v34, v33
	s_nop 0
	v_mul_f32_e32 v33, v40, v34
	v_mul_f32_e32 v32, v33, v32
	v_mul_f32_e32 v33, 0xbfb8aa3b, v41
	v_exp_f32_e32 v33, v33
	v_cvt_pk_bf16_f32 v32, v32, s0
	ds_write_b16 v64, v32 offset:4416
	ds_read_u16 v32, v64 offset:4688
	v_add_f32_e32 v33, 1.0, v33
	s_waitcnt lgkmcnt(0)
; DEV u16 f2bf(float f) { return (u16)(pk2bf(f, 0.f) & 0xffffu); }
; DEV float bf2f(u16 h) { return __uint_as_float(((unsigned)h) << 16); }
; DEV float siluf_(float x) { return x / (1.0f + __expf(-x)); }
; template <int MI>
; DEV void p4_tile(const Params& p, int l, int m0, int nt, unsigned char* smem) {
;     ...
;     acc_foreach_t<MI>([&](int mi, int ni, int r, int row, int col) __attribute__((always_inline)) {
;       sC[row * LDC + col] = f2bf(bf2f(sC[row * LDC + col]) * siluf_(acc[mi][ni][r]));
	v_lshlrev_b32_e32 v32, 16, v32
	v_rcp_f32_e32 v34, v33
	s_nop 0
	v_mul_f32_e32 v33, v41, v34
	v_mul_f32_e32 v32, v33, v32
	v_mul_f32_e32 v33, 0xbfb8aa3b, v42
	v_exp_f32_e32 v33, v33
	v_cvt_pk_bf16_f32 v32, v32, s0
	ds_write_b16 v64, v32 offset:4688
	ds_read_u16 v32, v64 offset:4960
	v_add_f32_e32 v33, 1.0, v33
	s_waitcnt lgkmcnt(0)
	v_lshlrev_b32_e32 v32, 16, v32
	v_rcp_f32_e32 v34, v33
	s_nop 0
	v_mul_f32_e32 v33, v42, v34
	v_mul_f32_e32 v32, v33, v32
	v_mul_f32_e32 v33, 0xbfb8aa3b, v43
	v_exp_f32_e32 v33, v33
	v_cvt_pk_bf16_f32 v32, v32, s0
	ds_write_b16 v64, v32 offset:4960
	ds_read_u16 v32, v64 offset:5232
	v_add_f32_e32 v33, 1.0, v33
	s_waitcnt lgkmcnt(0)
	v_lshlrev_b32_e32 v32, 16, v32
	v_rcp_f32_e32 v34, v33
	s_nop 0
	v_mul_f32_e32 v33, v43, v34
	v_mul_f32_e32 v32, v33, v32
	v_mul_f32_e32 v33, 0xbfb8aa3b, v44
	v_exp_f32_e32 v33, v33
	v_cvt_pk_bf16_f32 v32, v32, s0
	ds_write_b16 v64, v32 offset:5232
	ds_read_u16 v32, v64 offset:6592
	v_add_f32_e32 v33, 1.0, v33
	s_waitcnt lgkmcnt(0)
	v_lshlrev_b32_e32 v32, 16, v32
	v_rcp_f32_e32 v34, v33
	s_nop 0
	v_mul_f32_e32 v33, v44, v34
	v_mul_f32_e32 v32, v33, v32
	v_mul_f32_e32 v33, 0xbfb8aa3b, v45
	v_exp_f32_e32 v33, v33
	v_cvt_pk_bf16_f32 v32, v32, s0
	ds_write_b16 v64, v32 offset:6592
	ds_read_u16 v32, v64 offset:6864
	v_add_f32_e32 v33, 1.0, v33
	s_waitcnt lgkmcnt(0)
	v_lshlrev_b32_e32 v32, 16, v32
	v_rcp_f32_e32 v34, v33
	s_nop 0
	v_mul_f32_e32 v33, v45, v34
	v_mul_f32_e32 v32, v33, v32
	v_mul_f32_e32 v33, 0xbfb8aa3b, v46
	v_exp_f32_e32 v33, v33
	v_cvt_pk_bf16_f32 v32, v32, s0
	ds_write_b16 v64, v32 offset:6864
	ds_read_u16 v32, v64 offset:7136
	v_add_f32_e32 v33, 1.0, v33
	s_waitcnt lgkmcnt(0)
	v_lshlrev_b32_e32 v32, 16, v32
	v_rcp_f32_e32 v34, v33
	s_nop 0
	v_mul_f32_e32 v33, v46, v34
	v_mul_f32_e32 v32, v33, v32
	v_mul_f32_e32 v33, 0xbfb8aa3b, v47
	v_exp_f32_e32 v33, v33
	v_cvt_pk_bf16_f32 v32, v32, s0
	ds_write_b16 v64, v32 offset:7136
	ds_read_u16 v32, v64 offset:7408
	v_add_f32_e32 v33, 1.0, v33
	s_waitcnt lgkmcnt(0)
	v_lshlrev_b32_e32 v32, 16, v32
	v_rcp_f32_e32 v34, v33
	s_nop 0
	v_mul_f32_e32 v33, v47, v34
	v_mul_f32_e32 v32, v33, v32
	v_mul_f32_e32 v33, 0xbfb8aa3b, v16
	v_exp_f32_e32 v33, v33
	v_cvt_pk_bf16_f32 v32, v32, s0
	ds_write_b16 v64, v32 offset:7408
	ds_read_u16 v32, v64 offset:8704
	v_add_f32_e32 v33, 1.0, v33
	s_waitcnt lgkmcnt(0)
	v_lshlrev_b32_e32 v32, 16, v32
	v_rcp_f32_e32 v34, v33
	s_nop 0
	v_mul_f32_e32 v16, v16, v34
	v_mul_f32_e32 v16, v16, v32
	v_mul_f32_e32 v32, 0xbfb8aa3b, v17
	v_exp_f32_e32 v32, v32
	v_cvt_pk_bf16_f32 v16, v16, s0
	ds_write_b16 v64, v16 offset:8704
	ds_read_u16 v16, v64 offset:8976
	v_add_f32_e32 v32, 1.0, v32
	s_waitcnt lgkmcnt(0)
	v_lshlrev_b32_e32 v16, 16, v16
	v_rcp_f32_e32 v33, v32
	s_nop 0
	v_mul_f32_e32 v17, v17, v33
	v_mul_f32_e32 v16, v17, v16
	v_mul_f32_e32 v17, 0xbfb8aa3b, v18
	v_exp_f32_e32 v17, v17
	v_cvt_pk_bf16_f32 v16, v16, s0
	ds_write_b16 v64, v16 offset:8976
	ds_read_u16 v16, v64 offset:9248
	v_add_f32_e32 v17, 1.0, v17
	s_waitcnt lgkmcnt(0)
	v_lshlrev_b32_e32 v16, 16, v16
	v_rcp_f32_e32 v32, v17
	s_nop 0
	v_mul_f32_e32 v17, v18, v32
	v_mul_f32_e32 v16, v17, v16
	v_mul_f32_e32 v17, 0xbfb8aa3b, v19
	v_exp_f32_e32 v17, v17
	v_cvt_pk_bf16_f32 v16, v16, s0
	ds_write_b16 v64, v16 offset:9248
	ds_read_u16 v16, v64 offset:9520
	v_add_f32_e32 v17, 1.0, v17
	s_waitcnt lgkmcnt(0)
	v_lshlrev_b32_e32 v16, 16, v16
	v_rcp_f32_e32 v18, v17
	s_nop 0
	v_mul_f32_e32 v17, v19, v18
	v_mul_f32_e32 v16, v17, v16
	v_mul_f32_e32 v17, 0xbfb8aa3b, v20
	v_exp_f32_e32 v17, v17
	v_cvt_pk_bf16_f32 v16, v16, s0
	ds_write_b16 v64, v16 offset:9520
	ds_read_u16 v16, v64 offset:10880
	v_add_f32_e32 v17, 1.0, v17
	s_waitcnt lgkmcnt(0)
	v_lshlrev_b32_e32 v16, 16, v16
	v_rcp_f32_e32 v18, v17
	s_nop 0
	v_mul_f32_e32 v17, v20, v18
	v_mul_f32_e32 v16, v17, v16
	v_mul_f32_e32 v17, 0xbfb8aa3b, v21
	v_exp_f32_e32 v17, v17
	v_cvt_pk_bf16_f32 v16, v16, s0
	ds_write_b16 v64, v16 offset:10880
	ds_read_u16 v16, v64 offset:11152
	v_add_f32_e32 v17, 1.0, v17
	s_waitcnt lgkmcnt(0)
	v_lshlrev_b32_e32 v16, 16, v16
	v_rcp_f32_e32 v18, v17
	s_nop 0
	v_mul_f32_e32 v17, v21, v18
	v_mul_f32_e32 v16, v17, v16
	v_mul_f32_e32 v17, 0xbfb8aa3b, v22
	v_exp_f32_e32 v17, v17
	v_cvt_pk_bf16_f32 v16, v16, s0
	ds_write_b16 v64, v16 offset:11152
	ds_read_u16 v16, v64 offset:11424
	v_add_f32_e32 v17, 1.0, v17
	s_waitcnt lgkmcnt(0)
	v_lshlrev_b32_e32 v16, 16, v16
	v_rcp_f32_e32 v18, v17
	s_nop 0
	v_mul_f32_e32 v17, v22, v18
	v_mul_f32_e32 v16, v17, v16
	v_mul_f32_e32 v17, 0xbfb8aa3b, v23
	v_exp_f32_e32 v17, v17
	v_cvt_pk_bf16_f32 v16, v16, s0
	ds_write_b16 v64, v16 offset:11424
	ds_read_u16 v16, v64 offset:11696
	v_add_f32_e32 v17, 1.0, v17
	s_waitcnt lgkmcnt(0)
	v_lshlrev_b32_e32 v16, 16, v16
	v_rcp_f32_e32 v18, v17
	s_nop 0
	v_mul_f32_e32 v17, v23, v18
	v_mul_f32_e32 v16, v17, v16
	v_mul_f32_e32 v17, 0xbfb8aa3b, v24
	v_exp_f32_e32 v17, v17
	v_cvt_pk_bf16_f32 v16, v16, s0
	ds_write_b16 v64, v16 offset:11696
	ds_read_u16 v16, v64 offset:13056
	v_add_f32_e32 v17, 1.0, v17
	s_waitcnt lgkmcnt(0)
	v_lshlrev_b32_e32 v16, 16, v16
	v_rcp_f32_e32 v18, v17
	s_nop 0
	v_mul_f32_e32 v17, v24, v18
	v_mul_f32_e32 v16, v17, v16
	v_mul_f32_e32 v17, 0xbfb8aa3b, v25
	v_exp_f32_e32 v17, v17
	v_cvt_pk_bf16_f32 v16, v16, s0
	ds_write_b16 v64, v16 offset:13056
	ds_read_u16 v16, v64 offset:13328
	v_add_f32_e32 v17, 1.0, v17
	s_waitcnt lgkmcnt(0)
	v_lshlrev_b32_e32 v16, 16, v16
	v_rcp_f32_e32 v18, v17
	s_nop 0
	v_mul_f32_e32 v17, v25, v18
	v_mul_f32_e32 v16, v17, v16
	v_mul_f32_e32 v17, 0xbfb8aa3b, v26
	v_exp_f32_e32 v17, v17
	v_cvt_pk_bf16_f32 v16, v16, s0
	ds_write_b16 v64, v16 offset:13328
	ds_read_u16 v16, v64 offset:13600
	v_add_f32_e32 v17, 1.0, v17
	s_waitcnt lgkmcnt(0)
; DEV u16 f2bf(float f) { return (u16)(pk2bf(f, 0.f) & 0xffffu); }
; DEV float bf2f(u16 h) { return __uint_as_float(((unsigned)h) << 16); }
; DEV float siluf_(float x) { return x / (1.0f + __expf(-x)); }
; template <int MI>
; DEV void p4_tile(const Params& p, int l, int m0, int nt, unsigned char* smem) {
;     ...
;     tile_load_t<MI>(smem, YA + (size_t)m0 * 1024 + n0, 1024);
;     acc_foreach_t<MI>([&](int mi, int ni, int r, int row, int col) __attribute__((always_inline)) {
;       sC[row * LDC + col] = f2bf(bf2f(sC[row * LDC + col]) * siluf_(acc[mi][ni][r]));
;     });
	v_lshlrev_b32_e32 v16, 16, v16
	v_rcp_f32_e32 v18, v17
	s_nop 0
	v_mul_f32_e32 v17, v26, v18
	v_mul_f32_e32 v16, v17, v16
	v_mul_f32_e32 v17, 0xbfb8aa3b, v27
	v_exp_f32_e32 v17, v17
	v_cvt_pk_bf16_f32 v16, v16, s0
	ds_write_b16 v64, v16 offset:13600
	ds_read_u16 v16, v64 offset:13872
	v_add_f32_e32 v17, 1.0, v17
	s_waitcnt lgkmcnt(0)
	v_lshlrev_b32_e32 v16, 16, v16
	v_rcp_f32_e32 v18, v17
	s_nop 0
	v_mul_f32_e32 v17, v27, v18
	v_mul_f32_e32 v16, v17, v16
	v_mul_f32_e32 v17, 0xbfb8aa3b, v28
	v_exp_f32_e32 v17, v17
	v_cvt_pk_bf16_f32 v16, v16, s0
	ds_write_b16 v64, v16 offset:13872
	ds_read_u16 v16, v64 offset:15232
	v_add_f32_e32 v17, 1.0, v17
	s_waitcnt lgkmcnt(0)
	v_lshlrev_b32_e32 v16, 16, v16
	v_rcp_f32_e32 v18, v17
	s_nop 0
	v_mul_f32_e32 v17, v28, v18
	v_mul_f32_e32 v16, v17, v16
	v_mul_f32_e32 v17, 0xbfb8aa3b, v29
	v_exp_f32_e32 v17, v17
	v_cvt_pk_bf16_f32 v16, v16, s0
	ds_write_b16 v64, v16 offset:15232
	ds_read_u16 v16, v64 offset:15504
	v_add_f32_e32 v17, 1.0, v17
	s_waitcnt lgkmcnt(0)
	v_lshlrev_b32_e32 v16, 16, v16
	v_rcp_f32_e32 v18, v17
	s_nop 0
	v_mul_f32_e32 v17, v29, v18
	v_mul_f32_e32 v16, v17, v16
	v_mul_f32_e32 v17, 0xbfb8aa3b, v30
	v_exp_f32_e32 v17, v17
	v_cvt_pk_bf16_f32 v16, v16, s0
	ds_write_b16 v64, v16 offset:15504
	ds_read_u16 v16, v64 offset:15776
	v_add_f32_e32 v17, 1.0, v17
	s_waitcnt lgkmcnt(0)
	v_lshlrev_b32_e32 v16, 16, v16
	v_rcp_f32_e32 v18, v17
	s_nop 0
	v_mul_f32_e32 v17, v30, v18
	v_mul_f32_e32 v16, v17, v16
	v_mul_f32_e32 v17, 0xbfb8aa3b, v31
	v_exp_f32_e32 v17, v17
	v_cvt_pk_bf16_f32 v16, v16, s0
	ds_write_b16 v64, v16 offset:15776
	ds_read_u16 v16, v64 offset:16048
	v_add_f32_e32 v17, 1.0, v17
	s_waitcnt lgkmcnt(0)
	v_lshlrev_b32_e32 v16, 16, v16
	v_rcp_f32_e32 v18, v17
	s_nop 0
	v_mul_f32_e32 v17, v31, v18
	v_mul_f32_e32 v16, v17, v16
	v_mul_f32_e32 v17, 0xbfb8aa3b, v0
	v_exp_f32_e32 v17, v17
	v_cvt_pk_bf16_f32 v16, v16, s0
	ds_write_b16 v64, v16 offset:16048
	ds_read_u16 v16, v64 offset:8768
	v_add_f32_e32 v17, 1.0, v17
	s_waitcnt lgkmcnt(0)
	v_lshlrev_b32_e32 v16, 16, v16
	v_rcp_f32_e32 v18, v17
	s_nop 0
	v_mul_f32_e32 v0, v0, v18
	v_mul_f32_e32 v0, v0, v16
	v_mul_f32_e32 v16, 0xbfb8aa3b, v1
	v_exp_f32_e32 v16, v16
	v_cvt_pk_bf16_f32 v0, v0, s0
	ds_write_b16 v64, v0 offset:8768
	ds_read_u16 v0, v64 offset:9040
	v_add_f32_e32 v16, 1.0, v16
	s_waitcnt lgkmcnt(0)
	v_lshlrev_b32_e32 v0, 16, v0
	v_rcp_f32_e32 v17, v16
	s_nop 0
	v_mul_f32_e32 v1, v1, v17
	v_mul_f32_e32 v0, v1, v0
	v_mul_f32_e32 v1, 0xbfb8aa3b, v2
	v_exp_f32_e32 v1, v1
	v_cvt_pk_bf16_f32 v0, v0, s0
	ds_write_b16 v64, v0 offset:9040
	ds_read_u16 v0, v64 offset:9312
	v_add_f32_e32 v1, 1.0, v1
	s_waitcnt lgkmcnt(0)
	v_lshlrev_b32_e32 v0, 16, v0
	v_rcp_f32_e32 v16, v1
	s_nop 0
	v_mul_f32_e32 v1, v2, v16
	v_mul_f32_e32 v0, v1, v0
	v_mul_f32_e32 v1, 0xbfb8aa3b, v3
	v_exp_f32_e32 v1, v1
	v_cvt_pk_bf16_f32 v0, v0, s0
	ds_write_b16 v64, v0 offset:9312
	ds_read_u16 v0, v64 offset:9584
	v_add_f32_e32 v1, 1.0, v1
	s_waitcnt lgkmcnt(0)
	v_lshlrev_b32_e32 v0, 16, v0
	v_rcp_f32_e32 v2, v1
	s_nop 0
	v_mul_f32_e32 v1, v3, v2
	v_mul_f32_e32 v0, v1, v0
	v_mul_f32_e32 v1, 0xbfb8aa3b, v4
	v_exp_f32_e32 v1, v1
	v_cvt_pk_bf16_f32 v0, v0, s0
	ds_write_b16 v64, v0 offset:9584
	ds_read_u16 v0, v64 offset:10944
	v_add_f32_e32 v1, 1.0, v1
	s_waitcnt lgkmcnt(0)
	v_lshlrev_b32_e32 v0, 16, v0
	v_rcp_f32_e32 v2, v1
	s_nop 0
	v_mul_f32_e32 v1, v4, v2
	v_mul_f32_e32 v0, v1, v0
	v_mul_f32_e32 v1, 0xbfb8aa3b, v5
	v_exp_f32_e32 v1, v1
	v_cvt_pk_bf16_f32 v0, v0, s0
	ds_write_b16 v64, v0 offset:10944
	ds_read_u16 v0, v64 offset:11216
	v_add_f32_e32 v1, 1.0, v1
	s_waitcnt lgkmcnt(0)
; DEV u16 f2bf(float f) { return (u16)(pk2bf(f, 0.f) & 0xffffu); }
; DEV float bf2f(u16 h) { return __uint_as_float(((unsigned)h) << 16); }
; DEV float siluf_(float x) { return x / (1.0f + __expf(-x)); }
; template <int MI>
; DEV void p4_tile(const Params& p, int l, int m0, int nt, unsigned char* smem) {
;     ...
;     acc_foreach_t<MI>([&](int mi, int ni, int r, int row, int col) __attribute__((always_inline)) {
;       sC[row * LDC + col] = f2bf(bf2f(sC[row * LDC + col]) * siluf_(acc[mi][ni][r]));
;     });
;     tile_store_t<MI>(smem, YA + (size_t)m0 * 1024 + n0, 1024);
	v_lshlrev_b32_e32 v0, 16, v0
	v_rcp_f32_e32 v2, v1
	s_nop 0
	v_mul_f32_e32 v1, v5, v2
	v_mul_f32_e32 v0, v1, v0
	v_mul_f32_e32 v1, 0xbfb8aa3b, v6
	v_exp_f32_e32 v1, v1
	v_cvt_pk_bf16_f32 v0, v0, s0
	ds_write_b16 v64, v0 offset:11216
	ds_read_u16 v0, v64 offset:11488
	v_add_f32_e32 v1, 1.0, v1
	s_waitcnt lgkmcnt(0)
	v_lshlrev_b32_e32 v0, 16, v0
	v_rcp_f32_e32 v2, v1
	s_nop 0
	v_mul_f32_e32 v1, v6, v2
	v_mul_f32_e32 v0, v1, v0
	v_mul_f32_e32 v1, 0xbfb8aa3b, v7
	v_exp_f32_e32 v1, v1
	v_cvt_pk_bf16_f32 v0, v0, s0
	ds_write_b16 v64, v0 offset:11488
	ds_read_u16 v0, v64 offset:11760
	v_add_f32_e32 v1, 1.0, v1
	s_waitcnt lgkmcnt(0)
	v_lshlrev_b32_e32 v0, 16, v0
	v_rcp_f32_e32 v2, v1
	s_nop 0
	v_mul_f32_e32 v1, v7, v2
	v_mul_f32_e32 v0, v1, v0
	v_mul_f32_e32 v1, 0xbfb8aa3b, v8
	v_exp_f32_e32 v1, v1
	v_cvt_pk_bf16_f32 v0, v0, s0
	ds_write_b16 v64, v0 offset:11760
	ds_read_u16 v0, v64 offset:13120
	v_add_f32_e32 v1, 1.0, v1
	s_waitcnt lgkmcnt(0)
	v_lshlrev_b32_e32 v0, 16, v0
	v_rcp_f32_e32 v2, v1
	s_nop 0
	v_mul_f32_e32 v1, v8, v2
	v_mul_f32_e32 v0, v1, v0
	v_mul_f32_e32 v1, 0xbfb8aa3b, v9
	v_exp_f32_e32 v1, v1
	v_cvt_pk_bf16_f32 v0, v0, s0
	ds_write_b16 v64, v0 offset:13120
	ds_read_u16 v0, v64 offset:13392
	v_add_f32_e32 v1, 1.0, v1
	s_waitcnt lgkmcnt(0)
	v_lshlrev_b32_e32 v0, 16, v0
	v_rcp_f32_e32 v2, v1
	s_nop 0
	v_mul_f32_e32 v1, v9, v2
	v_mul_f32_e32 v0, v1, v0
	v_mul_f32_e32 v1, 0xbfb8aa3b, v10
	v_exp_f32_e32 v1, v1
	v_cvt_pk_bf16_f32 v0, v0, s0
	ds_write_b16 v64, v0 offset:13392
	ds_read_u16 v0, v64 offset:13664
	v_add_f32_e32 v1, 1.0, v1
	s_waitcnt lgkmcnt(0)
	v_lshlrev_b32_e32 v0, 16, v0
	v_rcp_f32_e32 v2, v1
	s_nop 0
	v_mul_f32_e32 v1, v10, v2
	v_mul_f32_e32 v0, v1, v0
	v_mul_f32_e32 v1, 0xbfb8aa3b, v11
	v_exp_f32_e32 v1, v1
	v_cvt_pk_bf16_f32 v0, v0, s0
	ds_write_b16 v64, v0 offset:13664
	ds_read_u16 v0, v64 offset:13936
	v_add_f32_e32 v1, 1.0, v1
	s_waitcnt lgkmcnt(0)
	v_lshlrev_b32_e32 v0, 16, v0
	v_rcp_f32_e32 v2, v1
	s_nop 0
	v_mul_f32_e32 v1, v11, v2
	v_mul_f32_e32 v0, v1, v0
	v_mul_f32_e32 v1, 0xbfb8aa3b, v12
	v_exp_f32_e32 v1, v1
	v_cvt_pk_bf16_f32 v0, v0, s0
	ds_write_b16 v64, v0 offset:13936
	ds_read_u16 v0, v64 offset:15296
	v_add_f32_e32 v1, 1.0, v1
	s_waitcnt lgkmcnt(0)
	v_lshlrev_b32_e32 v0, 16, v0
	v_rcp_f32_e32 v2, v1
	s_nop 0
	v_mul_f32_e32 v1, v12, v2
	v_mul_f32_e32 v0, v1, v0
	v_mul_f32_e32 v1, 0xbfb8aa3b, v13
	v_exp_f32_e32 v1, v1
	v_cvt_pk_bf16_f32 v0, v0, s0
	ds_write_b16 v64, v0 offset:15296
	ds_read_u16 v0, v64 offset:15568
	v_add_f32_e32 v1, 1.0, v1
	s_waitcnt lgkmcnt(0)
	v_lshlrev_b32_e32 v0, 16, v0
	v_rcp_f32_e32 v2, v1
	s_nop 0
	v_mul_f32_e32 v1, v13, v2
	v_mul_f32_e32 v0, v1, v0
	v_mul_f32_e32 v1, 0xbfb8aa3b, v14
	v_exp_f32_e32 v1, v1
	v_cvt_pk_bf16_f32 v0, v0, s0
	ds_write_b16 v64, v0 offset:15568
	ds_read_u16 v0, v64 offset:15840
	v_add_f32_e32 v1, 1.0, v1
	s_waitcnt lgkmcnt(0)
	v_lshlrev_b32_e32 v0, 16, v0
	v_rcp_f32_e32 v2, v1
	s_nop 0
	v_mul_f32_e32 v1, v14, v2
	v_mul_f32_e32 v0, v1, v0
	v_mul_f32_e32 v1, 0xbfb8aa3b, v15
	v_exp_f32_e32 v1, v1
	v_cvt_pk_bf16_f32 v0, v0, s0
	ds_write_b16 v64, v0 offset:15840
	ds_read_u16 v0, v64 offset:16112
	v_add_f32_e32 v1, 1.0, v1
	s_waitcnt lgkmcnt(0)
	v_lshlrev_b32_e32 v0, 16, v0
	s_mov_b64 s[6:7], 0
	v_rcp_f32_e32 v2, v1
	s_nop 0
	v_mul_f32_e32 v1, v15, v2
	v_mul_f32_e32 v0, v1, v0
	v_cvt_pk_bf16_f32 v0, v0, s0
	ds_write_b16 v64, v0 offset:16112
	v_mov_b32_e32 v0, v232
	s_waitcnt lgkmcnt(0)
	s_barrier
